# K-loop staging addresses in scalar-base form (global_load_lds v_off32, s[base]) with SALU sums replacing per-lane 64-bit VALU adds in load segments (161 of 176 DMA pieces)
# speedup vs baseline: 1.0204x; 1.0125x over previous
; #define G_STAGE(bufoff, gbase, o0, h64) do { \
;         __builtin_amdgcn_global_load_lds((const unsigned*)((const char*)(gbase) + (o0)), (LAS unsigned*)(lds + (bufoff) + ldsw), 16, 0, 0); \
;         __builtin_amdgcn_global_load_lds((const unsigned*)((const char*)(gbase) + (h64) + (o0)), (LAS unsigned*)(lds + (bufoff) + ldsw + 8192), 16, 0, 0); } while (0)
; #define G_LDA(dst, b, h) do { _Pragma("unroll") for (int m = 0; m < 4; ++m) _Pragma("unroll") for (int k = 0; k < 2; ++k) dst[m][k] = *(const LAS bf16x8*)(lds + G_SA(b, h) + aoff + m * 2048 + k * 1024); } while (0)
; #define G_LDB(dst, b, h) do { _Pragma("unroll") for (int n = 0; n < 2; ++n) _Pragma("unroll") for (int k = 0; k < 2; ++k) dst[n][k] = *(const LAS bf16x8*)(lds + G_SB(b, h) + boff + n * 2048 + k * 1024); } while (0)
; #define G_WAIT_V(n) asm volatile("s_waitcnt vmcnt(" #n ")" ::: "memory")
; #define G_BAR __builtin_amdgcn_s_barrier()
;     ...
;         for (int t = 0; t < nt; t += 2) {
;             const bool last = (t == nt - 2);
;             const char* a1 = cA + (size_t)(t + 1) * ckA;
;             const char* a2 = last ? nA : cA + (size_t)(t + 2) * ckA; const char* b2 = last ? nB : cB + (size_t)(t + 2) * kB;
;             const char* a3 = a2 + ckA; const char* b3 = b2 + kB;
;             G_LDB(B0, 0, 0); G_SCHED; G_LDA(At, 0, 0); G_STAGE(G_SA(1, 1), a1 + chA, cA0, qA);
;             G_WAIT_L(8); G_BAR; G_WAIT_L(0); G_MMA(0, 0, At, B0); G_BAR; G_SCHED;
;             G_LDB(B1, 0, 1); G_STAGE(G_SB(0, 0), b2, cB0, qB);
;             G_BAR; G_WAIT_L(0); G_MMA(0, 1, At, B1); G_BAR;
;             G_LDA(At, 0, 1); G_STAGE(G_SA(0, 0), a2, cA0, qA);
;             G_BAR; G_WAIT_L(0); G_MMA(1, 0, At, B0); G_BAR; G_SCHED;
;             G_STAGE(G_SB(0, 1), b2 + chB, cB0, qB);
;             G_WAIT_V(6); G_BAR; G_MMA(1, 1, At, B1); G_BAR;
;             G_LDB(B0, 1, 0); G_SCHED; G_LDA(At, 1, 0); G_STAGE(G_SA(0, 1), a2 + chA, cA0, qA);
;             G_WAIT_L(8); G_BAR; G_WAIT_L(0); G_MMA(0, 0, At, B0); G_BAR; G_SCHED;
;             G_LDB(B1, 1, 1); G_STAGE(G_SB(1, 0), b3, cB0, qB);
;             G_BAR; G_WAIT_L(0); G_MMA(0, 1, At, B1); G_BAR;
;             G_LDA(At, 1, 1); G_STAGE(G_SA(1, 0), a3, cA0, qA);
;             G_BAR; G_WAIT_L(0); G_MMA(1, 0, At, B0); G_BAR; G_SCHED;
;             G_STAGE(G_SB(1, 1), b3 + chB, cB0, qB);
;             G_WAIT_V(6); G_BAR; G_MMA(1, 1, At, B1); G_BAR;
.LBB0_212:
	s_add_u32 s4, s2, 0xfffc0080
	s_addc_u32 s5, s3, -1
	s_add_i32 s41, 0, 0x10000
	v_add_u32_e32 v0, s41, v167
	ds_read_b128 v[136:139], v0
	ds_read_b128 v[144:147], v0 offset:1024
	ds_read_b128 v[148:151], v0 offset:2048
	ds_read_b128 v[152:155], v0 offset:3072
	s_cmp_eq_u32 s23, 12
	s_cselect_b32 s43, s19, s5
	s_cselect_b32 s42, s18, s4
	s_cselect_b32 s51, s21, s22
	s_cselect_b32 s50, s20, s7
	s_add_i32 m0, s27, 0xc000
	ds_read_b128 v[156:159], v172
	ds_read_b128 v[160:163], v172 offset:1024
	ds_read_b128 v[174:177], v172 offset:2048
	ds_read_b128 v[178:181], v172 offset:3072
	ds_read_b128 v[182:185], v172 offset:4096
	ds_read_b128 v[196:199], v172 offset:5120
	ds_read_b128 v[200:203], v172 offset:6144
	ds_read_b128 v[204:207], v172 offset:7168
	global_load_lds_dwordx4 v142, s[2:3]
	s_add_i32 m0, s27, 0xe000
	s_nop 0
	s_add_u32 vcc_lo, s2, s0
	s_addc_u32 vcc_hi, s3, s1
	global_load_lds_dwordx4 v142, vcc
	s_waitcnt lgkmcnt(8)
	s_cmp_eq_u32 s101, 1
	s_cbranch_scc1 .Ldb_WIN_sk
	s_barrier
.Ldb_WIN_sk:
	s_mov_b32 s101, 0
	s_waitcnt lgkmcnt(0)
	v_mfma_f32_16x16x32_bf16 v[132:135], v[136:139], v[156:159], v[132:135]
	v_mfma_f32_16x16x32_bf16 v[128:131], v[148:151], v[156:159], v[128:131]
	v_mfma_f32_16x16x32_bf16 v[116:119], v[136:139], v[174:177], v[116:119]
	v_mfma_f32_16x16x32_bf16 v[112:115], v[148:151], v[174:177], v[112:115]
	v_mfma_f32_16x16x32_bf16 v[100:103], v[136:139], v[182:185], v[100:103]
	v_mfma_f32_16x16x32_bf16 v[96:99], v[148:151], v[182:185], v[96:99]
	v_mfma_f32_16x16x32_bf16 v[84:87], v[136:139], v[200:203], v[84:87]
	v_mfma_f32_16x16x32_bf16 v[80:83], v[148:151], v[200:203], v[80:83]
	v_mfma_f32_16x16x32_bf16 v[132:135], v[144:147], v[160:163], v[132:135]
	v_mfma_f32_16x16x32_bf16 v[128:131], v[152:155], v[160:163], v[128:131]
	v_mfma_f32_16x16x32_bf16 v[116:119], v[144:147], v[178:181], v[116:119]
	v_mfma_f32_16x16x32_bf16 v[112:115], v[152:155], v[178:181], v[112:115]
	v_mfma_f32_16x16x32_bf16 v[100:103], v[144:147], v[196:199], v[100:103]
	v_mfma_f32_16x16x32_bf16 v[96:99], v[152:155], v[196:199], v[96:99]
	v_mfma_f32_16x16x32_bf16 v[84:87], v[144:147], v[204:207], v[84:87]
	v_mfma_f32_16x16x32_bf16 v[80:83], v[152:155], v[204:207], v[80:83]
	s_barrier
	s_add_i32 s4, 0, 0x14000
	s_add_i32 s5, s41, s26
	v_add_u32_e32 v0, s4, v167
	s_mov_b32 m0, s5
	ds_read_b128 v[208:211], v0
	ds_read_b128 v[212:215], v0 offset:1024
	ds_read_b128 v[216:219], v0 offset:2048
	ds_read_b128 v[220:223], v0 offset:3072
	global_load_lds_dwordx4 v140, s[50:51]
	s_add_i32 m0, s5, 0x2000
	s_nop 0
	s_add_u32 vcc_lo, s50, s0
	s_addc_u32 vcc_hi, s51, s1
	global_load_lds_dwordx4 v140, vcc
	s_barrier
	s_waitcnt lgkmcnt(0)
	v_mfma_f32_16x16x32_bf16 v[124:127], v[208:211], v[156:159], v[124:127]
	v_mfma_f32_16x16x32_bf16 v[120:123], v[216:219], v[156:159], v[120:123]
	v_mfma_f32_16x16x32_bf16 v[108:111], v[208:211], v[174:177], v[108:111]
	v_mfma_f32_16x16x32_bf16 v[104:107], v[216:219], v[174:177], v[104:107]
	v_mfma_f32_16x16x32_bf16 v[92:95], v[208:211], v[182:185], v[92:95]
	v_mfma_f32_16x16x32_bf16 v[88:91], v[216:219], v[182:185], v[88:91]
	v_mfma_f32_16x16x32_bf16 v[76:79], v[208:211], v[200:203], v[76:79]
	v_mfma_f32_16x16x32_bf16 v[72:75], v[216:219], v[200:203], v[72:75]
	v_mfma_f32_16x16x32_bf16 v[124:127], v[212:215], v[160:163], v[124:127]
	v_mfma_f32_16x16x32_bf16 v[120:123], v[220:223], v[160:163], v[120:123]
	v_mfma_f32_16x16x32_bf16 v[108:111], v[212:215], v[178:181], v[108:111]
	v_mfma_f32_16x16x32_bf16 v[104:107], v[220:223], v[178:181], v[104:107]
	v_mfma_f32_16x16x32_bf16 v[92:95], v[212:215], v[196:199], v[92:95]
	v_mfma_f32_16x16x32_bf16 v[88:91], v[220:223], v[196:199], v[88:91]
	v_mfma_f32_16x16x32_bf16 v[76:79], v[212:215], v[204:207], v[76:79]
	v_mfma_f32_16x16x32_bf16 v[72:75], v[220:223], v[204:207], v[72:75]
	s_barrier
	s_mov_b32 m0, s27
	ds_read_b128 v[156:159], v172 offset:16384
	ds_read_b128 v[160:163], v172 offset:17408
	ds_read_b128 v[174:177], v172 offset:18432
	ds_read_b128 v[178:181], v172 offset:19456
	ds_read_b128 v[182:185], v172 offset:20480
	ds_read_b128 v[196:199], v172 offset:21504
	ds_read_b128 v[200:203], v172 offset:22528
	ds_read_b128 v[204:207], v172 offset:23552
	global_load_lds_dwordx4 v2, s[42:43]
	s_mov_b32 m0, s28
	s_nop 0
	s_add_u32 vcc_lo, s42, s0
	s_addc_u32 vcc_hi, s43, s1
	global_load_lds_dwordx4 v2, vcc
	s_barrier
	s_waitcnt lgkmcnt(0)
	v_mfma_f32_16x16x32_bf16 v[68:71], v[136:139], v[156:159], v[68:71]
	v_mfma_f32_16x16x32_bf16 v[64:67], v[148:151], v[156:159], v[64:67]
	v_mfma_f32_16x16x32_bf16 v[52:55], v[136:139], v[174:177], v[52:55]
	v_mfma_f32_16x16x32_bf16 v[48:51], v[148:151], v[174:177], v[48:51]
	v_mfma_f32_16x16x32_bf16 v[36:39], v[136:139], v[182:185], v[36:39]
	v_mfma_f32_16x16x32_bf16 v[32:35], v[148:151], v[182:185], v[32:35]
	v_mfma_f32_16x16x32_bf16 v[20:23], v[136:139], v[200:203], v[20:23]
	v_mfma_f32_16x16x32_bf16 v[16:19], v[148:151], v[200:203], v[16:19]
	v_mfma_f32_16x16x32_bf16 v[68:71], v[144:147], v[160:163], v[68:71]
	v_mfma_f32_16x16x32_bf16 v[64:67], v[152:155], v[160:163], v[64:67]
	v_mfma_f32_16x16x32_bf16 v[52:55], v[144:147], v[178:181], v[52:55]
	v_mfma_f32_16x16x32_bf16 v[48:51], v[152:155], v[178:181], v[48:51]
	v_mfma_f32_16x16x32_bf16 v[36:39], v[144:147], v[196:199], v[36:39]
	v_mfma_f32_16x16x32_bf16 v[32:35], v[152:155], v[196:199], v[32:35]
	v_mfma_f32_16x16x32_bf16 v[20:23], v[144:147], v[204:207], v[20:23]
	v_mfma_f32_16x16x32_bf16 v[16:19], v[152:155], v[204:207], v[16:19]
	s_barrier
	s_add_i32 s4, s4, s26
	s_mov_b32 m0, s4
	s_nop 0
	s_add_u32 vcc_lo, s50, s52
	s_addc_u32 vcc_hi, s51, s53
	global_load_lds_dwordx4 v140, vcc
	s_add_i32 m0, s4, 0x2000
	s_nop 0
	s_add_u32 vcc_lo, s50, s54
	s_addc_u32 vcc_hi, s51, s55
	global_load_lds_dwordx4 v140, vcc
	s_waitcnt vmcnt(6)
	s_barrier
; #define G_STAGE(bufoff, gbase, o0, h64) do { \
;         __builtin_amdgcn_global_load_lds((const unsigned*)((const char*)(gbase) + (o0)), (LAS unsigned*)(lds + (bufoff) + ldsw), 16, 0, 0); \
;         __builtin_amdgcn_global_load_lds((const unsigned*)((const char*)(gbase) + (h64) + (o0)), (LAS unsigned*)(lds + (bufoff) + ldsw + 8192), 16, 0, 0); } while (0)
; #define G_LDA(dst, b, h) do { _Pragma("unroll") for (int m = 0; m < 4; ++m) _Pragma("unroll") for (int k = 0; k < 2; ++k) dst[m][k] = *(const LAS bf16x8*)(lds + G_SA(b, h) + aoff + m * 2048 + k * 1024); } while (0)
; #define G_LDB(dst, b, h) do { _Pragma("unroll") for (int n = 0; n < 2; ++n) _Pragma("unroll") for (int k = 0; k < 2; ++k) dst[n][k] = *(const LAS bf16x8*)(lds + G_SB(b, h) + boff + n * 2048 + k * 1024); } while (0)
; #define G_WAIT_V(n) asm volatile("s_waitcnt vmcnt(" #n ")" ::: "memory")
; #define G_BAR __builtin_amdgcn_s_barrier()
;     ...
;         for (int t = 0; t < nt; t += 2) {
;             const bool last = (t == nt - 2);
;             const char* a1 = cA + (size_t)(t + 1) * ckA;
;             const char* a2 = last ? nA : cA + (size_t)(t + 2) * ckA; const char* b2 = last ? nB : cB + (size_t)(t + 2) * kB;
;             const char* a3 = a2 + ckA; const char* b3 = b2 + kB;
;             G_LDB(B0, 0, 0); G_SCHED; G_LDA(At, 0, 0); G_STAGE(G_SA(1, 1), a1 + chA, cA0, qA);
;             G_WAIT_L(8); G_BAR; G_WAIT_L(0); G_MMA(0, 0, At, B0); G_BAR; G_SCHED;
;             G_LDB(B1, 0, 1); G_STAGE(G_SB(0, 0), b2, cB0, qB);
;             G_BAR; G_WAIT_L(0); G_MMA(0, 1, At, B1); G_BAR;
;             G_LDA(At, 0, 1); G_STAGE(G_SA(0, 0), a2, cA0, qA);
;             G_BAR; G_WAIT_L(0); G_MMA(1, 0, At, B0); G_BAR; G_SCHED;
;             G_STAGE(G_SB(0, 1), b2 + chB, cB0, qB);
;             G_WAIT_V(6); G_BAR; G_MMA(1, 1, At, B1); G_BAR;
;             G_LDB(B0, 1, 0); G_SCHED; G_LDA(At, 1, 0); G_STAGE(G_SA(0, 1), a2 + chA, cA0, qA);
;             G_WAIT_L(8); G_BAR; G_WAIT_L(0); G_MMA(0, 0, At, B0); G_BAR; G_SCHED;
;             G_LDB(B1, 1, 1); G_STAGE(G_SB(1, 0), b3, cB0, qB);
;             G_BAR; G_WAIT_L(0); G_MMA(0, 1, At, B1); G_BAR;
;             G_LDA(At, 1, 1); G_STAGE(G_SA(1, 0), a3, cA0, qA);
;             G_BAR; G_WAIT_L(0); G_MMA(1, 0, At, B0); G_BAR; G_SCHED;
;             G_STAGE(G_SB(1, 1), b3 + chB, cB0, qB);
;             G_WAIT_V(6); G_BAR; G_MMA(1, 1, At, B1); G_BAR;
	v_mfma_f32_16x16x32_bf16 v[60:63], v[208:211], v[156:159], v[60:63]
	v_mfma_f32_16x16x32_bf16 v[56:59], v[216:219], v[156:159], v[56:59]
	v_mfma_f32_16x16x32_bf16 v[44:47], v[208:211], v[174:177], v[44:47]
	v_mfma_f32_16x16x32_bf16 v[40:43], v[216:219], v[174:177], v[40:43]
	v_mfma_f32_16x16x32_bf16 v[28:31], v[208:211], v[182:185], v[28:31]
	v_mfma_f32_16x16x32_bf16 v[24:27], v[216:219], v[182:185], v[24:27]
	v_mfma_f32_16x16x32_bf16 v[12:15], v[208:211], v[200:203], v[12:15]
	v_mfma_f32_16x16x32_bf16 v[8:11], v[216:219], v[200:203], v[8:11]
	v_mfma_f32_16x16x32_bf16 v[60:63], v[212:215], v[160:163], v[60:63]
	v_mfma_f32_16x16x32_bf16 v[56:59], v[220:223], v[160:163], v[56:59]
	v_mfma_f32_16x16x32_bf16 v[44:47], v[212:215], v[178:181], v[44:47]
	v_mfma_f32_16x16x32_bf16 v[40:43], v[220:223], v[178:181], v[40:43]
	v_mfma_f32_16x16x32_bf16 v[28:31], v[212:215], v[196:199], v[28:31]
	v_mfma_f32_16x16x32_bf16 v[24:27], v[220:223], v[196:199], v[24:27]
	v_mfma_f32_16x16x32_bf16 v[12:15], v[212:215], v[204:207], v[12:15]
	v_mfma_f32_16x16x32_bf16 v[8:11], v[220:223], v[204:207], v[8:11]
	s_barrier
	s_add_i32 s4, 0, 0x18000
	v_add_u32_e32 v0, s4, v167
	ds_read_b128 v[136:139], v0
	ds_read_b128 v[144:147], v0 offset:1024
	ds_read_b128 v[148:151], v0 offset:2048
	ds_read_b128 v[152:155], v0 offset:3072
	s_mov_b32 m0, s29
	ds_read_b128 v[156:159], v172 offset:32768
	ds_read_b128 v[160:163], v172 offset:33792
	ds_read_b128 v[174:177], v172 offset:34816
	ds_read_b128 v[178:181], v172 offset:35840
	ds_read_b128 v[182:185], v172 offset:36864
	ds_read_b128 v[196:199], v172 offset:37888
	ds_read_b128 v[200:203], v172 offset:38912
	ds_read_b128 v[204:207], v172 offset:39936
	s_add_u32 vcc_lo, s42, s52
	s_addc_u32 vcc_hi, s43, s53
	global_load_lds_dwordx4 v2, vcc
	s_mov_b32 m0, s30
	s_nop 0
	s_add_u32 vcc_lo, s42, s54
	s_addc_u32 vcc_hi, s43, s55
	global_load_lds_dwordx4 v2, vcc
	s_waitcnt lgkmcnt(8)
	s_barrier
	s_waitcnt lgkmcnt(0)
	v_mfma_f32_16x16x32_bf16 v[132:135], v[136:139], v[156:159], v[132:135]
	v_mfma_f32_16x16x32_bf16 v[128:131], v[148:151], v[156:159], v[128:131]
	v_mfma_f32_16x16x32_bf16 v[116:119], v[136:139], v[174:177], v[116:119]
	v_mfma_f32_16x16x32_bf16 v[112:115], v[148:151], v[174:177], v[112:115]
	v_mfma_f32_16x16x32_bf16 v[100:103], v[136:139], v[182:185], v[100:103]
	v_mfma_f32_16x16x32_bf16 v[96:99], v[148:151], v[182:185], v[96:99]
	v_mfma_f32_16x16x32_bf16 v[84:87], v[136:139], v[200:203], v[84:87]
	v_mfma_f32_16x16x32_bf16 v[80:83], v[148:151], v[200:203], v[80:83]
	v_mfma_f32_16x16x32_bf16 v[132:135], v[144:147], v[160:163], v[132:135]
	v_mfma_f32_16x16x32_bf16 v[128:131], v[152:155], v[160:163], v[128:131]
	v_mfma_f32_16x16x32_bf16 v[116:119], v[144:147], v[178:181], v[116:119]
	v_mfma_f32_16x16x32_bf16 v[112:115], v[152:155], v[178:181], v[112:115]
	v_mfma_f32_16x16x32_bf16 v[100:103], v[144:147], v[196:199], v[100:103]
	v_mfma_f32_16x16x32_bf16 v[96:99], v[152:155], v[196:199], v[96:99]
	v_mfma_f32_16x16x32_bf16 v[84:87], v[144:147], v[204:207], v[84:87]
	v_mfma_f32_16x16x32_bf16 v[80:83], v[152:155], v[204:207], v[80:83]
	s_barrier
	s_add_i32 s5, 0, 0x1c000
	s_add_i32 s4, s4, s26
	v_add_u32_e32 v0, s5, v167
	s_mov_b32 m0, s4
	ds_read_b128 v[208:211], v0
	ds_read_b128 v[212:215], v0 offset:1024
	ds_read_b128 v[216:219], v0 offset:2048
	ds_read_b128 v[220:223], v0 offset:3072
	s_add_u32 vcc_lo, s50, s46
	s_addc_u32 vcc_hi, s51, s47
	global_load_lds_dwordx4 v140, vcc
	s_add_i32 m0, s4, 0x2000
	s_nop 0
	s_add_u32 vcc_lo, s50, s58
	s_addc_u32 vcc_hi, s51, s59
	global_load_lds_dwordx4 v140, vcc
	s_barrier
; #define G_STAGE(bufoff, gbase, o0, h64) do { \
;         __builtin_amdgcn_global_load_lds((const unsigned*)((const char*)(gbase) + (o0)), (LAS unsigned*)(lds + (bufoff) + ldsw), 16, 0, 0); \
;         __builtin_amdgcn_global_load_lds((const unsigned*)((const char*)(gbase) + (h64) + (o0)), (LAS unsigned*)(lds + (bufoff) + ldsw + 8192), 16, 0, 0); } while (0)
; #define G_LDA(dst, b, h) do { _Pragma("unroll") for (int m = 0; m < 4; ++m) _Pragma("unroll") for (int k = 0; k < 2; ++k) dst[m][k] = *(const LAS bf16x8*)(lds + G_SA(b, h) + aoff + m * 2048 + k * 1024); } while (0)
; #define G_LDB(dst, b, h) do { _Pragma("unroll") for (int n = 0; n < 2; ++n) _Pragma("unroll") for (int k = 0; k < 2; ++k) dst[n][k] = *(const LAS bf16x8*)(lds + G_SB(b, h) + boff + n * 2048 + k * 1024); } while (0)
; #define G_WAIT_V(n) asm volatile("s_waitcnt vmcnt(" #n ")" ::: "memory")
; #define G_BAR __builtin_amdgcn_s_barrier()
;     ...
;         for (int t = 0; t < nt; t += 2) {
;             const bool last = (t == nt - 2);
;             const char* a1 = cA + (size_t)(t + 1) * ckA;
;             const char* a2 = last ? nA : cA + (size_t)(t + 2) * ckA; const char* b2 = last ? nB : cB + (size_t)(t + 2) * kB;
;             const char* a3 = a2 + ckA; const char* b3 = b2 + kB;
;             G_LDB(B0, 0, 0); G_SCHED; G_LDA(At, 0, 0); G_STAGE(G_SA(1, 1), a1 + chA, cA0, qA);
;             G_WAIT_L(8); G_BAR; G_WAIT_L(0); G_MMA(0, 0, At, B0); G_BAR; G_SCHED;
;             G_LDB(B1, 0, 1); G_STAGE(G_SB(0, 0), b2, cB0, qB);
;             G_BAR; G_WAIT_L(0); G_MMA(0, 1, At, B1); G_BAR;
;             G_LDA(At, 0, 1); G_STAGE(G_SA(0, 0), a2, cA0, qA);
;             G_BAR; G_WAIT_L(0); G_MMA(1, 0, At, B0); G_BAR; G_SCHED;
;             G_STAGE(G_SB(0, 1), b2 + chB, cB0, qB);
;             G_WAIT_V(6); G_BAR; G_MMA(1, 1, At, B1); G_BAR;
;             G_LDB(B0, 1, 0); G_SCHED; G_LDA(At, 1, 0); G_STAGE(G_SA(0, 1), a2 + chA, cA0, qA);
;             G_WAIT_L(8); G_BAR; G_WAIT_L(0); G_MMA(0, 0, At, B0); G_BAR; G_SCHED;
;             G_LDB(B1, 1, 1); G_STAGE(G_SB(1, 0), b3, cB0, qB);
;             G_BAR; G_WAIT_L(0); G_MMA(0, 1, At, B1); G_BAR;
;             G_LDA(At, 1, 1); G_STAGE(G_SA(1, 0), a3, cA0, qA);
;             G_BAR; G_WAIT_L(0); G_MMA(1, 0, At, B0); G_BAR; G_SCHED;
;             G_STAGE(G_SB(1, 1), b3 + chB, cB0, qB);
;             G_WAIT_V(6); G_BAR; G_MMA(1, 1, At, B1); G_BAR;
	s_waitcnt lgkmcnt(0)
	v_mfma_f32_16x16x32_bf16 v[124:127], v[208:211], v[156:159], v[124:127]
	v_mfma_f32_16x16x32_bf16 v[120:123], v[216:219], v[156:159], v[120:123]
	v_mfma_f32_16x16x32_bf16 v[108:111], v[208:211], v[174:177], v[108:111]
	v_mfma_f32_16x16x32_bf16 v[104:107], v[216:219], v[174:177], v[104:107]
	v_mfma_f32_16x16x32_bf16 v[92:95], v[208:211], v[182:185], v[92:95]
	v_mfma_f32_16x16x32_bf16 v[88:91], v[216:219], v[182:185], v[88:91]
	v_mfma_f32_16x16x32_bf16 v[76:79], v[208:211], v[200:203], v[76:79]
	v_mfma_f32_16x16x32_bf16 v[72:75], v[216:219], v[200:203], v[72:75]
	v_mfma_f32_16x16x32_bf16 v[124:127], v[212:215], v[160:163], v[124:127]
	v_mfma_f32_16x16x32_bf16 v[120:123], v[220:223], v[160:163], v[120:123]
	v_mfma_f32_16x16x32_bf16 v[108:111], v[212:215], v[178:181], v[108:111]
	v_mfma_f32_16x16x32_bf16 v[104:107], v[220:223], v[178:181], v[104:107]
	v_mfma_f32_16x16x32_bf16 v[92:95], v[212:215], v[196:199], v[92:95]
	v_mfma_f32_16x16x32_bf16 v[88:91], v[220:223], v[196:199], v[88:91]
	v_mfma_f32_16x16x32_bf16 v[76:79], v[212:215], v[204:207], v[76:79]
	v_mfma_f32_16x16x32_bf16 v[72:75], v[220:223], v[204:207], v[72:75]
	s_barrier
	s_mov_b32 m0, s31
	ds_read_b128 v[156:159], v172 offset:49152
	ds_read_b128 v[160:163], v172 offset:50176
	ds_read_b128 v[174:177], v172 offset:51200
	ds_read_b128 v[178:181], v172 offset:52224
	ds_read_b128 v[182:185], v172 offset:53248
	ds_read_b128 v[196:199], v172 offset:54272
	ds_read_b128 v[200:203], v172 offset:55296
	ds_read_b128 v[204:207], v172 offset:56320
	s_add_u32 vcc_lo, s42, s46
	s_addc_u32 vcc_hi, s43, s47
	global_load_lds_dwordx4 v2, vcc
	s_mov_b32 m0, s34
	s_nop 0
	s_add_u32 vcc_lo, s42, s58
	s_addc_u32 vcc_hi, s43, s59
	global_load_lds_dwordx4 v2, vcc
	s_barrier
	s_waitcnt lgkmcnt(0)
	v_mfma_f32_16x16x32_bf16 v[68:71], v[136:139], v[156:159], v[68:71]
	v_mfma_f32_16x16x32_bf16 v[64:67], v[148:151], v[156:159], v[64:67]
	v_mfma_f32_16x16x32_bf16 v[52:55], v[136:139], v[174:177], v[52:55]
	v_mfma_f32_16x16x32_bf16 v[48:51], v[148:151], v[174:177], v[48:51]
	v_mfma_f32_16x16x32_bf16 v[36:39], v[136:139], v[182:185], v[36:39]
	v_mfma_f32_16x16x32_bf16 v[32:35], v[148:151], v[182:185], v[32:35]
	v_mfma_f32_16x16x32_bf16 v[20:23], v[136:139], v[200:203], v[20:23]
	v_mfma_f32_16x16x32_bf16 v[16:19], v[148:151], v[200:203], v[16:19]
	v_mfma_f32_16x16x32_bf16 v[68:71], v[144:147], v[160:163], v[68:71]
	v_mfma_f32_16x16x32_bf16 v[64:67], v[152:155], v[160:163], v[64:67]
	v_mfma_f32_16x16x32_bf16 v[52:55], v[144:147], v[178:181], v[52:55]
	v_mfma_f32_16x16x32_bf16 v[48:51], v[152:155], v[178:181], v[48:51]
	v_mfma_f32_16x16x32_bf16 v[36:39], v[144:147], v[196:199], v[36:39]
	v_mfma_f32_16x16x32_bf16 v[32:35], v[152:155], v[196:199], v[32:35]
	v_mfma_f32_16x16x32_bf16 v[20:23], v[144:147], v[204:207], v[20:23]
	v_mfma_f32_16x16x32_bf16 v[16:19], v[152:155], v[204:207], v[16:19]
	s_barrier
	s_add_i32 s4, s5, s26
	s_mov_b32 m0, s4
	s_nop 0
	s_add_u32 vcc_lo, s50, s62
	s_addc_u32 vcc_hi, s51, s63
	global_load_lds_dwordx4 v140, vcc
	s_add_i32 m0, s4, 0x2000
	s_nop 0
	s_add_u32 vcc_lo, s50, s64
	s_addc_u32 vcc_hi, s51, s65
	global_load_lds_dwordx4 v140, vcc
	s_add_i32 s23, s23, 2
	s_add_u32 s2, s2, 0x100
	s_addc_u32 s3, s3, 0
	s_add_u32 s7, s7, 0x100
	s_addc_u32 s22, s22, 0
	s_cmp_gt_u32 s23, 13
	s_waitcnt vmcnt(6)
	s_barrier
	v_mfma_f32_16x16x32_bf16 v[60:63], v[208:211], v[156:159], v[60:63]
	v_mfma_f32_16x16x32_bf16 v[56:59], v[216:219], v[156:159], v[56:59]
	v_mfma_f32_16x16x32_bf16 v[44:47], v[208:211], v[174:177], v[44:47]
	v_mfma_f32_16x16x32_bf16 v[40:43], v[216:219], v[174:177], v[40:43]
	v_mfma_f32_16x16x32_bf16 v[28:31], v[208:211], v[182:185], v[28:31]
	v_mfma_f32_16x16x32_bf16 v[24:27], v[216:219], v[182:185], v[24:27]
	v_mfma_f32_16x16x32_bf16 v[12:15], v[208:211], v[200:203], v[12:15]
	v_mfma_f32_16x16x32_bf16 v[8:11], v[216:219], v[200:203], v[8:11]
	v_mfma_f32_16x16x32_bf16 v[60:63], v[212:215], v[160:163], v[60:63]
	v_mfma_f32_16x16x32_bf16 v[56:59], v[220:223], v[160:163], v[56:59]
	v_mfma_f32_16x16x32_bf16 v[44:47], v[212:215], v[178:181], v[44:47]
	v_mfma_f32_16x16x32_bf16 v[40:43], v[220:223], v[178:181], v[40:43]
	v_mfma_f32_16x16x32_bf16 v[28:31], v[212:215], v[196:199], v[28:31]
	v_mfma_f32_16x16x32_bf16 v[24:27], v[220:223], v[196:199], v[24:27]
	v_mfma_f32_16x16x32_bf16 v[12:15], v[212:215], v[204:207], v[12:15]
	v_mfma_f32_16x16x32_bf16 v[8:11], v[220:223], v[204:207], v[8:11]
	s_cbranch_scc0 .Ldb_WIN_cont
	v_readfirstlane_b32 s101, v186
	s_cmpk_gt_u32 s101, 0xff
	s_cbranch_scc1 .Ldb_WIN_young
	s_barrier
	s_mov_b32 s101, 1
	s_branch .Ldb_WIN_exit

; #define G_STAGE(bufoff, gbase, o0, h64) do { \
;         __builtin_amdgcn_global_load_lds((const unsigned*)((const char*)(gbase) + (o0)), (LAS unsigned*)(lds + (bufoff) + ldsw), 16, 0, 0); \
;         __builtin_amdgcn_global_load_lds((const unsigned*)((const char*)(gbase) + (h64) + (o0)), (LAS unsigned*)(lds + (bufoff) + ldsw + 8192), 16, 0, 0); } while (0)
; #define G_LDA(dst, b, h) do { _Pragma("unroll") for (int m = 0; m < 4; ++m) _Pragma("unroll") for (int k = 0; k < 2; ++k) dst[m][k] = *(const LAS bf16x8*)(lds + G_SA(b, h) + aoff + m * 2048 + k * 1024); } while (0)
; #define G_LDB(dst, b, h) do { _Pragma("unroll") for (int n = 0; n < 2; ++n) _Pragma("unroll") for (int k = 0; k < 2; ++k) dst[n][k] = *(const LAS bf16x8*)(lds + G_SB(b, h) + boff + n * 2048 + k * 1024); } while (0)
; #define G_WAIT_V(n) asm volatile("s_waitcnt vmcnt(" #n ")" ::: "memory")
; #define G_BAR __builtin_amdgcn_s_barrier()
;     ...
;         for (int t = 0; t < nt; t += 2) {
;             const bool last = (t == nt - 2);
;             const char* a1 = cA + (size_t)(t + 1) * ckA;
;             const char* a2 = last ? nA : cA + (size_t)(t + 2) * ckA; const char* b2 = last ? nB : cB + (size_t)(t + 2) * kB;
;             const char* a3 = a2 + ckA; const char* b3 = b2 + kB;
;             G_LDB(B0, 0, 0); G_SCHED; G_LDA(At, 0, 0); G_STAGE(G_SA(1, 1), a1 + chA, cA0, qA);
;             G_WAIT_L(8); G_BAR; G_WAIT_L(0); G_MMA(0, 0, At, B0); G_BAR; G_SCHED;
;             G_LDB(B1, 0, 1); G_STAGE(G_SB(0, 0), b2, cB0, qB);
;             G_BAR; G_WAIT_L(0); G_MMA(0, 1, At, B1); G_BAR;
;             G_LDA(At, 0, 1); G_STAGE(G_SA(0, 0), a2, cA0, qA);
;             G_BAR; G_WAIT_L(0); G_MMA(1, 0, At, B0); G_BAR; G_SCHED;
;             G_STAGE(G_SB(0, 1), b2 + chB, cB0, qB);
;             G_WAIT_V(6); G_BAR; G_MMA(1, 1, At, B1); G_BAR;
;             G_LDB(B0, 1, 0); G_SCHED; G_LDA(At, 1, 0); G_STAGE(G_SA(0, 1), a2 + chA, cA0, qA);
;             G_WAIT_L(8); G_BAR; G_WAIT_L(0); G_MMA(0, 0, At, B0); G_BAR; G_SCHED;
;             G_LDB(B1, 1, 1); G_STAGE(G_SB(1, 0), b3, cB0, qB);
;             G_BAR; G_WAIT_L(0); G_MMA(0, 1, At, B1); G_BAR;
;             G_LDA(At, 1, 1); G_STAGE(G_SA(1, 0), a3, cA0, qA);
;             G_BAR; G_WAIT_L(0); G_MMA(1, 0, At, B0); G_BAR; G_SCHED;
;             G_STAGE(G_SB(1, 1), b3 + chB, cB0, qB);
;             G_WAIT_V(6); G_BAR; G_MMA(1, 1, At, B1); G_BAR;
.LBB0_450:
	s_add_u32 s4, s6, 0xfffe0080
	s_addc_u32 s5, s7, -1
	s_add_i32 s41, 0, 0x10000
	v_add_u32_e32 v0, s41, v145
	ds_read_b128 v[140:143], v0
	ds_read_b128 v[148:151], v0 offset:1024
	ds_read_b128 v[152:155], v0 offset:2048
	ds_read_b128 v[156:159], v0 offset:3072
	s_cmp_eq_u32 s21, 4
	s_cselect_b32 s23, s11, s5
	s_cselect_b32 s22, s10, s4
	s_cselect_b32 s43, s17, s20
	s_cselect_b32 s42, s16, s19
	s_add_i32 m0, s27, 0xc000
	ds_read_b128 v[160:163], v146
	ds_read_b128 v[164:167], v146 offset:1024
	ds_read_b128 v[172:175], v146 offset:2048
	ds_read_b128 v[176:179], v146 offset:3072
	ds_read_b128 v[180:183], v146 offset:4096
	ds_read_b128 v[196:199], v146 offset:5120
	ds_read_b128 v[200:203], v146 offset:6144
	ds_read_b128 v[204:207], v146 offset:7168
	global_load_lds_dwordx4 v138, s[6:7]
	s_add_i32 m0, s27, 0xe000
	s_nop 0
	s_add_u32 vcc_lo, s6, s52
	s_addc_u32 vcc_hi, s7, s53
	global_load_lds_dwordx4 v138, vcc
	s_waitcnt lgkmcnt(8)
	s_cmp_eq_u32 s101, 1
	s_cbranch_scc1 .Ldb_SSM1_sk
	s_barrier
.Ldb_SSM1_sk:
	s_mov_b32 s101, 0
	s_waitcnt lgkmcnt(0)
	v_mfma_f32_16x16x32_bf16 v[132:135], v[140:143], v[160:163], v[132:135]
	v_mfma_f32_16x16x32_bf16 v[128:131], v[152:155], v[160:163], v[128:131]
	v_mfma_f32_16x16x32_bf16 v[116:119], v[140:143], v[172:175], v[116:119]
	v_mfma_f32_16x16x32_bf16 v[112:115], v[152:155], v[172:175], v[112:115]
	v_mfma_f32_16x16x32_bf16 v[100:103], v[140:143], v[180:183], v[100:103]
	v_mfma_f32_16x16x32_bf16 v[96:99], v[152:155], v[180:183], v[96:99]
	v_mfma_f32_16x16x32_bf16 v[84:87], v[140:143], v[200:203], v[84:87]
	v_mfma_f32_16x16x32_bf16 v[80:83], v[152:155], v[200:203], v[80:83]
	v_mfma_f32_16x16x32_bf16 v[132:135], v[148:151], v[164:167], v[132:135]
	v_mfma_f32_16x16x32_bf16 v[128:131], v[156:159], v[164:167], v[128:131]
	v_mfma_f32_16x16x32_bf16 v[116:119], v[148:151], v[176:179], v[116:119]
	v_mfma_f32_16x16x32_bf16 v[112:115], v[156:159], v[176:179], v[112:115]
	v_mfma_f32_16x16x32_bf16 v[100:103], v[148:151], v[196:199], v[100:103]
	v_mfma_f32_16x16x32_bf16 v[96:99], v[156:159], v[196:199], v[96:99]
	v_mfma_f32_16x16x32_bf16 v[84:87], v[148:151], v[204:207], v[84:87]
	v_mfma_f32_16x16x32_bf16 v[80:83], v[156:159], v[204:207], v[80:83]
	s_barrier
	s_add_i32 s4, 0, 0x14000
	s_add_i32 s5, s41, s26
	v_add_u32_e32 v0, s4, v145
	s_mov_b32 m0, s5
	ds_read_b128 v[208:211], v0
	ds_read_b128 v[212:215], v0 offset:1024
	ds_read_b128 v[216:219], v0 offset:2048
	ds_read_b128 v[220:223], v0 offset:3072
	global_load_lds_dwordx4 v136, s[42:43]
	s_add_i32 m0, s5, 0x2000
	s_nop 0
	s_add_u32 vcc_lo, s42, s52
	s_addc_u32 vcc_hi, s43, s53
	global_load_lds_dwordx4 v136, vcc
	s_barrier
	s_waitcnt lgkmcnt(0)
	v_mfma_f32_16x16x32_bf16 v[124:127], v[208:211], v[160:163], v[124:127]
	v_mfma_f32_16x16x32_bf16 v[120:123], v[216:219], v[160:163], v[120:123]
	v_mfma_f32_16x16x32_bf16 v[108:111], v[208:211], v[172:175], v[108:111]
	v_mfma_f32_16x16x32_bf16 v[104:107], v[216:219], v[172:175], v[104:107]
	v_mfma_f32_16x16x32_bf16 v[92:95], v[208:211], v[180:183], v[92:95]
	v_mfma_f32_16x16x32_bf16 v[88:91], v[216:219], v[180:183], v[88:91]
	v_mfma_f32_16x16x32_bf16 v[76:79], v[208:211], v[200:203], v[76:79]
	v_mfma_f32_16x16x32_bf16 v[72:75], v[216:219], v[200:203], v[72:75]
	v_mfma_f32_16x16x32_bf16 v[124:127], v[212:215], v[164:167], v[124:127]
	v_mfma_f32_16x16x32_bf16 v[120:123], v[220:223], v[164:167], v[120:123]
	v_mfma_f32_16x16x32_bf16 v[108:111], v[212:215], v[176:179], v[108:111]
	v_mfma_f32_16x16x32_bf16 v[104:107], v[220:223], v[176:179], v[104:107]
	v_mfma_f32_16x16x32_bf16 v[92:95], v[212:215], v[196:199], v[92:95]
	v_mfma_f32_16x16x32_bf16 v[88:91], v[220:223], v[196:199], v[88:91]
	v_mfma_f32_16x16x32_bf16 v[76:79], v[212:215], v[204:207], v[76:79]
	v_mfma_f32_16x16x32_bf16 v[72:75], v[220:223], v[204:207], v[72:75]
	s_barrier
	s_mov_b32 m0, s27
	ds_read_b128 v[160:163], v146 offset:16384
	ds_read_b128 v[164:167], v146 offset:17408
	ds_read_b128 v[172:175], v146 offset:18432
	ds_read_b128 v[176:179], v146 offset:19456
	ds_read_b128 v[180:183], v146 offset:20480
	ds_read_b128 v[196:199], v146 offset:21504
	ds_read_b128 v[200:203], v146 offset:22528
	ds_read_b128 v[204:207], v146 offset:23552
	global_load_lds_dwordx4 v2, s[22:23]
	s_mov_b32 m0, s28
	s_nop 0
	s_add_u32 vcc_lo, s22, s52
	s_addc_u32 vcc_hi, s23, s53
	global_load_lds_dwordx4 v2, vcc
	s_barrier
	s_waitcnt lgkmcnt(0)
	v_mfma_f32_16x16x32_bf16 v[68:71], v[140:143], v[160:163], v[68:71]
	v_mfma_f32_16x16x32_bf16 v[64:67], v[152:155], v[160:163], v[64:67]
	v_mfma_f32_16x16x32_bf16 v[52:55], v[140:143], v[172:175], v[52:55]
	v_mfma_f32_16x16x32_bf16 v[48:51], v[152:155], v[172:175], v[48:51]
	v_mfma_f32_16x16x32_bf16 v[36:39], v[140:143], v[180:183], v[36:39]
	v_mfma_f32_16x16x32_bf16 v[32:35], v[152:155], v[180:183], v[32:35]
	v_mfma_f32_16x16x32_bf16 v[20:23], v[140:143], v[200:203], v[20:23]
	v_mfma_f32_16x16x32_bf16 v[16:19], v[152:155], v[200:203], v[16:19]
	v_mfma_f32_16x16x32_bf16 v[68:71], v[148:151], v[164:167], v[68:71]
	v_mfma_f32_16x16x32_bf16 v[64:67], v[156:159], v[164:167], v[64:67]
	v_mfma_f32_16x16x32_bf16 v[52:55], v[148:151], v[176:179], v[52:55]
	v_mfma_f32_16x16x32_bf16 v[48:51], v[156:159], v[176:179], v[48:51]
	v_mfma_f32_16x16x32_bf16 v[36:39], v[148:151], v[196:199], v[36:39]
	v_mfma_f32_16x16x32_bf16 v[32:35], v[156:159], v[196:199], v[32:35]
	v_mfma_f32_16x16x32_bf16 v[20:23], v[148:151], v[204:207], v[20:23]
	v_mfma_f32_16x16x32_bf16 v[16:19], v[156:159], v[204:207], v[16:19]
	s_barrier
; #define G_STAGE(bufoff, gbase, o0, h64) do { \
;         __builtin_amdgcn_global_load_lds((const unsigned*)((const char*)(gbase) + (o0)), (LAS unsigned*)(lds + (bufoff) + ldsw), 16, 0, 0); \
;         __builtin_amdgcn_global_load_lds((const unsigned*)((const char*)(gbase) + (h64) + (o0)), (LAS unsigned*)(lds + (bufoff) + ldsw + 8192), 16, 0, 0); } while (0)
; #define G_LDA(dst, b, h) do { _Pragma("unroll") for (int m = 0; m < 4; ++m) _Pragma("unroll") for (int k = 0; k < 2; ++k) dst[m][k] = *(const LAS bf16x8*)(lds + G_SA(b, h) + aoff + m * 2048 + k * 1024); } while (0)
; #define G_LDB(dst, b, h) do { _Pragma("unroll") for (int n = 0; n < 2; ++n) _Pragma("unroll") for (int k = 0; k < 2; ++k) dst[n][k] = *(const LAS bf16x8*)(lds + G_SB(b, h) + boff + n * 2048 + k * 1024); } while (0)
; #define G_WAIT_V(n) asm volatile("s_waitcnt vmcnt(" #n ")" ::: "memory")
; #define G_BAR __builtin_amdgcn_s_barrier()
;     ...
;         for (int t = 0; t < nt; t += 2) {
;             const bool last = (t == nt - 2);
;             const char* a1 = cA + (size_t)(t + 1) * ckA;
;             const char* a2 = last ? nA : cA + (size_t)(t + 2) * ckA; const char* b2 = last ? nB : cB + (size_t)(t + 2) * kB;
;             const char* a3 = a2 + ckA; const char* b3 = b2 + kB;
;             G_LDB(B0, 0, 0); G_SCHED; G_LDA(At, 0, 0); G_STAGE(G_SA(1, 1), a1 + chA, cA0, qA);
;             G_WAIT_L(8); G_BAR; G_WAIT_L(0); G_MMA(0, 0, At, B0); G_BAR; G_SCHED;
;             G_LDB(B1, 0, 1); G_STAGE(G_SB(0, 0), b2, cB0, qB);
;             G_BAR; G_WAIT_L(0); G_MMA(0, 1, At, B1); G_BAR;
;             G_LDA(At, 0, 1); G_STAGE(G_SA(0, 0), a2, cA0, qA);
;             G_BAR; G_WAIT_L(0); G_MMA(1, 0, At, B0); G_BAR; G_SCHED;
;             G_STAGE(G_SB(0, 1), b2 + chB, cB0, qB);
;             G_WAIT_V(6); G_BAR; G_MMA(1, 1, At, B1); G_BAR;
;             G_LDB(B0, 1, 0); G_SCHED; G_LDA(At, 1, 0); G_STAGE(G_SA(0, 1), a2 + chA, cA0, qA);
;             G_WAIT_L(8); G_BAR; G_WAIT_L(0); G_MMA(0, 0, At, B0); G_BAR; G_SCHED;
;             G_LDB(B1, 1, 1); G_STAGE(G_SB(1, 0), b3, cB0, qB);
;             G_BAR; G_WAIT_L(0); G_MMA(0, 1, At, B1); G_BAR;
;             G_LDA(At, 1, 1); G_STAGE(G_SA(1, 0), a3, cA0, qA);
;             G_BAR; G_WAIT_L(0); G_MMA(1, 0, At, B0); G_BAR; G_SCHED;
;             G_STAGE(G_SB(1, 1), b3 + chB, cB0, qB);
;             G_WAIT_V(6); G_BAR; G_MMA(1, 1, At, B1); G_BAR;
	s_add_i32 s4, s4, s26
	s_mov_b32 m0, s4
	s_nop 0
	s_add_u32 vcc_lo, s42, s0
	s_addc_u32 vcc_hi, s43, s1
	global_load_lds_dwordx4 v136, vcc
	s_add_i32 m0, s4, 0x2000
	s_nop 0
	s_add_u32 vcc_lo, s42, s54
	s_addc_u32 vcc_hi, s43, s55
	global_load_lds_dwordx4 v136, vcc
	s_waitcnt vmcnt(6)
	s_barrier
	v_mfma_f32_16x16x32_bf16 v[60:63], v[208:211], v[160:163], v[60:63]
	v_mfma_f32_16x16x32_bf16 v[56:59], v[216:219], v[160:163], v[56:59]
	v_mfma_f32_16x16x32_bf16 v[44:47], v[208:211], v[172:175], v[44:47]
	v_mfma_f32_16x16x32_bf16 v[40:43], v[216:219], v[172:175], v[40:43]
	v_mfma_f32_16x16x32_bf16 v[28:31], v[208:211], v[180:183], v[28:31]
	v_mfma_f32_16x16x32_bf16 v[24:27], v[216:219], v[180:183], v[24:27]
	v_mfma_f32_16x16x32_bf16 v[12:15], v[208:211], v[200:203], v[12:15]
	v_mfma_f32_16x16x32_bf16 v[8:11], v[216:219], v[200:203], v[8:11]
	v_mfma_f32_16x16x32_bf16 v[60:63], v[212:215], v[164:167], v[60:63]
	v_mfma_f32_16x16x32_bf16 v[56:59], v[220:223], v[164:167], v[56:59]
	v_mfma_f32_16x16x32_bf16 v[44:47], v[212:215], v[176:179], v[44:47]
	v_mfma_f32_16x16x32_bf16 v[40:43], v[220:223], v[176:179], v[40:43]
	v_mfma_f32_16x16x32_bf16 v[28:31], v[212:215], v[196:199], v[28:31]
	v_mfma_f32_16x16x32_bf16 v[24:27], v[220:223], v[196:199], v[24:27]
	v_mfma_f32_16x16x32_bf16 v[12:15], v[212:215], v[204:207], v[12:15]
	v_mfma_f32_16x16x32_bf16 v[8:11], v[220:223], v[204:207], v[8:11]
	s_barrier
	s_add_i32 s4, 0, 0x18000
	v_add_u32_e32 v0, s4, v145
	ds_read_b128 v[140:143], v0
	ds_read_b128 v[148:151], v0 offset:1024
	ds_read_b128 v[152:155], v0 offset:2048
	ds_read_b128 v[156:159], v0 offset:3072
	s_mov_b32 m0, s29
	ds_read_b128 v[160:163], v146 offset:32768
	ds_read_b128 v[164:167], v146 offset:33792
	ds_read_b128 v[172:175], v146 offset:34816
	ds_read_b128 v[176:179], v146 offset:35840
	ds_read_b128 v[180:183], v146 offset:36864
	ds_read_b128 v[196:199], v146 offset:37888
	ds_read_b128 v[200:203], v146 offset:38912
	ds_read_b128 v[204:207], v146 offset:39936
	s_add_u32 vcc_lo, s22, s0
	s_addc_u32 vcc_hi, s23, s1
	global_load_lds_dwordx4 v2, vcc
	s_mov_b32 m0, s30
	s_nop 0
	s_add_u32 vcc_lo, s22, s54
	s_addc_u32 vcc_hi, s23, s55
	global_load_lds_dwordx4 v2, vcc
	s_waitcnt lgkmcnt(8)
	s_barrier
	s_waitcnt lgkmcnt(0)
	v_mfma_f32_16x16x32_bf16 v[132:135], v[140:143], v[160:163], v[132:135]
	v_mfma_f32_16x16x32_bf16 v[128:131], v[152:155], v[160:163], v[128:131]
	v_mfma_f32_16x16x32_bf16 v[116:119], v[140:143], v[172:175], v[116:119]
	v_mfma_f32_16x16x32_bf16 v[112:115], v[152:155], v[172:175], v[112:115]
	v_mfma_f32_16x16x32_bf16 v[100:103], v[140:143], v[180:183], v[100:103]
	v_mfma_f32_16x16x32_bf16 v[96:99], v[152:155], v[180:183], v[96:99]
	v_mfma_f32_16x16x32_bf16 v[84:87], v[140:143], v[200:203], v[84:87]
	v_mfma_f32_16x16x32_bf16 v[80:83], v[152:155], v[200:203], v[80:83]
	v_mfma_f32_16x16x32_bf16 v[132:135], v[148:151], v[164:167], v[132:135]
	v_mfma_f32_16x16x32_bf16 v[128:131], v[156:159], v[164:167], v[128:131]
	v_mfma_f32_16x16x32_bf16 v[116:119], v[148:151], v[176:179], v[116:119]
	v_mfma_f32_16x16x32_bf16 v[112:115], v[156:159], v[176:179], v[112:115]
	v_mfma_f32_16x16x32_bf16 v[100:103], v[148:151], v[196:199], v[100:103]
	v_mfma_f32_16x16x32_bf16 v[96:99], v[156:159], v[196:199], v[96:99]
	v_mfma_f32_16x16x32_bf16 v[84:87], v[148:151], v[204:207], v[84:87]
	v_mfma_f32_16x16x32_bf16 v[80:83], v[156:159], v[204:207], v[80:83]
	s_barrier
	s_add_i32 s5, 0, 0x1c000
	s_add_i32 s4, s4, s26
	v_add_u32_e32 v0, s5, v145
	s_mov_b32 m0, s4
	ds_read_b128 v[208:211], v0
	ds_read_b128 v[212:215], v0 offset:1024
	ds_read_b128 v[216:219], v0 offset:2048
	ds_read_b128 v[220:223], v0 offset:3072
	s_add_u32 vcc_lo, s42, s46
	s_addc_u32 vcc_hi, s43, s47
	global_load_lds_dwordx4 v136, vcc
	s_add_i32 m0, s4, 0x2000
	s_nop 0
	s_add_u32 vcc_lo, s42, s58
	s_addc_u32 vcc_hi, s43, s59
	global_load_lds_dwordx4 v136, vcc
	s_barrier
; #define G_STAGE(bufoff, gbase, o0, h64) do { \
;         __builtin_amdgcn_global_load_lds((const unsigned*)((const char*)(gbase) + (o0)), (LAS unsigned*)(lds + (bufoff) + ldsw), 16, 0, 0); \
;         __builtin_amdgcn_global_load_lds((const unsigned*)((const char*)(gbase) + (h64) + (o0)), (LAS unsigned*)(lds + (bufoff) + ldsw + 8192), 16, 0, 0); } while (0)
; #define G_LDA(dst, b, h) do { _Pragma("unroll") for (int m = 0; m < 4; ++m) _Pragma("unroll") for (int k = 0; k < 2; ++k) dst[m][k] = *(const LAS bf16x8*)(lds + G_SA(b, h) + aoff + m * 2048 + k * 1024); } while (0)
; #define G_LDB(dst, b, h) do { _Pragma("unroll") for (int n = 0; n < 2; ++n) _Pragma("unroll") for (int k = 0; k < 2; ++k) dst[n][k] = *(const LAS bf16x8*)(lds + G_SB(b, h) + boff + n * 2048 + k * 1024); } while (0)
; #define G_WAIT_V(n) asm volatile("s_waitcnt vmcnt(" #n ")" ::: "memory")
; #define G_BAR __builtin_amdgcn_s_barrier()
;     ...
;         for (int t = 0; t < nt; t += 2) {
;             const bool last = (t == nt - 2);
;             const char* a1 = cA + (size_t)(t + 1) * ckA;
;             const char* a2 = last ? nA : cA + (size_t)(t + 2) * ckA; const char* b2 = last ? nB : cB + (size_t)(t + 2) * kB;
;             const char* a3 = a2 + ckA; const char* b3 = b2 + kB;
;             G_LDB(B0, 0, 0); G_SCHED; G_LDA(At, 0, 0); G_STAGE(G_SA(1, 1), a1 + chA, cA0, qA);
;             G_WAIT_L(8); G_BAR; G_WAIT_L(0); G_MMA(0, 0, At, B0); G_BAR; G_SCHED;
;             G_LDB(B1, 0, 1); G_STAGE(G_SB(0, 0), b2, cB0, qB);
;             G_BAR; G_WAIT_L(0); G_MMA(0, 1, At, B1); G_BAR;
;             G_LDA(At, 0, 1); G_STAGE(G_SA(0, 0), a2, cA0, qA);
;             G_BAR; G_WAIT_L(0); G_MMA(1, 0, At, B0); G_BAR; G_SCHED;
;             G_STAGE(G_SB(0, 1), b2 + chB, cB0, qB);
;             G_WAIT_V(6); G_BAR; G_MMA(1, 1, At, B1); G_BAR;
;             G_LDB(B0, 1, 0); G_SCHED; G_LDA(At, 1, 0); G_STAGE(G_SA(0, 1), a2 + chA, cA0, qA);
;             G_WAIT_L(8); G_BAR; G_WAIT_L(0); G_MMA(0, 0, At, B0); G_BAR; G_SCHED;
;             G_LDB(B1, 1, 1); G_STAGE(G_SB(1, 0), b3, cB0, qB);
;             G_BAR; G_WAIT_L(0); G_MMA(0, 1, At, B1); G_BAR;
;             G_LDA(At, 1, 1); G_STAGE(G_SA(1, 0), a3, cA0, qA);
;             G_BAR; G_WAIT_L(0); G_MMA(1, 0, At, B0); G_BAR; G_SCHED;
;             G_STAGE(G_SB(1, 1), b3 + chB, cB0, qB);
;             G_WAIT_V(6); G_BAR; G_MMA(1, 1, At, B1); G_BAR;
	s_waitcnt lgkmcnt(0)
	v_mfma_f32_16x16x32_bf16 v[124:127], v[208:211], v[160:163], v[124:127]
	v_mfma_f32_16x16x32_bf16 v[120:123], v[216:219], v[160:163], v[120:123]
	v_mfma_f32_16x16x32_bf16 v[108:111], v[208:211], v[172:175], v[108:111]
	v_mfma_f32_16x16x32_bf16 v[104:107], v[216:219], v[172:175], v[104:107]
	v_mfma_f32_16x16x32_bf16 v[92:95], v[208:211], v[180:183], v[92:95]
	v_mfma_f32_16x16x32_bf16 v[88:91], v[216:219], v[180:183], v[88:91]
	v_mfma_f32_16x16x32_bf16 v[76:79], v[208:211], v[200:203], v[76:79]
	v_mfma_f32_16x16x32_bf16 v[72:75], v[216:219], v[200:203], v[72:75]
	v_mfma_f32_16x16x32_bf16 v[124:127], v[212:215], v[164:167], v[124:127]
	v_mfma_f32_16x16x32_bf16 v[120:123], v[220:223], v[164:167], v[120:123]
	v_mfma_f32_16x16x32_bf16 v[108:111], v[212:215], v[176:179], v[108:111]
	v_mfma_f32_16x16x32_bf16 v[104:107], v[220:223], v[176:179], v[104:107]
	v_mfma_f32_16x16x32_bf16 v[92:95], v[212:215], v[196:199], v[92:95]
	v_mfma_f32_16x16x32_bf16 v[88:91], v[220:223], v[196:199], v[88:91]
	v_mfma_f32_16x16x32_bf16 v[76:79], v[212:215], v[204:207], v[76:79]
	v_mfma_f32_16x16x32_bf16 v[72:75], v[220:223], v[204:207], v[72:75]
	s_barrier
	s_mov_b32 m0, s31
	ds_read_b128 v[160:163], v146 offset:49152
	ds_read_b128 v[164:167], v146 offset:50176
	ds_read_b128 v[172:175], v146 offset:51200
	ds_read_b128 v[176:179], v146 offset:52224
	ds_read_b128 v[180:183], v146 offset:53248
	ds_read_b128 v[196:199], v146 offset:54272
	ds_read_b128 v[200:203], v146 offset:55296
	ds_read_b128 v[204:207], v146 offset:56320
	s_add_u32 vcc_lo, s22, s46
	s_addc_u32 vcc_hi, s23, s47
	global_load_lds_dwordx4 v2, vcc
	s_mov_b32 m0, s33
	s_nop 0
	s_add_u32 vcc_lo, s22, s58
	s_addc_u32 vcc_hi, s23, s59
	global_load_lds_dwordx4 v2, vcc
	s_barrier
	s_waitcnt lgkmcnt(0)
	v_mfma_f32_16x16x32_bf16 v[68:71], v[140:143], v[160:163], v[68:71]
	v_mfma_f32_16x16x32_bf16 v[64:67], v[152:155], v[160:163], v[64:67]
	v_mfma_f32_16x16x32_bf16 v[52:55], v[140:143], v[172:175], v[52:55]
	v_mfma_f32_16x16x32_bf16 v[48:51], v[152:155], v[172:175], v[48:51]
	v_mfma_f32_16x16x32_bf16 v[36:39], v[140:143], v[180:183], v[36:39]
	v_mfma_f32_16x16x32_bf16 v[32:35], v[152:155], v[180:183], v[32:35]
	v_mfma_f32_16x16x32_bf16 v[20:23], v[140:143], v[200:203], v[20:23]
	v_mfma_f32_16x16x32_bf16 v[16:19], v[152:155], v[200:203], v[16:19]
	v_mfma_f32_16x16x32_bf16 v[68:71], v[148:151], v[164:167], v[68:71]
	v_mfma_f32_16x16x32_bf16 v[64:67], v[156:159], v[164:167], v[64:67]
	v_mfma_f32_16x16x32_bf16 v[52:55], v[148:151], v[176:179], v[52:55]
	v_mfma_f32_16x16x32_bf16 v[48:51], v[156:159], v[176:179], v[48:51]
	v_mfma_f32_16x16x32_bf16 v[36:39], v[148:151], v[196:199], v[36:39]
	v_mfma_f32_16x16x32_bf16 v[32:35], v[156:159], v[196:199], v[32:35]
	v_mfma_f32_16x16x32_bf16 v[20:23], v[148:151], v[204:207], v[20:23]
	v_mfma_f32_16x16x32_bf16 v[16:19], v[156:159], v[204:207], v[16:19]
	s_barrier
	s_add_i32 s4, s5, s26
	s_mov_b32 m0, s4
	s_nop 0
	s_add_u32 vcc_lo, s42, s50
	s_addc_u32 vcc_hi, s43, s51
	global_load_lds_dwordx4 v136, vcc
	s_add_i32 m0, s4, 0x2000
	s_nop 0
	s_add_u32 vcc_lo, s42, s62
	s_addc_u32 vcc_hi, s43, s63
	global_load_lds_dwordx4 v136, vcc
	s_add_i32 s21, s21, 2
	s_add_u32 s6, s6, 0x100
	s_addc_u32 s7, s7, 0
	s_add_u32 s19, s19, 0x100
	s_addc_u32 s20, s20, 0
	s_cmp_gt_u32 s21, 5
	s_waitcnt vmcnt(6)
	s_barrier
	v_mfma_f32_16x16x32_bf16 v[60:63], v[208:211], v[160:163], v[60:63]
	v_mfma_f32_16x16x32_bf16 v[56:59], v[216:219], v[160:163], v[56:59]
	v_mfma_f32_16x16x32_bf16 v[44:47], v[208:211], v[172:175], v[44:47]
	v_mfma_f32_16x16x32_bf16 v[40:43], v[216:219], v[172:175], v[40:43]
	v_mfma_f32_16x16x32_bf16 v[28:31], v[208:211], v[180:183], v[28:31]
	v_mfma_f32_16x16x32_bf16 v[24:27], v[216:219], v[180:183], v[24:27]
	v_mfma_f32_16x16x32_bf16 v[12:15], v[208:211], v[200:203], v[12:15]
	v_mfma_f32_16x16x32_bf16 v[8:11], v[216:219], v[200:203], v[8:11]
	v_mfma_f32_16x16x32_bf16 v[60:63], v[212:215], v[164:167], v[60:63]
	v_mfma_f32_16x16x32_bf16 v[56:59], v[220:223], v[164:167], v[56:59]
	v_mfma_f32_16x16x32_bf16 v[44:47], v[212:215], v[176:179], v[44:47]
	v_mfma_f32_16x16x32_bf16 v[40:43], v[220:223], v[176:179], v[40:43]
	v_mfma_f32_16x16x32_bf16 v[28:31], v[212:215], v[196:199], v[28:31]
	v_mfma_f32_16x16x32_bf16 v[24:27], v[220:223], v[196:199], v[24:27]
	v_mfma_f32_16x16x32_bf16 v[12:15], v[212:215], v[204:207], v[12:15]
	v_mfma_f32_16x16x32_bf16 v[8:11], v[220:223], v[204:207], v[8:11]
	s_cbranch_scc0 .Ldb_SSM1_cont
	v_readfirstlane_b32 s101, v186
	s_cmpk_gt_u32 s101, 0xff
	s_cbranch_scc1 .Ldb_SSM1_young
	s_barrier
	s_mov_b32 s101, 1
	s_branch .Ldb_SSM1_exit

; #define G_STAGE(bufoff, gbase, o0, h64) do { \
;         __builtin_amdgcn_global_load_lds((const unsigned*)((const char*)(gbase) + (o0)), (LAS unsigned*)(lds + (bufoff) + ldsw), 16, 0, 0); \
;         __builtin_amdgcn_global_load_lds((const unsigned*)((const char*)(gbase) + (h64) + (o0)), (LAS unsigned*)(lds + (bufoff) + ldsw + 8192), 16, 0, 0); } while (0)
; #define G_LDA(dst, b, h) do { _Pragma("unroll") for (int m = 0; m < 4; ++m) _Pragma("unroll") for (int k = 0; k < 2; ++k) dst[m][k] = *(const LAS bf16x8*)(lds + G_SA(b, h) + aoff + m * 2048 + k * 1024); } while (0)
; #define G_LDB(dst, b, h) do { _Pragma("unroll") for (int n = 0; n < 2; ++n) _Pragma("unroll") for (int k = 0; k < 2; ++k) dst[n][k] = *(const LAS bf16x8*)(lds + G_SB(b, h) + boff + n * 2048 + k * 1024); } while (0)
; #define G_WAIT_V(n) asm volatile("s_waitcnt vmcnt(" #n ")" ::: "memory")
; #define G_BAR __builtin_amdgcn_s_barrier()
;     ...
;         for (int t = 0; t < nt; t += 2) {
;             const bool last = (t == nt - 2);
;             const char* a1 = cA + (size_t)(t + 1) * ckA;
;             const char* a2 = last ? nA : cA + (size_t)(t + 2) * ckA; const char* b2 = last ? nB : cB + (size_t)(t + 2) * kB;
;             const char* a3 = a2 + ckA; const char* b3 = b2 + kB;
;             G_LDB(B0, 0, 0); G_SCHED; G_LDA(At, 0, 0); G_STAGE(G_SA(1, 1), a1 + chA, cA0, qA);
;             G_WAIT_L(8); G_BAR; G_WAIT_L(0); G_MMA(0, 0, At, B0); G_BAR; G_SCHED;
;             G_LDB(B1, 0, 1); G_STAGE(G_SB(0, 0), b2, cB0, qB);
;             G_BAR; G_WAIT_L(0); G_MMA(0, 1, At, B1); G_BAR;
;             G_LDA(At, 0, 1); G_STAGE(G_SA(0, 0), a2, cA0, qA);
;             G_BAR; G_WAIT_L(0); G_MMA(1, 0, At, B0); G_BAR; G_SCHED;
;             G_STAGE(G_SB(0, 1), b2 + chB, cB0, qB);
;             G_WAIT_V(6); G_BAR; G_MMA(1, 1, At, B1); G_BAR;
;             G_LDB(B0, 1, 0); G_SCHED; G_LDA(At, 1, 0); G_STAGE(G_SA(0, 1), a2 + chA, cA0, qA);
;             G_WAIT_L(8); G_BAR; G_WAIT_L(0); G_MMA(0, 0, At, B0); G_BAR; G_SCHED;
;             G_LDB(B1, 1, 1); G_STAGE(G_SB(1, 0), b3, cB0, qB);
;             G_BAR; G_WAIT_L(0); G_MMA(0, 1, At, B1); G_BAR;
;             G_LDA(At, 1, 1); G_STAGE(G_SA(1, 0), a3, cA0, qA);
;             G_BAR; G_WAIT_L(0); G_MMA(1, 0, At, B0); G_BAR; G_SCHED;
;             G_STAGE(G_SB(1, 1), b3 + chB, cB0, qB);
;             G_WAIT_V(6); G_BAR; G_MMA(1, 1, At, B1); G_BAR;
.LBB0_742:
	s_add_u32 s36, s2, s30
	s_addc_u32 s37, s3, s31
	s_add_u32 s19, s36, 0x100
	s_addc_u32 s35, s37, 0
	s_and_b64 s[4:5], s[26:27], exec
	s_cselect_b32 s34, s12, s19
	s_cselect_b32 s35, s13, s35
	s_add_u32 s4, s20, s30
	s_addc_u32 s5, s21, s31
	s_add_u32 s19, s4, 0x100
	s_addc_u32 s30, s5, 0
	s_add_i32 s44, 0, 0x10000
	v_add_u32_e32 v0, s44, v183
	ds_read_b128 v[56:59], v0
	ds_read_b128 v[60:63], v0 offset:1024
	ds_read_b128 v[144:147], v0 offset:2048
	ds_read_b128 v[148:151], v0 offset:3072
	s_and_b64 s[4:5], s[26:27], exec
	s_cselect_b32 s26, s16, s19
	s_cselect_b32 s27, s17, s30
	s_add_i32 s48, 0, 0x14000
	s_add_i32 s31, 0, 0x18000
	s_add_i32 s19, 0, 0x1c000
	s_add_i32 s49, s44, s38
	s_add_i32 s63, s48, s38
	s_add_i32 s30, s31, s38
	s_add_i32 s65, s19, s38
	s_add_i32 m0, s43, 0xc000
	s_add_i32 s45, s43, 0xe000
	s_add_i32 s66, s49, 0x2000
	s_add_i32 s62, s63, 0x2000
	s_add_i32 s67, s30, 0x2000
	s_add_i32 s64, s65, 0x2000
	s_mov_b64 s[4:5], 0x200080
	s_add_u32 vcc_lo, s36, s4
	s_addc_u32 vcc_hi, s37, s5
	s_mov_b64 s[4:5], 0x300080
	ds_read_b128 v[152:155], v184
	ds_read_b128 v[156:159], v184 offset:1024
	ds_read_b128 v[162:165], v184 offset:2048
	ds_read_b128 v[172:175], v184 offset:3072
	ds_read_b128 v[176:179], v184 offset:4096
	ds_read_b128 v[196:199], v184 offset:5120
	ds_read_b128 v[200:203], v184 offset:6144
	ds_read_b128 v[204:207], v184 offset:7168
	global_load_lds_dwordx4 v160, vcc
	s_mov_b32 m0, s45
	s_nop 0
	s_add_u32 vcc_lo, s36, s4
	s_addc_u32 vcc_hi, s37, s5
	global_load_lds_dwordx4 v160, vcc
	s_waitcnt lgkmcnt(8)
	s_cmp_eq_u32 s101, 1
	s_cbranch_scc1 .Ldb_SSM2_sk
	s_barrier
.Ldb_SSM2_sk:
	s_mov_b32 s101, 0
	s_waitcnt lgkmcnt(0)
	v_mfma_f32_16x16x32_bf16 v[140:143], v[56:59], v[152:155], v[140:143]
	v_mfma_f32_16x16x32_bf16 v[136:139], v[144:147], v[152:155], v[136:139]
	v_mfma_f32_16x16x32_bf16 v[124:127], v[56:59], v[162:165], v[124:127]
	v_mfma_f32_16x16x32_bf16 v[120:123], v[144:147], v[162:165], v[120:123]
	v_mfma_f32_16x16x32_bf16 v[108:111], v[56:59], v[176:179], v[108:111]
	v_mfma_f32_16x16x32_bf16 v[104:107], v[144:147], v[176:179], v[104:107]
	v_mfma_f32_16x16x32_bf16 v[92:95], v[56:59], v[200:203], v[92:95]
	v_mfma_f32_16x16x32_bf16 v[88:91], v[144:147], v[200:203], v[88:91]
	v_mfma_f32_16x16x32_bf16 v[140:143], v[60:63], v[156:159], v[140:143]
	v_mfma_f32_16x16x32_bf16 v[136:139], v[148:151], v[156:159], v[136:139]
	v_mfma_f32_16x16x32_bf16 v[124:127], v[60:63], v[172:175], v[124:127]
	v_mfma_f32_16x16x32_bf16 v[120:123], v[148:151], v[172:175], v[120:123]
	v_mfma_f32_16x16x32_bf16 v[108:111], v[60:63], v[196:199], v[108:111]
	v_mfma_f32_16x16x32_bf16 v[104:107], v[148:151], v[196:199], v[104:107]
	v_mfma_f32_16x16x32_bf16 v[92:95], v[60:63], v[204:207], v[92:95]
	v_mfma_f32_16x16x32_bf16 v[88:91], v[148:151], v[204:207], v[88:91]
	s_barrier
	s_mov_b32 m0, s49
	v_add_u32_e32 v0, s48, v183
	ds_read_b128 v[208:211], v0
	ds_read_b128 v[212:215], v0 offset:1024
	ds_read_b128 v[216:219], v0 offset:2048
	ds_read_b128 v[220:223], v0 offset:3072
	global_load_lds_dwordx4 v2, s[26:27]
	s_mov_b32 m0, s66
	s_nop 0
	s_add_u32 vcc_lo, s26, s92
	s_addc_u32 vcc_hi, s27, s93
	global_load_lds_dwordx4 v2, vcc
	s_barrier
	s_waitcnt lgkmcnt(0)
	v_mfma_f32_16x16x32_bf16 v[132:135], v[208:211], v[152:155], v[132:135]
	v_mfma_f32_16x16x32_bf16 v[128:131], v[216:219], v[152:155], v[128:131]
	v_mfma_f32_16x16x32_bf16 v[116:119], v[208:211], v[162:165], v[116:119]
	v_mfma_f32_16x16x32_bf16 v[112:115], v[216:219], v[162:165], v[112:115]
	v_mfma_f32_16x16x32_bf16 v[100:103], v[208:211], v[176:179], v[100:103]
	v_mfma_f32_16x16x32_bf16 v[96:99], v[216:219], v[176:179], v[96:99]
	v_mfma_f32_16x16x32_bf16 v[84:87], v[208:211], v[200:203], v[84:87]
	v_mfma_f32_16x16x32_bf16 v[80:83], v[216:219], v[200:203], v[80:83]
	v_mfma_f32_16x16x32_bf16 v[132:135], v[212:215], v[156:159], v[132:135]
	v_mfma_f32_16x16x32_bf16 v[128:131], v[220:223], v[156:159], v[128:131]
	v_mfma_f32_16x16x32_bf16 v[116:119], v[212:215], v[172:175], v[116:119]
	v_mfma_f32_16x16x32_bf16 v[112:115], v[220:223], v[172:175], v[112:115]
	v_mfma_f32_16x16x32_bf16 v[100:103], v[212:215], v[196:199], v[100:103]
	v_mfma_f32_16x16x32_bf16 v[96:99], v[220:223], v[196:199], v[96:99]
	v_mfma_f32_16x16x32_bf16 v[84:87], v[212:215], v[204:207], v[84:87]
	v_mfma_f32_16x16x32_bf16 v[80:83], v[220:223], v[204:207], v[80:83]
	s_barrier
	s_mov_b32 m0, s43
	ds_read_b128 v[152:155], v184 offset:16384
	ds_read_b128 v[156:159], v184 offset:17408
	ds_read_b128 v[162:165], v184 offset:18432
	ds_read_b128 v[172:175], v184 offset:19456
	ds_read_b128 v[176:179], v184 offset:20480
	ds_read_b128 v[196:199], v184 offset:21504
	ds_read_b128 v[200:203], v184 offset:22528
	ds_read_b128 v[204:207], v184 offset:23552
	global_load_lds_dwordx4 v160, s[34:35]
	s_mov_b32 m0, s50
	s_nop 0
	s_add_u32 vcc_lo, s34, s88
	s_addc_u32 vcc_hi, s35, s89
	global_load_lds_dwordx4 v160, vcc
	s_barrier
	s_waitcnt lgkmcnt(0)
	v_mfma_f32_16x16x32_bf16 v[76:79], v[56:59], v[152:155], v[76:79]
	v_mfma_f32_16x16x32_bf16 v[72:75], v[144:147], v[152:155], v[72:75]
	v_mfma_f32_16x16x32_bf16 v[52:55], v[56:59], v[162:165], v[52:55]
	v_mfma_f32_16x16x32_bf16 v[48:51], v[144:147], v[162:165], v[48:51]
	v_mfma_f32_16x16x32_bf16 v[36:39], v[56:59], v[176:179], v[36:39]
	v_mfma_f32_16x16x32_bf16 v[32:35], v[144:147], v[176:179], v[32:35]
	v_mfma_f32_16x16x32_bf16 v[20:23], v[56:59], v[200:203], v[20:23]
	v_mfma_f32_16x16x32_bf16 v[16:19], v[144:147], v[200:203], v[16:19]
	v_mfma_f32_16x16x32_bf16 v[76:79], v[60:63], v[156:159], v[76:79]
	v_mfma_f32_16x16x32_bf16 v[72:75], v[148:151], v[156:159], v[72:75]
	v_mfma_f32_16x16x32_bf16 v[52:55], v[60:63], v[172:175], v[52:55]
	v_mfma_f32_16x16x32_bf16 v[48:51], v[148:151], v[172:175], v[48:51]
	v_mfma_f32_16x16x32_bf16 v[36:39], v[60:63], v[196:199], v[36:39]
	v_mfma_f32_16x16x32_bf16 v[32:35], v[148:151], v[196:199], v[32:35]
	v_mfma_f32_16x16x32_bf16 v[20:23], v[60:63], v[204:207], v[20:23]
	v_mfma_f32_16x16x32_bf16 v[16:19], v[148:151], v[204:207], v[16:19]
	s_barrier
; #define G_STAGE(bufoff, gbase, o0, h64) do { \
;         __builtin_amdgcn_global_load_lds((const unsigned*)((const char*)(gbase) + (o0)), (LAS unsigned*)(lds + (bufoff) + ldsw), 16, 0, 0); \
;         __builtin_amdgcn_global_load_lds((const unsigned*)((const char*)(gbase) + (h64) + (o0)), (LAS unsigned*)(lds + (bufoff) + ldsw + 8192), 16, 0, 0); } while (0)
; #define G_LDA(dst, b, h) do { _Pragma("unroll") for (int m = 0; m < 4; ++m) _Pragma("unroll") for (int k = 0; k < 2; ++k) dst[m][k] = *(const LAS bf16x8*)(lds + G_SA(b, h) + aoff + m * 2048 + k * 1024); } while (0)
; #define G_LDB(dst, b, h) do { _Pragma("unroll") for (int n = 0; n < 2; ++n) _Pragma("unroll") for (int k = 0; k < 2; ++k) dst[n][k] = *(const LAS bf16x8*)(lds + G_SB(b, h) + boff + n * 2048 + k * 1024); } while (0)
; #define G_WAIT_V(n) asm volatile("s_waitcnt vmcnt(" #n ")" ::: "memory")
; #define G_BAR __builtin_amdgcn_s_barrier()
;     ...
;         for (int t = 0; t < nt; t += 2) {
;             const bool last = (t == nt - 2);
;             const char* a1 = cA + (size_t)(t + 1) * ckA;
;             const char* a2 = last ? nA : cA + (size_t)(t + 2) * ckA; const char* b2 = last ? nB : cB + (size_t)(t + 2) * kB;
;             const char* a3 = a2 + ckA; const char* b3 = b2 + kB;
;             G_LDB(B0, 0, 0); G_SCHED; G_LDA(At, 0, 0); G_STAGE(G_SA(1, 1), a1 + chA, cA0, qA);
;             G_WAIT_L(8); G_BAR; G_WAIT_L(0); G_MMA(0, 0, At, B0); G_BAR; G_SCHED;
;             G_LDB(B1, 0, 1); G_STAGE(G_SB(0, 0), b2, cB0, qB);
;             G_BAR; G_WAIT_L(0); G_MMA(0, 1, At, B1); G_BAR;
;             G_LDA(At, 0, 1); G_STAGE(G_SA(0, 0), a2, cA0, qA);
;             G_BAR; G_WAIT_L(0); G_MMA(1, 0, At, B0); G_BAR; G_SCHED;
;             G_STAGE(G_SB(0, 1), b2 + chB, cB0, qB);
;             G_WAIT_V(6); G_BAR; G_MMA(1, 1, At, B1); G_BAR;
;             G_LDB(B0, 1, 0); G_SCHED; G_LDA(At, 1, 0); G_STAGE(G_SA(0, 1), a2 + chA, cA0, qA);
;             G_WAIT_L(8); G_BAR; G_WAIT_L(0); G_MMA(0, 0, At, B0); G_BAR; G_SCHED;
;             G_LDB(B1, 1, 1); G_STAGE(G_SB(1, 0), b3, cB0, qB);
;             G_BAR; G_WAIT_L(0); G_MMA(0, 1, At, B1); G_BAR;
;             G_LDA(At, 1, 1); G_STAGE(G_SA(1, 0), a3, cA0, qA);
;             G_BAR; G_WAIT_L(0); G_MMA(1, 0, At, B0); G_BAR; G_SCHED;
;             G_STAGE(G_SB(1, 1), b3 + chB, cB0, qB);
;             G_WAIT_V(6); G_BAR; G_MMA(1, 1, At, B1); G_BAR;
	s_mov_b32 m0, s63
	s_add_u32 vcc_lo, s26, s82
	s_addc_u32 vcc_hi, s27, s83
	global_load_lds_dwordx4 v2, vcc
	s_mov_b32 m0, s62
	s_nop 0
	s_add_u32 vcc_lo, s26, s94
	s_addc_u32 vcc_hi, s27, s95
	global_load_lds_dwordx4 v2, vcc
	s_waitcnt vmcnt(6)
	s_barrier
	v_mfma_f32_16x16x32_bf16 v[44:47], v[208:211], v[162:165], v[44:47]
	v_mfma_f32_16x16x32_bf16 v[40:43], v[216:219], v[162:165], v[40:43]
	v_mfma_f32_16x16x32_bf16 v[28:31], v[208:211], v[176:179], v[28:31]
	v_mfma_f32_16x16x32_bf16 v[24:27], v[216:219], v[176:179], v[24:27]
	v_mfma_f32_16x16x32_bf16 v[12:15], v[208:211], v[200:203], v[12:15]
	v_mfma_f32_16x16x32_bf16 v[8:11], v[216:219], v[200:203], v[8:11]
	v_mfma_f32_16x16x32_bf16 v[56:59], v[208:211], v[152:155], v[68:71]
	v_mfma_f32_16x16x32_bf16 v[60:63], v[216:219], v[152:155], v[64:67]
	v_mfma_f32_16x16x32_bf16 v[44:47], v[212:215], v[172:175], v[44:47]
	v_mfma_f32_16x16x32_bf16 v[40:43], v[220:223], v[172:175], v[40:43]
	v_mfma_f32_16x16x32_bf16 v[28:31], v[212:215], v[196:199], v[28:31]
	v_mfma_f32_16x16x32_bf16 v[24:27], v[220:223], v[196:199], v[24:27]
	v_mfma_f32_16x16x32_bf16 v[12:15], v[212:215], v[204:207], v[12:15]
	v_mfma_f32_16x16x32_bf16 v[8:11], v[220:223], v[204:207], v[8:11]
	v_mfma_f32_16x16x32_bf16 v[56:59], v[212:215], v[156:159], v[56:59]
	v_mfma_f32_16x16x32_bf16 v[60:63], v[220:223], v[156:159], v[60:63]
	s_barrier
	v_add_u32_e32 v0, s31, v183
	ds_read_b128 v[64:67], v0
	ds_read_b128 v[68:71], v0 offset:1024
	ds_read_b128 v[144:147], v0 offset:2048
	ds_read_b128 v[148:151], v0 offset:3072
	s_mov_b32 m0, s51
	ds_read_b128 v[152:155], v184 offset:32768
	ds_read_b128 v[156:159], v184 offset:33792
	ds_read_b128 v[162:165], v184 offset:34816
	ds_read_b128 v[172:175], v184 offset:35840
	ds_read_b128 v[176:179], v184 offset:36864
	ds_read_b128 v[196:199], v184 offset:37888
	ds_read_b128 v[200:203], v184 offset:38912
	ds_read_b128 v[204:207], v184 offset:39936
	s_add_u32 vcc_lo, s34, s86
	s_addc_u32 vcc_hi, s35, s87
	global_load_lds_dwordx4 v160, vcc
	s_mov_b32 m0, s52
	s_nop 0
	s_add_u32 vcc_lo, s34, s96
	s_addc_u32 vcc_hi, s35, s97
	global_load_lds_dwordx4 v160, vcc
	s_waitcnt lgkmcnt(8)
	s_barrier
	s_waitcnt lgkmcnt(0)
	v_mfma_f32_16x16x32_bf16 v[140:143], v[64:67], v[152:155], v[140:143]
	v_mfma_f32_16x16x32_bf16 v[136:139], v[144:147], v[152:155], v[136:139]
	v_mfma_f32_16x16x32_bf16 v[124:127], v[64:67], v[162:165], v[124:127]
	v_mfma_f32_16x16x32_bf16 v[120:123], v[144:147], v[162:165], v[120:123]
	v_mfma_f32_16x16x32_bf16 v[108:111], v[64:67], v[176:179], v[108:111]
	v_mfma_f32_16x16x32_bf16 v[104:107], v[144:147], v[176:179], v[104:107]
	v_mfma_f32_16x16x32_bf16 v[92:95], v[64:67], v[200:203], v[92:95]
	v_mfma_f32_16x16x32_bf16 v[88:91], v[144:147], v[200:203], v[88:91]
	v_mfma_f32_16x16x32_bf16 v[140:143], v[68:71], v[156:159], v[140:143]
	v_mfma_f32_16x16x32_bf16 v[136:139], v[148:151], v[156:159], v[136:139]
	v_mfma_f32_16x16x32_bf16 v[124:127], v[68:71], v[172:175], v[124:127]
	v_mfma_f32_16x16x32_bf16 v[120:123], v[148:151], v[172:175], v[120:123]
	v_mfma_f32_16x16x32_bf16 v[108:111], v[68:71], v[196:199], v[108:111]
	v_mfma_f32_16x16x32_bf16 v[104:107], v[148:151], v[196:199], v[104:107]
	v_mfma_f32_16x16x32_bf16 v[92:95], v[68:71], v[204:207], v[92:95]
	v_mfma_f32_16x16x32_bf16 v[88:91], v[148:151], v[204:207], v[88:91]
	s_barrier
	s_mov_b32 m0, s30
	v_add_u32_e32 v0, s19, v183
	ds_read_b128 v[208:211], v0
	ds_read_b128 v[212:215], v0 offset:1024
	ds_read_b128 v[216:219], v0 offset:2048
	ds_read_b128 v[220:223], v0 offset:3072
	s_add_u32 vcc_lo, s26, s46
	s_addc_u32 vcc_hi, s27, s47
	global_load_lds_dwordx4 v2, vcc
	s_mov_b32 m0, s67
	s_nop 0
	s_add_u32 vcc_lo, s26, s70
	s_addc_u32 vcc_hi, s27, s71
	global_load_lds_dwordx4 v2, vcc
	s_barrier
; #define G_STAGE(bufoff, gbase, o0, h64) do { \
;         __builtin_amdgcn_global_load_lds((const unsigned*)((const char*)(gbase) + (o0)), (LAS unsigned*)(lds + (bufoff) + ldsw), 16, 0, 0); \
;         __builtin_amdgcn_global_load_lds((const unsigned*)((const char*)(gbase) + (h64) + (o0)), (LAS unsigned*)(lds + (bufoff) + ldsw + 8192), 16, 0, 0); } while (0)
; #define G_LDA(dst, b, h) do { _Pragma("unroll") for (int m = 0; m < 4; ++m) _Pragma("unroll") for (int k = 0; k < 2; ++k) dst[m][k] = *(const LAS bf16x8*)(lds + G_SA(b, h) + aoff + m * 2048 + k * 1024); } while (0)
; #define G_LDB(dst, b, h) do { _Pragma("unroll") for (int n = 0; n < 2; ++n) _Pragma("unroll") for (int k = 0; k < 2; ++k) dst[n][k] = *(const LAS bf16x8*)(lds + G_SB(b, h) + boff + n * 2048 + k * 1024); } while (0)
; #define G_WAIT_V(n) asm volatile("s_waitcnt vmcnt(" #n ")" ::: "memory")
; #define G_BAR __builtin_amdgcn_s_barrier()
;     ...
;         for (int t = 0; t < nt; t += 2) {
;             const bool last = (t == nt - 2);
;             const char* a1 = cA + (size_t)(t + 1) * ckA;
;             const char* a2 = last ? nA : cA + (size_t)(t + 2) * ckA; const char* b2 = last ? nB : cB + (size_t)(t + 2) * kB;
;             const char* a3 = a2 + ckA; const char* b3 = b2 + kB;
;             G_LDB(B0, 0, 0); G_SCHED; G_LDA(At, 0, 0); G_STAGE(G_SA(1, 1), a1 + chA, cA0, qA);
;             G_WAIT_L(8); G_BAR; G_WAIT_L(0); G_MMA(0, 0, At, B0); G_BAR; G_SCHED;
;             G_LDB(B1, 0, 1); G_STAGE(G_SB(0, 0), b2, cB0, qB);
;             G_BAR; G_WAIT_L(0); G_MMA(0, 1, At, B1); G_BAR;
;             G_LDA(At, 0, 1); G_STAGE(G_SA(0, 0), a2, cA0, qA);
;             G_BAR; G_WAIT_L(0); G_MMA(1, 0, At, B0); G_BAR; G_SCHED;
;             G_STAGE(G_SB(0, 1), b2 + chB, cB0, qB);
;             G_WAIT_V(6); G_BAR; G_MMA(1, 1, At, B1); G_BAR;
;             G_LDB(B0, 1, 0); G_SCHED; G_LDA(At, 1, 0); G_STAGE(G_SA(0, 1), a2 + chA, cA0, qA);
;             G_WAIT_L(8); G_BAR; G_WAIT_L(0); G_MMA(0, 0, At, B0); G_BAR; G_SCHED;
;             G_LDB(B1, 1, 1); G_STAGE(G_SB(1, 0), b3, cB0, qB);
;             G_BAR; G_WAIT_L(0); G_MMA(0, 1, At, B1); G_BAR;
;             G_LDA(At, 1, 1); G_STAGE(G_SA(1, 0), a3, cA0, qA);
;             G_BAR; G_WAIT_L(0); G_MMA(1, 0, At, B0); G_BAR; G_SCHED;
;             G_STAGE(G_SB(1, 1), b3 + chB, cB0, qB);
;             G_WAIT_V(6); G_BAR; G_MMA(1, 1, At, B1); G_BAR;
	s_waitcnt lgkmcnt(0)
	v_mfma_f32_16x16x32_bf16 v[132:135], v[208:211], v[152:155], v[132:135]
	v_mfma_f32_16x16x32_bf16 v[128:131], v[216:219], v[152:155], v[128:131]
	v_mfma_f32_16x16x32_bf16 v[116:119], v[208:211], v[162:165], v[116:119]
	v_mfma_f32_16x16x32_bf16 v[112:115], v[216:219], v[162:165], v[112:115]
	v_mfma_f32_16x16x32_bf16 v[100:103], v[208:211], v[176:179], v[100:103]
	v_mfma_f32_16x16x32_bf16 v[96:99], v[216:219], v[176:179], v[96:99]
	v_mfma_f32_16x16x32_bf16 v[84:87], v[208:211], v[200:203], v[84:87]
	v_mfma_f32_16x16x32_bf16 v[80:83], v[216:219], v[200:203], v[80:83]
	v_mfma_f32_16x16x32_bf16 v[132:135], v[212:215], v[156:159], v[132:135]
	v_mfma_f32_16x16x32_bf16 v[128:131], v[220:223], v[156:159], v[128:131]
	v_mfma_f32_16x16x32_bf16 v[116:119], v[212:215], v[172:175], v[116:119]
	v_mfma_f32_16x16x32_bf16 v[112:115], v[220:223], v[172:175], v[112:115]
	v_mfma_f32_16x16x32_bf16 v[100:103], v[212:215], v[196:199], v[100:103]
	v_mfma_f32_16x16x32_bf16 v[96:99], v[220:223], v[196:199], v[96:99]
	v_mfma_f32_16x16x32_bf16 v[84:87], v[212:215], v[204:207], v[84:87]
	v_mfma_f32_16x16x32_bf16 v[80:83], v[220:223], v[204:207], v[80:83]
	s_barrier
	s_mov_b32 m0, s53
	ds_read_b128 v[152:155], v184 offset:49152
	ds_read_b128 v[156:159], v184 offset:50176
	ds_read_b128 v[162:165], v184 offset:51200
	ds_read_b128 v[172:175], v184 offset:52224
	ds_read_b128 v[176:179], v184 offset:53248
	ds_read_b128 v[196:199], v184 offset:54272
	ds_read_b128 v[200:203], v184 offset:55296
	ds_read_b128 v[204:207], v184 offset:56320
	s_add_u32 vcc_lo, s34, s46
	s_addc_u32 vcc_hi, s35, s47
	global_load_lds_dwordx4 v160, vcc
	s_mov_b32 m0, s54
	s_nop 0
	s_add_u32 vcc_lo, s34, s68
	s_addc_u32 vcc_hi, s35, s69
	global_load_lds_dwordx4 v160, vcc
	s_barrier
	s_waitcnt lgkmcnt(0)
	v_mfma_f32_16x16x32_bf16 v[76:79], v[64:67], v[152:155], v[76:79]
	v_mfma_f32_16x16x32_bf16 v[72:75], v[144:147], v[152:155], v[72:75]
	v_mfma_f32_16x16x32_bf16 v[52:55], v[64:67], v[162:165], v[52:55]
	v_mfma_f32_16x16x32_bf16 v[48:51], v[144:147], v[162:165], v[48:51]
	v_mfma_f32_16x16x32_bf16 v[36:39], v[64:67], v[176:179], v[36:39]
	v_mfma_f32_16x16x32_bf16 v[32:35], v[144:147], v[176:179], v[32:35]
	v_mfma_f32_16x16x32_bf16 v[20:23], v[64:67], v[200:203], v[20:23]
	v_mfma_f32_16x16x32_bf16 v[16:19], v[144:147], v[200:203], v[16:19]
	v_mfma_f32_16x16x32_bf16 v[76:79], v[68:71], v[156:159], v[76:79]
	v_mfma_f32_16x16x32_bf16 v[72:75], v[148:151], v[156:159], v[72:75]
	v_mfma_f32_16x16x32_bf16 v[52:55], v[68:71], v[172:175], v[52:55]
	v_mfma_f32_16x16x32_bf16 v[48:51], v[148:151], v[172:175], v[48:51]
	v_mfma_f32_16x16x32_bf16 v[36:39], v[68:71], v[196:199], v[36:39]
	v_mfma_f32_16x16x32_bf16 v[32:35], v[148:151], v[196:199], v[32:35]
	v_mfma_f32_16x16x32_bf16 v[20:23], v[68:71], v[204:207], v[20:23]
	v_mfma_f32_16x16x32_bf16 v[16:19], v[148:151], v[204:207], v[16:19]
	s_barrier
	s_mov_b32 m0, s65
	s_add_u32 vcc_lo, s26, s84
	s_addc_u32 vcc_hi, s27, s85
	global_load_lds_dwordx4 v2, vcc
	s_mov_b32 m0, s64
	s_nop 0
	s_add_u32 vcc_lo, s26, s28
	s_addc_u32 vcc_hi, s27, s29
	global_load_lds_dwordx4 v2, vcc
	s_waitcnt vmcnt(6)
	s_barrier
	v_mfma_f32_16x16x32_bf16 v[56:59], v[208:211], v[152:155], v[56:59]
	v_mfma_f32_16x16x32_bf16 v[68:71], v[212:215], v[156:159], v[56:59]
	v_mfma_f32_16x16x32_bf16 v[56:59], v[216:219], v[152:155], v[60:63]
	v_mfma_f32_16x16x32_bf16 v[44:47], v[208:211], v[162:165], v[44:47]
	v_mfma_f32_16x16x32_bf16 v[40:43], v[216:219], v[162:165], v[40:43]
	v_mfma_f32_16x16x32_bf16 v[28:31], v[208:211], v[176:179], v[28:31]
	v_mfma_f32_16x16x32_bf16 v[24:27], v[216:219], v[176:179], v[24:27]
	v_mfma_f32_16x16x32_bf16 v[12:15], v[208:211], v[200:203], v[12:15]
	v_mfma_f32_16x16x32_bf16 v[8:11], v[216:219], v[200:203], v[8:11]
	v_mfma_f32_16x16x32_bf16 v[64:67], v[220:223], v[156:159], v[56:59]
	v_mfma_f32_16x16x32_bf16 v[44:47], v[212:215], v[172:175], v[44:47]
	v_mfma_f32_16x16x32_bf16 v[40:43], v[220:223], v[172:175], v[40:43]
	v_mfma_f32_16x16x32_bf16 v[28:31], v[212:215], v[196:199], v[28:31]
	v_mfma_f32_16x16x32_bf16 v[24:27], v[220:223], v[196:199], v[24:27]
	v_mfma_f32_16x16x32_bf16 v[12:15], v[212:215], v[204:207], v[12:15]
	v_mfma_f32_16x16x32_bf16 v[8:11], v[220:223], v[204:207], v[8:11]
	s_andn2_b64 vcc, exec, s[24:25]
	s_mov_b64 s[26:27], -1
	s_mov_b64 s[24:25], 0
	s_mov_b64 s[30:31], 0x100
	s_cbranch_vccz .Ldb_SSM2_cont
	v_readfirstlane_b32 s101, v186
	s_cmpk_gt_u32 s101, 0xff
	s_cbranch_scc1 .Ldb_SSM2_young
	s_barrier
	s_mov_b32 s101, 1
	s_branch .Ldb_SSM2_exit

; #define G_STAGE(bufoff, gbase, o0, h64) do { \
;         __builtin_amdgcn_global_load_lds((const unsigned*)((const char*)(gbase) + (o0)), (LAS unsigned*)(lds + (bufoff) + ldsw), 16, 0, 0); \
;         __builtin_amdgcn_global_load_lds((const unsigned*)((const char*)(gbase) + (h64) + (o0)), (LAS unsigned*)(lds + (bufoff) + ldsw + 8192), 16, 0, 0); } while (0)
; #define G_LDA(dst, b, h) do { _Pragma("unroll") for (int m = 0; m < 4; ++m) _Pragma("unroll") for (int k = 0; k < 2; ++k) dst[m][k] = *(const LAS bf16x8*)(lds + G_SA(b, h) + aoff + m * 2048 + k * 1024); } while (0)
; #define G_LDB(dst, b, h) do { _Pragma("unroll") for (int n = 0; n < 2; ++n) _Pragma("unroll") for (int k = 0; k < 2; ++k) dst[n][k] = *(const LAS bf16x8*)(lds + G_SB(b, h) + boff + n * 2048 + k * 1024); } while (0)
; #define G_WAIT_V(n) asm volatile("s_waitcnt vmcnt(" #n ")" ::: "memory")
; #define G_BAR __builtin_amdgcn_s_barrier()
;     ...
;         for (int t = 0; t < nt; t += 2) {
;             const bool last = (t == nt - 2);
;             const char* a1 = cA + (size_t)(t + 1) * ckA;
;             const char* a2 = last ? nA : cA + (size_t)(t + 2) * ckA; const char* b2 = last ? nB : cB + (size_t)(t + 2) * kB;
;             const char* a3 = a2 + ckA; const char* b3 = b2 + kB;
;             G_LDB(B0, 0, 0); G_SCHED; G_LDA(At, 0, 0); G_STAGE(G_SA(1, 1), a1 + chA, cA0, qA);
;             G_WAIT_L(8); G_BAR; G_WAIT_L(0); G_MMA(0, 0, At, B0); G_BAR; G_SCHED;
;             G_LDB(B1, 0, 1); G_STAGE(G_SB(0, 0), b2, cB0, qB);
;             G_BAR; G_WAIT_L(0); G_MMA(0, 1, At, B1); G_BAR;
;             G_LDA(At, 0, 1); G_STAGE(G_SA(0, 0), a2, cA0, qA);
;             G_BAR; G_WAIT_L(0); G_MMA(1, 0, At, B0); G_BAR; G_SCHED;
;             G_STAGE(G_SB(0, 1), b2 + chB, cB0, qB);
;             G_WAIT_V(6); G_BAR; G_MMA(1, 1, At, B1); G_BAR;
;             G_LDB(B0, 1, 0); G_SCHED; G_LDA(At, 1, 0); G_STAGE(G_SA(0, 1), a2 + chA, cA0, qA);
;             G_WAIT_L(8); G_BAR; G_WAIT_L(0); G_MMA(0, 0, At, B0); G_BAR; G_SCHED;
;             G_LDB(B1, 1, 1); G_STAGE(G_SB(1, 0), b3, cB0, qB);
;             G_BAR; G_WAIT_L(0); G_MMA(0, 1, At, B1); G_BAR;
;             G_LDA(At, 1, 1); G_STAGE(G_SA(1, 0), a3, cA0, qA);
;             G_BAR; G_WAIT_L(0); G_MMA(1, 0, At, B0); G_BAR; G_SCHED;
;             G_STAGE(G_SB(1, 1), b3 + chB, cB0, qB);
;             G_WAIT_V(6); G_BAR; G_MMA(1, 1, At, B1); G_BAR;
.LBB0_804:
	s_add_i32 s40, 0, 0x10000
	v_add_u32_e32 v0, s40, v196
	ds_read_b128 v[112:115], v0
	ds_read_b128 v[124:127], v0 offset:1024
	ds_read_b128 v[136:139], v0 offset:2048
	ds_read_b128 v[148:151], v0 offset:3072
	s_cmp_eq_u32 s19, 4
	s_cselect_b32 s5, s15, s3
	s_cselect_b32 s4, s14, s2
	s_cselect_b32 s37, s17, s18
	s_cselect_b32 s36, s16, s13
	s_mov_b32 s38, 0xffc01000
	s_mov_b32 s39, -1
	s_add_u32 vcc_lo, s2, s38
	s_addc_u32 vcc_hi, s3, s39
	s_mov_b32 s38, 0xffc01800
	s_add_i32 m0, s24, 0xc000
	s_mov_b32 s39, -1
	ds_read_b128 v[152:155], v197
	ds_read_b128 v[156:159], v197 offset:1024
	ds_read_b128 v[160:163], v197 offset:2048
	ds_read_b128 v[172:175], v197 offset:3072
	ds_read_b128 v[176:179], v197 offset:4096
	ds_read_b128 v[180:183], v197 offset:5120
	ds_read_b128 v[198:201], v197 offset:6144
	ds_read_b128 v[202:205], v197 offset:7168
	global_load_lds_dwordx4 v166, vcc
	s_add_i32 m0, s24, 0xe000
	s_nop 0
	s_add_u32 vcc_lo, s2, s38
	s_addc_u32 vcc_hi, s3, s39
	global_load_lds_dwordx4 v166, vcc
	s_waitcnt lgkmcnt(8)
	s_cmp_eq_u32 s101, 1
	s_cbranch_scc1 .Ldb_GLU_sk
	s_barrier
.Ldb_GLU_sk:
	s_mov_b32 s101, 0
	s_waitcnt lgkmcnt(0)
	v_mfma_f32_16x16x32_bf16 v[144:147], v[112:115], v[152:155], v[144:147]
	v_mfma_f32_16x16x32_bf16 v[140:143], v[136:139], v[152:155], v[140:143]
	v_mfma_f32_16x16x32_bf16 v[120:123], v[112:115], v[160:163], v[120:123]
	v_mfma_f32_16x16x32_bf16 v[116:119], v[136:139], v[160:163], v[116:119]
	v_mfma_f32_16x16x32_bf16 v[100:103], v[112:115], v[176:179], v[100:103]
	v_mfma_f32_16x16x32_bf16 v[96:99], v[136:139], v[176:179], v[96:99]
	v_mfma_f32_16x16x32_bf16 v[84:87], v[112:115], v[198:201], v[84:87]
	v_mfma_f32_16x16x32_bf16 v[80:83], v[136:139], v[198:201], v[80:83]
	v_mfma_f32_16x16x32_bf16 v[144:147], v[124:127], v[156:159], v[144:147]
	v_mfma_f32_16x16x32_bf16 v[140:143], v[148:151], v[156:159], v[140:143]
	v_mfma_f32_16x16x32_bf16 v[120:123], v[124:127], v[172:175], v[120:123]
	v_mfma_f32_16x16x32_bf16 v[116:119], v[148:151], v[172:175], v[116:119]
	v_mfma_f32_16x16x32_bf16 v[100:103], v[124:127], v[180:183], v[100:103]
	v_mfma_f32_16x16x32_bf16 v[96:99], v[148:151], v[180:183], v[96:99]
	v_mfma_f32_16x16x32_bf16 v[84:87], v[124:127], v[202:205], v[84:87]
	v_mfma_f32_16x16x32_bf16 v[80:83], v[148:151], v[202:205], v[80:83]
	s_barrier
	s_add_i32 s38, 0, 0x14000
	s_add_i32 s100, s40, s21
	v_add_u32_e32 v0, s38, v196
	s_mov_b32 m0, s100
	ds_read_b128 v[206:209], v0
	ds_read_b128 v[210:213], v0 offset:1024
	ds_read_b128 v[214:217], v0 offset:2048
	ds_read_b128 v[218:221], v0 offset:3072
	global_load_lds_dwordx4 v2, s[36:37]
	s_add_i32 m0, s100, 0x2000
	s_nop 0
	s_add_u32 vcc_lo, s36, s50
	s_addc_u32 vcc_hi, s37, s51
	global_load_lds_dwordx4 v2, vcc
	s_barrier
	s_waitcnt lgkmcnt(0)
	v_mfma_f32_16x16x32_bf16 v[132:135], v[206:209], v[152:155], v[132:135]
	v_mfma_f32_16x16x32_bf16 v[128:131], v[214:217], v[152:155], v[128:131]
	v_mfma_f32_16x16x32_bf16 v[108:111], v[206:209], v[160:163], v[108:111]
	v_mfma_f32_16x16x32_bf16 v[104:107], v[214:217], v[160:163], v[104:107]
	v_mfma_f32_16x16x32_bf16 v[92:95], v[206:209], v[176:179], v[92:95]
	v_mfma_f32_16x16x32_bf16 v[88:91], v[214:217], v[176:179], v[88:91]
	v_mfma_f32_16x16x32_bf16 v[76:79], v[206:209], v[198:201], v[76:79]
	v_mfma_f32_16x16x32_bf16 v[72:75], v[214:217], v[198:201], v[72:75]
	v_mfma_f32_16x16x32_bf16 v[132:135], v[210:213], v[156:159], v[132:135]
	v_mfma_f32_16x16x32_bf16 v[128:131], v[218:221], v[156:159], v[128:131]
	v_mfma_f32_16x16x32_bf16 v[108:111], v[210:213], v[172:175], v[108:111]
	v_mfma_f32_16x16x32_bf16 v[104:107], v[218:221], v[172:175], v[104:107]
	v_mfma_f32_16x16x32_bf16 v[92:95], v[210:213], v[180:183], v[92:95]
	v_mfma_f32_16x16x32_bf16 v[88:91], v[218:221], v[180:183], v[88:91]
	v_mfma_f32_16x16x32_bf16 v[76:79], v[210:213], v[202:205], v[76:79]
	v_mfma_f32_16x16x32_bf16 v[72:75], v[218:221], v[202:205], v[72:75]
	s_barrier
	s_mov_b32 m0, s24
	v_lshl_add_u64 v[222:223], s[4:5], 0, v[164:165]
	ds_read_b128 v[152:155], v197 offset:16384
	ds_read_b128 v[156:159], v197 offset:17408
	ds_read_b128 v[160:163], v197 offset:18432
	ds_read_b128 v[172:175], v197 offset:19456
	ds_read_b128 v[176:179], v197 offset:20480
	ds_read_b128 v[180:183], v197 offset:21504
	ds_read_b128 v[198:201], v197 offset:22528
	ds_read_b128 v[202:205], v197 offset:23552
	global_load_lds_dwordx4 v164, s[4:5]
	s_mov_b32 m0, s25
	s_nop 0
	s_add_u32 vcc_lo, s4, s70
	s_addc_u32 vcc_hi, s5, s71
	global_load_lds_dwordx4 v164, vcc
	s_barrier
	s_waitcnt lgkmcnt(0)
	v_mfma_f32_16x16x32_bf16 v[68:71], v[112:115], v[152:155], v[68:71]
	v_mfma_f32_16x16x32_bf16 v[64:67], v[136:139], v[152:155], v[64:67]
	v_mfma_f32_16x16x32_bf16 v[52:55], v[112:115], v[160:163], v[52:55]
	v_mfma_f32_16x16x32_bf16 v[48:51], v[136:139], v[160:163], v[48:51]
	v_mfma_f32_16x16x32_bf16 v[36:39], v[112:115], v[176:179], v[36:39]
	v_mfma_f32_16x16x32_bf16 v[32:35], v[136:139], v[176:179], v[32:35]
	v_mfma_f32_16x16x32_bf16 v[20:23], v[112:115], v[198:201], v[20:23]
	v_mfma_f32_16x16x32_bf16 v[16:19], v[136:139], v[198:201], v[16:19]
	v_mfma_f32_16x16x32_bf16 v[68:71], v[124:127], v[156:159], v[68:71]
	v_mfma_f32_16x16x32_bf16 v[64:67], v[148:151], v[156:159], v[64:67]
	v_mfma_f32_16x16x32_bf16 v[52:55], v[124:127], v[172:175], v[52:55]
	v_mfma_f32_16x16x32_bf16 v[48:51], v[148:151], v[172:175], v[48:51]
	v_mfma_f32_16x16x32_bf16 v[36:39], v[124:127], v[180:183], v[36:39]
	v_mfma_f32_16x16x32_bf16 v[32:35], v[148:151], v[180:183], v[32:35]
	v_mfma_f32_16x16x32_bf16 v[20:23], v[124:127], v[202:205], v[20:23]
	v_mfma_f32_16x16x32_bf16 v[16:19], v[148:151], v[202:205], v[16:19]
	s_barrier
; #define G_STAGE(bufoff, gbase, o0, h64) do { \
;         __builtin_amdgcn_global_load_lds((const unsigned*)((const char*)(gbase) + (o0)), (LAS unsigned*)(lds + (bufoff) + ldsw), 16, 0, 0); \
;         __builtin_amdgcn_global_load_lds((const unsigned*)((const char*)(gbase) + (h64) + (o0)), (LAS unsigned*)(lds + (bufoff) + ldsw + 8192), 16, 0, 0); } while (0)
; #define G_LDA(dst, b, h) do { _Pragma("unroll") for (int m = 0; m < 4; ++m) _Pragma("unroll") for (int k = 0; k < 2; ++k) dst[m][k] = *(const LAS bf16x8*)(lds + G_SA(b, h) + aoff + m * 2048 + k * 1024); } while (0)
; #define G_LDB(dst, b, h) do { _Pragma("unroll") for (int n = 0; n < 2; ++n) _Pragma("unroll") for (int k = 0; k < 2; ++k) dst[n][k] = *(const LAS bf16x8*)(lds + G_SB(b, h) + boff + n * 2048 + k * 1024); } while (0)
; #define G_WAIT_V(n) asm volatile("s_waitcnt vmcnt(" #n ")" ::: "memory")
; #define G_BAR __builtin_amdgcn_s_barrier()
;     ...
;         for (int t = 0; t < nt; t += 2) {
;             const bool last = (t == nt - 2);
;             const char* a1 = cA + (size_t)(t + 1) * ckA;
;             const char* a2 = last ? nA : cA + (size_t)(t + 2) * ckA; const char* b2 = last ? nB : cB + (size_t)(t + 2) * kB;
;             const char* a3 = a2 + ckA; const char* b3 = b2 + kB;
;             G_LDB(B0, 0, 0); G_SCHED; G_LDA(At, 0, 0); G_STAGE(G_SA(1, 1), a1 + chA, cA0, qA);
;             G_WAIT_L(8); G_BAR; G_WAIT_L(0); G_MMA(0, 0, At, B0); G_BAR; G_SCHED;
;             G_LDB(B1, 0, 1); G_STAGE(G_SB(0, 0), b2, cB0, qB);
;             G_BAR; G_WAIT_L(0); G_MMA(0, 1, At, B1); G_BAR;
;             G_LDA(At, 0, 1); G_STAGE(G_SA(0, 0), a2, cA0, qA);
;             G_BAR; G_WAIT_L(0); G_MMA(1, 0, At, B0); G_BAR; G_SCHED;
;             G_STAGE(G_SB(0, 1), b2 + chB, cB0, qB);
;             G_WAIT_V(6); G_BAR; G_MMA(1, 1, At, B1); G_BAR;
;             G_LDB(B0, 1, 0); G_SCHED; G_LDA(At, 1, 0); G_STAGE(G_SA(0, 1), a2 + chA, cA0, qA);
;             G_WAIT_L(8); G_BAR; G_WAIT_L(0); G_MMA(0, 0, At, B0); G_BAR; G_SCHED;
;             G_LDB(B1, 1, 1); G_STAGE(G_SB(1, 0), b3, cB0, qB);
;             G_BAR; G_WAIT_L(0); G_MMA(0, 1, At, B1); G_BAR;
;             G_LDA(At, 1, 1); G_STAGE(G_SA(1, 0), a3, cA0, qA);
;             G_BAR; G_WAIT_L(0); G_MMA(1, 0, At, B0); G_BAR; G_SCHED;
;             G_STAGE(G_SB(1, 1), b3 + chB, cB0, qB);
;             G_WAIT_V(6); G_BAR; G_MMA(1, 1, At, B1); G_BAR;
	s_add_i32 s100, s38, s21
	s_mov_b32 m0, s100
	s_nop 0
	s_add_u32 vcc_lo, s36, s0
	s_addc_u32 vcc_hi, s37, s1
	global_load_lds_dwordx4 v2, vcc
	s_add_i32 m0, s100, 0x2000
	s_nop 0
	s_add_u32 vcc_lo, s36, s52
	s_addc_u32 vcc_hi, s37, s53
	global_load_lds_dwordx4 v2, vcc
	s_waitcnt vmcnt(6)
	s_barrier
	v_mfma_f32_16x16x32_bf16 v[60:63], v[206:209], v[152:155], v[60:63]
	v_mfma_f32_16x16x32_bf16 v[56:59], v[214:217], v[152:155], v[56:59]
	v_mfma_f32_16x16x32_bf16 v[44:47], v[206:209], v[160:163], v[44:47]
	v_mfma_f32_16x16x32_bf16 v[40:43], v[214:217], v[160:163], v[40:43]
	v_mfma_f32_16x16x32_bf16 v[28:31], v[206:209], v[176:179], v[28:31]
	v_mfma_f32_16x16x32_bf16 v[24:27], v[214:217], v[176:179], v[24:27]
	v_mfma_f32_16x16x32_bf16 v[12:15], v[206:209], v[198:201], v[12:15]
	v_mfma_f32_16x16x32_bf16 v[8:11], v[214:217], v[198:201], v[8:11]
	v_mfma_f32_16x16x32_bf16 v[60:63], v[210:213], v[156:159], v[60:63]
	v_mfma_f32_16x16x32_bf16 v[56:59], v[218:221], v[156:159], v[56:59]
	v_mfma_f32_16x16x32_bf16 v[44:47], v[210:213], v[172:175], v[44:47]
	v_mfma_f32_16x16x32_bf16 v[40:43], v[218:221], v[172:175], v[40:43]
	v_mfma_f32_16x16x32_bf16 v[28:31], v[210:213], v[180:183], v[28:31]
	v_mfma_f32_16x16x32_bf16 v[24:27], v[218:221], v[180:183], v[24:27]
	v_mfma_f32_16x16x32_bf16 v[12:15], v[210:213], v[202:205], v[12:15]
	v_mfma_f32_16x16x32_bf16 v[8:11], v[218:221], v[202:205], v[8:11]
	s_barrier
	s_add_i32 s100, 0, 0x18000
	v_add_u32_e32 v0, s100, v196
	ds_read_b128 v[112:115], v0
	ds_read_b128 v[124:127], v0 offset:1024
	ds_read_b128 v[136:139], v0 offset:2048
	ds_read_b128 v[148:151], v0 offset:3072
	s_mov_b32 m0, s26
	ds_read_b128 v[152:155], v197 offset:32768
	ds_read_b128 v[156:159], v197 offset:33792
	ds_read_b128 v[160:163], v197 offset:34816
	ds_read_b128 v[172:175], v197 offset:35840
	ds_read_b128 v[176:179], v197 offset:36864
	ds_read_b128 v[180:183], v197 offset:37888
	ds_read_b128 v[198:201], v197 offset:38912
	ds_read_b128 v[202:205], v197 offset:39936
	s_add_u32 vcc_lo, s4, s80
	s_addc_u32 vcc_hi, s5, s81
	global_load_lds_dwordx4 v164, vcc
	s_mov_b32 m0, s27
	s_nop 0
	s_add_u32 vcc_lo, s4, s82
	s_addc_u32 vcc_hi, s5, s83
	global_load_lds_dwordx4 v164, vcc
	s_waitcnt lgkmcnt(8)
	s_barrier
	s_waitcnt lgkmcnt(0)
	v_mfma_f32_16x16x32_bf16 v[144:147], v[112:115], v[152:155], v[144:147]
	v_mfma_f32_16x16x32_bf16 v[140:143], v[136:139], v[152:155], v[140:143]
	v_mfma_f32_16x16x32_bf16 v[120:123], v[112:115], v[160:163], v[120:123]
	v_mfma_f32_16x16x32_bf16 v[116:119], v[136:139], v[160:163], v[116:119]
	v_mfma_f32_16x16x32_bf16 v[100:103], v[112:115], v[176:179], v[100:103]
	v_mfma_f32_16x16x32_bf16 v[96:99], v[136:139], v[176:179], v[96:99]
	v_mfma_f32_16x16x32_bf16 v[84:87], v[112:115], v[198:201], v[84:87]
	v_mfma_f32_16x16x32_bf16 v[80:83], v[136:139], v[198:201], v[80:83]
	v_mfma_f32_16x16x32_bf16 v[144:147], v[124:127], v[156:159], v[144:147]
	v_mfma_f32_16x16x32_bf16 v[140:143], v[148:151], v[156:159], v[140:143]
	v_mfma_f32_16x16x32_bf16 v[120:123], v[124:127], v[172:175], v[120:123]
	v_mfma_f32_16x16x32_bf16 v[116:119], v[148:151], v[172:175], v[116:119]
	v_mfma_f32_16x16x32_bf16 v[100:103], v[124:127], v[180:183], v[100:103]
	v_mfma_f32_16x16x32_bf16 v[96:99], v[148:151], v[180:183], v[96:99]
	v_mfma_f32_16x16x32_bf16 v[84:87], v[124:127], v[202:205], v[84:87]
	v_mfma_f32_16x16x32_bf16 v[80:83], v[148:151], v[202:205], v[80:83]
	s_barrier
	s_add_i32 s5, 0, 0x1c000
	s_add_i32 s4, s100, s21
	v_add_u32_e32 v0, s5, v196
	s_mov_b32 m0, s4
	ds_read_b128 v[206:209], v0
	ds_read_b128 v[210:213], v0 offset:1024
	ds_read_b128 v[214:217], v0 offset:2048
	ds_read_b128 v[218:221], v0 offset:3072
	s_add_u32 vcc_lo, s36, s46
	s_addc_u32 vcc_hi, s37, s47
	global_load_lds_dwordx4 v2, vcc
	s_add_i32 m0, s4, 0x2000
	s_nop 0
	s_add_u32 vcc_lo, s36, s54
	s_addc_u32 vcc_hi, s37, s55
	global_load_lds_dwordx4 v2, vcc
	s_barrier
; #define G_STAGE(bufoff, gbase, o0, h64) do { \
;         __builtin_amdgcn_global_load_lds((const unsigned*)((const char*)(gbase) + (o0)), (LAS unsigned*)(lds + (bufoff) + ldsw), 16, 0, 0); \
;         __builtin_amdgcn_global_load_lds((const unsigned*)((const char*)(gbase) + (h64) + (o0)), (LAS unsigned*)(lds + (bufoff) + ldsw + 8192), 16, 0, 0); } while (0)
; #define G_LDA(dst, b, h) do { _Pragma("unroll") for (int m = 0; m < 4; ++m) _Pragma("unroll") for (int k = 0; k < 2; ++k) dst[m][k] = *(const LAS bf16x8*)(lds + G_SA(b, h) + aoff + m * 2048 + k * 1024); } while (0)
; #define G_LDB(dst, b, h) do { _Pragma("unroll") for (int n = 0; n < 2; ++n) _Pragma("unroll") for (int k = 0; k < 2; ++k) dst[n][k] = *(const LAS bf16x8*)(lds + G_SB(b, h) + boff + n * 2048 + k * 1024); } while (0)
; #define G_WAIT_V(n) asm volatile("s_waitcnt vmcnt(" #n ")" ::: "memory")
; #define G_BAR __builtin_amdgcn_s_barrier()
;     ...
;         for (int t = 0; t < nt; t += 2) {
;             const bool last = (t == nt - 2);
;             const char* a1 = cA + (size_t)(t + 1) * ckA;
;             const char* a2 = last ? nA : cA + (size_t)(t + 2) * ckA; const char* b2 = last ? nB : cB + (size_t)(t + 2) * kB;
;             const char* a3 = a2 + ckA; const char* b3 = b2 + kB;
;             G_LDB(B0, 0, 0); G_SCHED; G_LDA(At, 0, 0); G_STAGE(G_SA(1, 1), a1 + chA, cA0, qA);
;             G_WAIT_L(8); G_BAR; G_WAIT_L(0); G_MMA(0, 0, At, B0); G_BAR; G_SCHED;
;             G_LDB(B1, 0, 1); G_STAGE(G_SB(0, 0), b2, cB0, qB);
;             G_BAR; G_WAIT_L(0); G_MMA(0, 1, At, B1); G_BAR;
;             G_LDA(At, 0, 1); G_STAGE(G_SA(0, 0), a2, cA0, qA);
;             G_BAR; G_WAIT_L(0); G_MMA(1, 0, At, B0); G_BAR; G_SCHED;
;             G_STAGE(G_SB(0, 1), b2 + chB, cB0, qB);
;             G_WAIT_V(6); G_BAR; G_MMA(1, 1, At, B1); G_BAR;
;             G_LDB(B0, 1, 0); G_SCHED; G_LDA(At, 1, 0); G_STAGE(G_SA(0, 1), a2 + chA, cA0, qA);
;             G_WAIT_L(8); G_BAR; G_WAIT_L(0); G_MMA(0, 0, At, B0); G_BAR; G_SCHED;
;             G_LDB(B1, 1, 1); G_STAGE(G_SB(1, 0), b3, cB0, qB);
;             G_BAR; G_WAIT_L(0); G_MMA(0, 1, At, B1); G_BAR;
;             G_LDA(At, 1, 1); G_STAGE(G_SA(1, 0), a3, cA0, qA);
;             G_BAR; G_WAIT_L(0); G_MMA(1, 0, At, B0); G_BAR; G_SCHED;
;             G_STAGE(G_SB(1, 1), b3 + chB, cB0, qB);
;             G_WAIT_V(6); G_BAR; G_MMA(1, 1, At, B1); G_BAR;
	s_waitcnt lgkmcnt(0)
	v_mfma_f32_16x16x32_bf16 v[132:135], v[206:209], v[152:155], v[132:135]
	v_mfma_f32_16x16x32_bf16 v[128:131], v[214:217], v[152:155], v[128:131]
	v_mfma_f32_16x16x32_bf16 v[108:111], v[206:209], v[160:163], v[108:111]
	v_mfma_f32_16x16x32_bf16 v[104:107], v[214:217], v[160:163], v[104:107]
	v_mfma_f32_16x16x32_bf16 v[92:95], v[206:209], v[176:179], v[92:95]
	v_mfma_f32_16x16x32_bf16 v[88:91], v[214:217], v[176:179], v[88:91]
	v_mfma_f32_16x16x32_bf16 v[76:79], v[206:209], v[198:201], v[76:79]
	v_mfma_f32_16x16x32_bf16 v[72:75], v[214:217], v[198:201], v[72:75]
	v_mfma_f32_16x16x32_bf16 v[132:135], v[210:213], v[156:159], v[132:135]
	v_mfma_f32_16x16x32_bf16 v[128:131], v[218:221], v[156:159], v[128:131]
	v_mfma_f32_16x16x32_bf16 v[108:111], v[210:213], v[172:175], v[108:111]
	v_mfma_f32_16x16x32_bf16 v[104:107], v[218:221], v[172:175], v[104:107]
	v_mfma_f32_16x16x32_bf16 v[92:95], v[210:213], v[180:183], v[92:95]
	v_mfma_f32_16x16x32_bf16 v[88:91], v[218:221], v[180:183], v[88:91]
	v_mfma_f32_16x16x32_bf16 v[76:79], v[210:213], v[202:205], v[76:79]
	v_mfma_f32_16x16x32_bf16 v[72:75], v[218:221], v[202:205], v[72:75]
	s_barrier
	s_mov_b32 m0, s29
	v_lshl_add_u64 v[224:225], v[222:223], 0, s[62:63]
	ds_read_b128 v[152:155], v197 offset:49152
	ds_read_b128 v[156:159], v197 offset:50176
	ds_read_b128 v[160:163], v197 offset:51200
	ds_read_b128 v[172:175], v197 offset:52224
	ds_read_b128 v[176:179], v197 offset:53248
	ds_read_b128 v[180:183], v197 offset:54272
	ds_read_b128 v[198:201], v197 offset:55296
	ds_read_b128 v[202:205], v197 offset:56320
	global_load_lds_dwordx4 v[224:225], off
	v_lshl_add_u64 v[222:223], v[222:223], 0, s[84:85]
	s_mov_b32 m0, s30
	s_nop 0
	global_load_lds_dwordx4 v[222:223], off
	s_barrier
	s_waitcnt lgkmcnt(0)
	v_mfma_f32_16x16x32_bf16 v[68:71], v[112:115], v[152:155], v[68:71]
	v_mfma_f32_16x16x32_bf16 v[64:67], v[136:139], v[152:155], v[64:67]
	v_mfma_f32_16x16x32_bf16 v[52:55], v[112:115], v[160:163], v[52:55]
	v_mfma_f32_16x16x32_bf16 v[48:51], v[136:139], v[160:163], v[48:51]
	v_mfma_f32_16x16x32_bf16 v[36:39], v[112:115], v[176:179], v[36:39]
	v_mfma_f32_16x16x32_bf16 v[32:35], v[136:139], v[176:179], v[32:35]
	v_mfma_f32_16x16x32_bf16 v[20:23], v[112:115], v[198:201], v[20:23]
	v_mfma_f32_16x16x32_bf16 v[16:19], v[136:139], v[198:201], v[16:19]
	v_mfma_f32_16x16x32_bf16 v[68:71], v[124:127], v[156:159], v[68:71]
	v_mfma_f32_16x16x32_bf16 v[64:67], v[148:151], v[156:159], v[64:67]
	v_mfma_f32_16x16x32_bf16 v[52:55], v[124:127], v[172:175], v[52:55]
	v_mfma_f32_16x16x32_bf16 v[48:51], v[148:151], v[172:175], v[48:51]
	v_mfma_f32_16x16x32_bf16 v[36:39], v[124:127], v[180:183], v[36:39]
	v_mfma_f32_16x16x32_bf16 v[32:35], v[148:151], v[180:183], v[32:35]
	v_mfma_f32_16x16x32_bf16 v[20:23], v[124:127], v[202:205], v[20:23]
	v_mfma_f32_16x16x32_bf16 v[16:19], v[148:151], v[202:205], v[16:19]
	s_barrier
	s_add_i32 s4, s5, s21
	s_mov_b32 m0, s4
	s_nop 0
	s_add_u32 vcc_lo, s36, s42
	s_addc_u32 vcc_hi, s37, s43
	global_load_lds_dwordx4 v2, vcc
	s_add_i32 m0, s4, 0x2000
	s_nop 0
	s_add_u32 vcc_lo, s36, s58
	s_addc_u32 vcc_hi, s37, s59
	global_load_lds_dwordx4 v2, vcc
	s_add_i32 s19, s19, 2
	s_add_u32 s13, s13, 0x100
	s_addc_u32 s18, s18, 0
	s_add_u32 s2, s2, 0x800000
	s_addc_u32 s3, s3, 0
	s_cmp_gt_u32 s19, 5
	s_waitcnt vmcnt(6)
	s_barrier
	v_mfma_f32_16x16x32_bf16 v[60:63], v[206:209], v[152:155], v[60:63]
	v_mfma_f32_16x16x32_bf16 v[56:59], v[214:217], v[152:155], v[56:59]
	v_mfma_f32_16x16x32_bf16 v[44:47], v[206:209], v[160:163], v[44:47]
	v_mfma_f32_16x16x32_bf16 v[40:43], v[214:217], v[160:163], v[40:43]
	v_mfma_f32_16x16x32_bf16 v[28:31], v[206:209], v[176:179], v[28:31]
	v_mfma_f32_16x16x32_bf16 v[24:27], v[214:217], v[176:179], v[24:27]
	v_mfma_f32_16x16x32_bf16 v[12:15], v[206:209], v[198:201], v[12:15]
	v_mfma_f32_16x16x32_bf16 v[8:11], v[214:217], v[198:201], v[8:11]
	v_mfma_f32_16x16x32_bf16 v[60:63], v[210:213], v[156:159], v[60:63]
	v_mfma_f32_16x16x32_bf16 v[56:59], v[218:221], v[156:159], v[56:59]
	v_mfma_f32_16x16x32_bf16 v[44:47], v[210:213], v[172:175], v[44:47]
	v_mfma_f32_16x16x32_bf16 v[40:43], v[218:221], v[172:175], v[40:43]
	v_mfma_f32_16x16x32_bf16 v[28:31], v[210:213], v[180:183], v[28:31]
	v_mfma_f32_16x16x32_bf16 v[24:27], v[218:221], v[180:183], v[24:27]
	v_mfma_f32_16x16x32_bf16 v[12:15], v[210:213], v[202:205], v[12:15]
	v_mfma_f32_16x16x32_bf16 v[8:11], v[218:221], v[202:205], v[8:11]
	s_cbranch_scc0 .Ldb_GLU_cont
	v_readfirstlane_b32 s101, v186
	s_cmpk_gt_u32 s101, 0xff
	s_cbranch_scc1 .Ldb_GLU_young
	s_barrier
	s_mov_b32 s101, 1
	s_branch .Ldb_GLU_exit

; #define G_STAGE(bufoff, gbase, o0, h64) do { \
;         __builtin_amdgcn_global_load_lds((const unsigned*)((const char*)(gbase) + (o0)), (LAS unsigned*)(lds + (bufoff) + ldsw), 16, 0, 0); \
;         __builtin_amdgcn_global_load_lds((const unsigned*)((const char*)(gbase) + (h64) + (o0)), (LAS unsigned*)(lds + (bufoff) + ldsw + 8192), 16, 0, 0); } while (0)
; #define G_LDA(dst, b, h) do { _Pragma("unroll") for (int m = 0; m < 4; ++m) _Pragma("unroll") for (int k = 0; k < 2; ++k) dst[m][k] = *(const LAS bf16x8*)(lds + G_SA(b, h) + aoff + m * 2048 + k * 1024); } while (0)
; #define G_LDB(dst, b, h) do { _Pragma("unroll") for (int n = 0; n < 2; ++n) _Pragma("unroll") for (int k = 0; k < 2; ++k) dst[n][k] = *(const LAS bf16x8*)(lds + G_SB(b, h) + boff + n * 2048 + k * 1024); } while (0)
; #define G_WAIT_V(n) asm volatile("s_waitcnt vmcnt(" #n ")" ::: "memory")
; #define G_BAR __builtin_amdgcn_s_barrier()
;     ...
;         for (int t = 0; t < nt; t += 2) {
;             const bool last = (t == nt - 2);
;             const char* a1 = cA + (size_t)(t + 1) * ckA;
;             const char* a2 = last ? nA : cA + (size_t)(t + 2) * ckA; const char* b2 = last ? nB : cB + (size_t)(t + 2) * kB;
;             const char* a3 = a2 + ckA; const char* b3 = b2 + kB;
;             G_LDB(B0, 0, 0); G_SCHED; G_LDA(At, 0, 0); G_STAGE(G_SA(1, 1), a1 + chA, cA0, qA);
;             G_WAIT_L(8); G_BAR; G_WAIT_L(0); G_MMA(0, 0, At, B0); G_BAR; G_SCHED;
;             G_LDB(B1, 0, 1); G_STAGE(G_SB(0, 0), b2, cB0, qB);
;             G_BAR; G_WAIT_L(0); G_MMA(0, 1, At, B1); G_BAR;
;             G_LDA(At, 0, 1); G_STAGE(G_SA(0, 0), a2, cA0, qA);
;             G_BAR; G_WAIT_L(0); G_MMA(1, 0, At, B0); G_BAR; G_SCHED;
;             G_STAGE(G_SB(0, 1), b2 + chB, cB0, qB);
;             G_WAIT_V(6); G_BAR; G_MMA(1, 1, At, B1); G_BAR;
;             G_LDB(B0, 1, 0); G_SCHED; G_LDA(At, 1, 0); G_STAGE(G_SA(0, 1), a2 + chA, cA0, qA);
;             G_WAIT_L(8); G_BAR; G_WAIT_L(0); G_MMA(0, 0, At, B0); G_BAR; G_SCHED;
;             G_LDB(B1, 1, 1); G_STAGE(G_SB(1, 0), b3, cB0, qB);
;             G_BAR; G_WAIT_L(0); G_MMA(0, 1, At, B1); G_BAR;
;             G_LDA(At, 1, 1); G_STAGE(G_SA(1, 0), a3, cA0, qA);
;             G_BAR; G_WAIT_L(0); G_MMA(1, 0, At, B0); G_BAR; G_SCHED;
;             G_STAGE(G_SB(1, 1), b3 + chB, cB0, qB);
;             G_WAIT_V(6); G_BAR; G_MMA(1, 1, At, B1); G_BAR;
.LBB0_872:
	s_add_u32 s4, s2, 0xfff50080
	s_addc_u32 s5, s3, -1
	s_add_i32 s40, 0, 0x10000
	v_add_u32_e32 v140, s40, v159
	ds_read_b128 v[144:147], v140
	ds_read_b128 v[148:151], v140 offset:1024
	ds_read_b128 v[136:139], v140 offset:2048
	ds_read_b128 v[140:143], v140 offset:3072
	s_cmp_eq_u32 s39, 4
	s_cselect_b32 s13, s9, s5
	s_cselect_b32 s12, s8, s4
	s_cselect_b32 s15, s11, s38
	s_cselect_b32 s14, s10, s37
	s_add_i32 m0, s22, 0xc000
	ds_read_b128 v[160:163], v236
	ds_read_b128 v[164:167], v236 offset:1024
	ds_read_b128 v[176:179], v236 offset:2048
	ds_read_b128 v[180:183], v236 offset:3072
	ds_read_b128 v[196:199], v236 offset:4096
	ds_read_b128 v[200:203], v236 offset:5120
	ds_read_b128 v[204:207], v236 offset:6144
	ds_read_b128 v[208:211], v236 offset:7168
	global_load_lds_dwordx4 v152, s[2:3]
	s_add_i32 m0, s22, 0xe000
	s_nop 0
	s_add_u32 vcc_lo, s2, s86
	s_addc_u32 vcc_hi, s3, s87
	global_load_lds_dwordx4 v152, vcc
	s_waitcnt lgkmcnt(8)
	s_cmp_eq_u32 s101, 1
	s_cbranch_scc1 .Ldb_MG0_sk
	s_barrier
.Ldb_MG0_sk:
	s_mov_b32 s101, 0
	s_waitcnt lgkmcnt(0)
	v_mfma_f32_16x16x128_f8f6f4 v[128:131], v[144:151], v[160:167], v[128:131]
	v_mfma_f32_16x16x128_f8f6f4 v[132:135], v[136:143], v[160:167], v[132:135]
	v_mfma_f32_16x16x128_f8f6f4 v[112:115], v[144:151], v[176:183], v[112:115]
	v_mfma_f32_16x16x128_f8f6f4 v[116:119], v[136:143], v[176:183], v[116:119]
	v_mfma_f32_16x16x128_f8f6f4 v[96:99], v[144:151], v[196:203], v[96:99]
	v_mfma_f32_16x16x128_f8f6f4 v[100:103], v[136:143], v[196:203], v[100:103]
	v_mfma_f32_16x16x128_f8f6f4 v[80:83], v[144:151], v[204:211], v[80:83]
	v_mfma_f32_16x16x128_f8f6f4 v[84:87], v[136:143], v[204:211], v[84:87]
	s_barrier
	s_add_i32 s4, 0, 0x14000
	v_add_u32_e32 v154, s4, v159
	s_add_i32 s5, s40, s17
	ds_read_b128 v[212:215], v154
	ds_read_b128 v[216:219], v154 offset:1024
	ds_read_b128 v[220:223], v154 offset:2048
	ds_read_b128 v[224:227], v154 offset:3072
	s_mov_b32 m0, s5
	global_load_lds_dwordx4 v0, s[14:15]
	s_add_i32 m0, s5, 0x2000
	s_nop 0
	s_add_u32 vcc_lo, s14, s50
	s_addc_u32 vcc_hi, s15, s51
	global_load_lds_dwordx4 v0, vcc
	s_barrier
	s_waitcnt lgkmcnt(0)
	v_mfma_f32_16x16x128_f8f6f4 v[124:127], v[212:219], v[160:167], v[124:127]
	v_mfma_f32_16x16x128_f8f6f4 v[120:123], v[220:227], v[160:167], v[120:123]
	v_mfma_f32_16x16x128_f8f6f4 v[108:111], v[212:219], v[176:183], v[108:111]
	v_mfma_f32_16x16x128_f8f6f4 v[104:107], v[220:227], v[176:183], v[104:107]
	v_mfma_f32_16x16x128_f8f6f4 v[92:95], v[212:219], v[196:203], v[92:95]
	v_mfma_f32_16x16x128_f8f6f4 v[88:91], v[220:227], v[196:203], v[88:91]
	v_mfma_f32_16x16x128_f8f6f4 v[76:79], v[212:219], v[204:211], v[76:79]
	v_mfma_f32_16x16x128_f8f6f4 v[72:75], v[220:227], v[204:211], v[72:75]
	s_barrier
	s_mov_b32 m0, s22
	ds_read_b128 v[160:163], v236 offset:16384
	ds_read_b128 v[164:167], v236 offset:17408
	ds_read_b128 v[176:179], v236 offset:18432
	ds_read_b128 v[180:183], v236 offset:19456
	ds_read_b128 v[196:199], v236 offset:20480
	ds_read_b128 v[200:203], v236 offset:21504
	ds_read_b128 v[204:207], v236 offset:22528
	ds_read_b128 v[208:211], v236 offset:23552
	global_load_lds_dwordx4 v2, s[12:13]
	s_mov_b32 m0, s23
	s_nop 0
	s_add_u32 vcc_lo, s12, s86
	s_addc_u32 vcc_hi, s13, s87
	global_load_lds_dwordx4 v2, vcc
	s_barrier
	s_waitcnt lgkmcnt(0)
	v_mfma_f32_16x16x128_f8f6f4 v[64:67], v[144:151], v[160:167], v[64:67]
	v_mfma_f32_16x16x128_f8f6f4 v[68:71], v[136:143], v[160:167], v[68:71]
	v_mfma_f32_16x16x128_f8f6f4 v[48:51], v[144:151], v[176:183], v[48:51]
	v_mfma_f32_16x16x128_f8f6f4 v[52:55], v[136:143], v[176:183], v[52:55]
	v_mfma_f32_16x16x128_f8f6f4 v[32:35], v[144:151], v[196:203], v[32:35]
	v_mfma_f32_16x16x128_f8f6f4 v[36:39], v[136:143], v[196:203], v[36:39]
	v_mfma_f32_16x16x128_f8f6f4 v[20:23], v[144:151], v[204:211], v[20:23]
	v_mfma_f32_16x16x128_f8f6f4 v[16:19], v[136:143], v[204:211], v[16:19]
	s_barrier
	s_add_i32 s4, s4, s17
	s_mov_b32 m0, s4
	s_nop 0
	s_add_u32 vcc_lo, s14, s0
	s_addc_u32 vcc_hi, s15, s1
	global_load_lds_dwordx4 v0, vcc
	s_add_i32 m0, s4, 0x2000
	s_nop 0
	s_add_u32 vcc_lo, s14, s52
	s_addc_u32 vcc_hi, s15, s53
	global_load_lds_dwordx4 v0, vcc
	s_waitcnt vmcnt(6)
	s_barrier
	v_mfma_f32_16x16x128_f8f6f4 v[60:63], v[212:219], v[160:167], v[60:63]
	v_mfma_f32_16x16x128_f8f6f4 v[56:59], v[220:227], v[160:167], v[56:59]
	v_mfma_f32_16x16x128_f8f6f4 v[44:47], v[212:219], v[176:183], v[44:47]
	v_mfma_f32_16x16x128_f8f6f4 v[40:43], v[220:227], v[176:183], v[40:43]
	v_mfma_f32_16x16x128_f8f6f4 v[28:31], v[212:219], v[196:203], v[28:31]
	v_mfma_f32_16x16x128_f8f6f4 v[24:27], v[220:227], v[196:203], v[24:27]
	v_mfma_f32_16x16x128_f8f6f4 v[12:15], v[212:219], v[204:211], v[12:15]
	v_mfma_f32_16x16x128_f8f6f4 v[8:11], v[220:227], v[204:211], v[8:11]
	s_barrier
; #define G_STAGE(bufoff, gbase, o0, h64) do { \
;         __builtin_amdgcn_global_load_lds((const unsigned*)((const char*)(gbase) + (o0)), (LAS unsigned*)(lds + (bufoff) + ldsw), 16, 0, 0); \
;         __builtin_amdgcn_global_load_lds((const unsigned*)((const char*)(gbase) + (h64) + (o0)), (LAS unsigned*)(lds + (bufoff) + ldsw + 8192), 16, 0, 0); } while (0)
; #define G_LDA(dst, b, h) do { _Pragma("unroll") for (int m = 0; m < 4; ++m) _Pragma("unroll") for (int k = 0; k < 2; ++k) dst[m][k] = *(const LAS bf16x8*)(lds + G_SA(b, h) + aoff + m * 2048 + k * 1024); } while (0)
; #define G_LDB(dst, b, h) do { _Pragma("unroll") for (int n = 0; n < 2; ++n) _Pragma("unroll") for (int k = 0; k < 2; ++k) dst[n][k] = *(const LAS bf16x8*)(lds + G_SB(b, h) + boff + n * 2048 + k * 1024); } while (0)
; #define G_WAIT_V(n) asm volatile("s_waitcnt vmcnt(" #n ")" ::: "memory")
; #define G_BAR __builtin_amdgcn_s_barrier()
;     ...
;         for (int t = 0; t < nt; t += 2) {
;             const bool last = (t == nt - 2);
;             const char* a1 = cA + (size_t)(t + 1) * ckA;
;             const char* a2 = last ? nA : cA + (size_t)(t + 2) * ckA; const char* b2 = last ? nB : cB + (size_t)(t + 2) * kB;
;             const char* a3 = a2 + ckA; const char* b3 = b2 + kB;
;             G_LDB(B0, 0, 0); G_SCHED; G_LDA(At, 0, 0); G_STAGE(G_SA(1, 1), a1 + chA, cA0, qA);
;             G_WAIT_L(8); G_BAR; G_WAIT_L(0); G_MMA(0, 0, At, B0); G_BAR; G_SCHED;
;             G_LDB(B1, 0, 1); G_STAGE(G_SB(0, 0), b2, cB0, qB);
;             G_BAR; G_WAIT_L(0); G_MMA(0, 1, At, B1); G_BAR;
;             G_LDA(At, 0, 1); G_STAGE(G_SA(0, 0), a2, cA0, qA);
;             G_BAR; G_WAIT_L(0); G_MMA(1, 0, At, B0); G_BAR; G_SCHED;
;             G_STAGE(G_SB(0, 1), b2 + chB, cB0, qB);
;             G_WAIT_V(6); G_BAR; G_MMA(1, 1, At, B1); G_BAR;
;             G_LDB(B0, 1, 0); G_SCHED; G_LDA(At, 1, 0); G_STAGE(G_SA(0, 1), a2 + chA, cA0, qA);
;             G_WAIT_L(8); G_BAR; G_WAIT_L(0); G_MMA(0, 0, At, B0); G_BAR; G_SCHED;
;             G_LDB(B1, 1, 1); G_STAGE(G_SB(1, 0), b3, cB0, qB);
;             G_BAR; G_WAIT_L(0); G_MMA(0, 1, At, B1); G_BAR;
;             G_LDA(At, 1, 1); G_STAGE(G_SA(1, 0), a3, cA0, qA);
;             G_BAR; G_WAIT_L(0); G_MMA(1, 0, At, B0); G_BAR; G_SCHED;
;             G_STAGE(G_SB(1, 1), b3 + chB, cB0, qB);
;             G_WAIT_V(6); G_BAR; G_MMA(1, 1, At, B1); G_BAR;
	s_add_i32 s4, 0, 0x18000
	v_add_u32_e32 v140, s4, v159
	ds_read_b128 v[144:147], v140
	ds_read_b128 v[148:151], v140 offset:1024
	ds_read_b128 v[136:139], v140 offset:2048
	ds_read_b128 v[140:143], v140 offset:3072
	s_mov_b32 m0, s24
	ds_read_b128 v[160:163], v236 offset:32768
	ds_read_b128 v[164:167], v236 offset:33792
	ds_read_b128 v[176:179], v236 offset:34816
	ds_read_b128 v[180:183], v236 offset:35840
	ds_read_b128 v[196:199], v236 offset:36864
	ds_read_b128 v[200:203], v236 offset:37888
	ds_read_b128 v[204:207], v236 offset:38912
	ds_read_b128 v[208:211], v236 offset:39936
	s_add_u32 vcc_lo, s12, s88
	s_addc_u32 vcc_hi, s13, s89
	global_load_lds_dwordx4 v2, vcc
	s_mov_b32 m0, s25
	s_nop 0
	s_add_u32 vcc_lo, s12, s64
	s_addc_u32 vcc_hi, s13, s65
	global_load_lds_dwordx4 v2, vcc
	s_waitcnt lgkmcnt(8)
	s_barrier
	s_waitcnt lgkmcnt(0)
	v_mfma_f32_16x16x128_f8f6f4 v[128:131], v[144:151], v[160:167], v[128:131]
	v_mfma_f32_16x16x128_f8f6f4 v[132:135], v[136:143], v[160:167], v[132:135]
	v_mfma_f32_16x16x128_f8f6f4 v[112:115], v[144:151], v[176:183], v[112:115]
	v_mfma_f32_16x16x128_f8f6f4 v[116:119], v[136:143], v[176:183], v[116:119]
	v_mfma_f32_16x16x128_f8f6f4 v[96:99], v[144:151], v[196:203], v[96:99]
	v_mfma_f32_16x16x128_f8f6f4 v[100:103], v[136:143], v[196:203], v[100:103]
	v_mfma_f32_16x16x128_f8f6f4 v[80:83], v[144:151], v[204:211], v[80:83]
	v_mfma_f32_16x16x128_f8f6f4 v[84:87], v[136:143], v[204:211], v[84:87]
	s_barrier
	s_add_i32 s5, 0, 0x1c000
	s_add_i32 s4, s4, s17
	v_add_u32_e32 v237, s5, v159
	s_mov_b32 m0, s4
	ds_read_b128 v[212:215], v237
	ds_read_b128 v[216:219], v237 offset:1024
	ds_read_b128 v[220:223], v237 offset:2048
	ds_read_b128 v[224:227], v237 offset:3072
	s_add_u32 vcc_lo, s14, s46
	s_addc_u32 vcc_hi, s15, s47
	global_load_lds_dwordx4 v0, vcc
	s_add_i32 m0, s4, 0x2000
	s_nop 0
	s_add_u32 vcc_lo, s14, s54
	s_addc_u32 vcc_hi, s15, s55
	global_load_lds_dwordx4 v0, vcc
	s_barrier
	s_waitcnt lgkmcnt(0)
	v_mfma_f32_16x16x128_f8f6f4 v[124:127], v[212:219], v[160:167], v[124:127]
	v_mfma_f32_16x16x128_f8f6f4 v[120:123], v[220:227], v[160:167], v[120:123]
	v_mfma_f32_16x16x128_f8f6f4 v[108:111], v[212:219], v[176:183], v[108:111]
	v_mfma_f32_16x16x128_f8f6f4 v[104:107], v[220:227], v[176:183], v[104:107]
	v_mfma_f32_16x16x128_f8f6f4 v[92:95], v[212:219], v[196:203], v[92:95]
	v_mfma_f32_16x16x128_f8f6f4 v[88:91], v[220:227], v[196:203], v[88:91]
	v_mfma_f32_16x16x128_f8f6f4 v[76:79], v[212:219], v[204:211], v[76:79]
	v_mfma_f32_16x16x128_f8f6f4 v[72:75], v[220:227], v[204:211], v[72:75]
	s_barrier
	s_mov_b32 m0, s26
	ds_read_b128 v[160:163], v236 offset:49152
	ds_read_b128 v[164:167], v236 offset:50176
	ds_read_b128 v[176:179], v236 offset:51200
	ds_read_b128 v[180:183], v236 offset:52224
	ds_read_b128 v[196:199], v236 offset:53248
	ds_read_b128 v[200:203], v236 offset:54272
	ds_read_b128 v[204:207], v236 offset:55296
	ds_read_b128 v[208:211], v236 offset:56320
	s_add_u32 vcc_lo, s12, s46
	s_addc_u32 vcc_hi, s13, s47
	global_load_lds_dwordx4 v2, vcc
	s_mov_b32 m0, s27
	s_nop 0
	s_add_u32 vcc_lo, s12, s66
	s_addc_u32 vcc_hi, s13, s67
	global_load_lds_dwordx4 v2, vcc
	s_barrier
	s_waitcnt lgkmcnt(0)
	v_mfma_f32_16x16x128_f8f6f4 v[64:67], v[144:151], v[160:167], v[64:67]
	v_mfma_f32_16x16x128_f8f6f4 v[68:71], v[136:143], v[160:167], v[68:71]
	v_mfma_f32_16x16x128_f8f6f4 v[48:51], v[144:151], v[176:183], v[48:51]
	v_mfma_f32_16x16x128_f8f6f4 v[52:55], v[136:143], v[176:183], v[52:55]
	v_mfma_f32_16x16x128_f8f6f4 v[32:35], v[144:151], v[196:203], v[32:35]
	v_mfma_f32_16x16x128_f8f6f4 v[36:39], v[136:143], v[196:203], v[36:39]
	v_mfma_f32_16x16x128_f8f6f4 v[20:23], v[144:151], v[204:211], v[20:23]
	v_mfma_f32_16x16x128_f8f6f4 v[16:19], v[136:143], v[204:211], v[16:19]
	s_barrier
	s_add_i32 s4, s5, s17
	s_mov_b32 m0, s4
	s_nop 0
	s_add_u32 vcc_lo, s14, s42
	s_addc_u32 vcc_hi, s15, s43
	global_load_lds_dwordx4 v0, vcc
	s_add_i32 m0, s4, 0x2000
	s_nop 0
	s_add_u32 vcc_lo, s14, s58
	s_addc_u32 vcc_hi, s15, s59
	global_load_lds_dwordx4 v0, vcc
	s_add_i32 s39, s39, 2
	s_add_u32 s2, s2, 0x100
	s_addc_u32 s3, s3, 0
	s_add_u32 s37, s37, 0x100
	s_addc_u32 s38, s38, 0
	s_cmp_gt_u32 s39, 5
	s_waitcnt vmcnt(6)
	s_barrier
	v_mfma_f32_16x16x128_f8f6f4 v[60:63], v[212:219], v[160:167], v[60:63]
	v_mfma_f32_16x16x128_f8f6f4 v[56:59], v[220:227], v[160:167], v[56:59]
	v_mfma_f32_16x16x128_f8f6f4 v[44:47], v[212:219], v[176:183], v[44:47]
	v_mfma_f32_16x16x128_f8f6f4 v[40:43], v[220:227], v[176:183], v[40:43]
	v_mfma_f32_16x16x128_f8f6f4 v[28:31], v[212:219], v[196:203], v[28:31]
	v_mfma_f32_16x16x128_f8f6f4 v[24:27], v[220:227], v[196:203], v[24:27]
	v_mfma_f32_16x16x128_f8f6f4 v[12:15], v[212:219], v[204:211], v[12:15]
	v_mfma_f32_16x16x128_f8f6f4 v[8:11], v[220:227], v[204:211], v[8:11]
	s_cbranch_scc0 .Ldb_MG0_cont
	v_readfirstlane_b32 s101, v186
	s_cmpk_gt_u32 s101, 0xff
	s_cbranch_scc1 .Ldb_MG0_young
	s_barrier
	s_mov_b32 s101, 1
	s_branch .Ldb_MG0_exit

; #define G_STAGE(bufoff, gbase, o0, h64) do { \
;         __builtin_amdgcn_global_load_lds((const unsigned*)((const char*)(gbase) + (o0)), (LAS unsigned*)(lds + (bufoff) + ldsw), 16, 0, 0); \
;         __builtin_amdgcn_global_load_lds((const unsigned*)((const char*)(gbase) + (h64) + (o0)), (LAS unsigned*)(lds + (bufoff) + ldsw + 8192), 16, 0, 0); } while (0)
; #define G_LDA(dst, b, h) do { _Pragma("unroll") for (int m = 0; m < 4; ++m) _Pragma("unroll") for (int k = 0; k < 2; ++k) dst[m][k] = *(const LAS bf16x8*)(lds + G_SA(b, h) + aoff + m * 2048 + k * 1024); } while (0)
; #define G_LDB(dst, b, h) do { _Pragma("unroll") for (int n = 0; n < 2; ++n) _Pragma("unroll") for (int k = 0; k < 2; ++k) dst[n][k] = *(const LAS bf16x8*)(lds + G_SB(b, h) + boff + n * 2048 + k * 1024); } while (0)
; #define G_WAIT_V(n) asm volatile("s_waitcnt vmcnt(" #n ")" ::: "memory")
; #define G_BAR __builtin_amdgcn_s_barrier()
;     ...
;         for (int t = 0; t < nt; t += 2) {
;             const bool last = (t == nt - 2);
;             const char* a1 = cA + (size_t)(t + 1) * ckA;
;             const char* a2 = last ? nA : cA + (size_t)(t + 2) * ckA; const char* b2 = last ? nB : cB + (size_t)(t + 2) * kB;
;             const char* a3 = a2 + ckA; const char* b3 = b2 + kB;
;             G_LDB(B0, 0, 0); G_SCHED; G_LDA(At, 0, 0); G_STAGE(G_SA(1, 1), a1 + chA, cA0, qA);
;             G_WAIT_L(8); G_BAR; G_WAIT_L(0); G_MMA(0, 0, At, B0); G_BAR; G_SCHED;
;             G_LDB(B1, 0, 1); G_STAGE(G_SB(0, 0), b2, cB0, qB);
;             G_BAR; G_WAIT_L(0); G_MMA(0, 1, At, B1); G_BAR;
;             G_LDA(At, 0, 1); G_STAGE(G_SA(0, 0), a2, cA0, qA);
;             G_BAR; G_WAIT_L(0); G_MMA(1, 0, At, B0); G_BAR; G_SCHED;
;             G_STAGE(G_SB(0, 1), b2 + chB, cB0, qB);
;             G_WAIT_V(6); G_BAR; G_MMA(1, 1, At, B1); G_BAR;
;             G_LDB(B0, 1, 0); G_SCHED; G_LDA(At, 1, 0); G_STAGE(G_SA(0, 1), a2 + chA, cA0, qA);
;             G_WAIT_L(8); G_BAR; G_WAIT_L(0); G_MMA(0, 0, At, B0); G_BAR; G_SCHED;
;             G_LDB(B1, 1, 1); G_STAGE(G_SB(1, 0), b3, cB0, qB);
;             G_BAR; G_WAIT_L(0); G_MMA(0, 1, At, B1); G_BAR;
;             G_LDA(At, 1, 1); G_STAGE(G_SA(1, 0), a3, cA0, qA);
;             G_BAR; G_WAIT_L(0); G_MMA(1, 0, At, B0); G_BAR; G_SCHED;
;             G_STAGE(G_SB(1, 1), b3 + chB, cB0, qB);
;             G_WAIT_V(6); G_BAR; G_MMA(1, 1, At, B1); G_BAR;
.LBB0_890:
	s_add_u32 s4, s6, 0xfff50080
	s_addc_u32 s5, s7, -1
	s_add_i32 s19, 0, 0x10000
	v_add_u32_e32 v0, s19, v175
	ds_read_b128 v[136:139], v0
	ds_read_b128 v[140:143], v0 offset:1024
	ds_read_b128 v[144:147], v0 offset:2048
	ds_read_b128 v[148:151], v0 offset:3072
	s_cmp_eq_u32 s18, 4
	s_cselect_b32 s45, s15, s9
	s_cselect_b32 s44, s14, s8
	s_cselect_b32 s5, s13, s5
	s_cselect_b32 s4, s12, s4
	s_add_i32 m0, s22, 0xc000
	ds_read_b128 v[158:161], v176
	ds_read_b128 v[162:165], v176 offset:1024
	ds_read_b128 v[178:181], v176 offset:2048
	ds_read_b128 v[182:185], v176 offset:3072
	ds_read_b128 v[196:199], v176 offset:4096
	ds_read_b128 v[200:203], v176 offset:5120
	ds_read_b128 v[204:207], v176 offset:6144
	ds_read_b128 v[208:211], v176 offset:7168
	global_load_lds_dwordx4 v156, s[6:7]
	s_add_i32 m0, s22, 0xe000
	s_nop 0
	s_add_u32 vcc_lo, s6, s86
	s_addc_u32 vcc_hi, s7, s87
	global_load_lds_dwordx4 v156, vcc
	s_waitcnt lgkmcnt(8)
	s_cmp_eq_u32 s101, 1
	s_cbranch_scc1 .Ldb_MG1_sk
	s_barrier
.Ldb_MG1_sk:
	s_mov_b32 s101, 0
	s_waitcnt lgkmcnt(0)
	v_mfma_f32_16x16x32_bf16 v[104:107], v[136:139], v[158:161], v[104:107]
	v_mfma_f32_16x16x32_bf16 v[108:111], v[144:147], v[158:161], v[108:111]
	v_mfma_f32_16x16x32_bf16 v[132:135], v[136:139], v[178:181], v[132:135]
	v_mfma_f32_16x16x32_bf16 v[128:131], v[144:147], v[178:181], v[128:131]
	v_mfma_f32_16x16x32_bf16 v[124:127], v[136:139], v[196:199], v[124:127]
	v_mfma_f32_16x16x32_bf16 v[120:123], v[144:147], v[196:199], v[120:123]
	v_mfma_f32_16x16x32_bf16 v[116:119], v[136:139], v[204:207], v[116:119]
	v_mfma_f32_16x16x32_bf16 v[112:115], v[144:147], v[204:207], v[112:115]
	v_mfma_f32_16x16x32_bf16 v[104:107], v[140:143], v[162:165], v[104:107]
	v_mfma_f32_16x16x32_bf16 v[108:111], v[148:151], v[162:165], v[108:111]
	v_mfma_f32_16x16x32_bf16 v[132:135], v[140:143], v[182:185], v[132:135]
	v_mfma_f32_16x16x32_bf16 v[128:131], v[148:151], v[182:185], v[128:131]
	v_mfma_f32_16x16x32_bf16 v[124:127], v[140:143], v[200:203], v[124:127]
	v_mfma_f32_16x16x32_bf16 v[120:123], v[148:151], v[200:203], v[120:123]
	v_mfma_f32_16x16x32_bf16 v[116:119], v[140:143], v[208:211], v[116:119]
	v_mfma_f32_16x16x32_bf16 v[112:115], v[148:151], v[208:211], v[112:115]
	s_barrier
	s_add_i32 s43, 0, 0x14000
	s_add_i32 s19, s19, s21
	v_add_u32_e32 v0, s43, v175
	v_lshl_add_u64 v[2:3], s[44:45], 0, v[154:155]
	s_mov_b64 vcc, s[44:45]
	s_mov_b64 s[44:45], 0x10000
	s_mov_b32 m0, s19
	ds_read_b128 v[212:215], v0
	ds_read_b128 v[216:219], v0 offset:1024
	ds_read_b128 v[220:223], v0 offset:2048
	ds_read_b128 v[224:227], v0 offset:3072
	global_load_lds_dwordx4 v154, vcc
	v_lshl_add_u64 v[166:167], v[2:3], 0, s[44:45]
	s_add_i32 m0, s19, 0x2000
	s_nop 0
	global_load_lds_dwordx4 v[166:167], off
	s_barrier
	s_waitcnt lgkmcnt(0)
	v_mfma_f32_16x16x32_bf16 v[100:103], v[212:215], v[158:161], v[100:103]
	v_mfma_f32_16x16x32_bf16 v[96:99], v[220:223], v[158:161], v[96:99]
	v_mfma_f32_16x16x32_bf16 v[92:95], v[212:215], v[178:181], v[92:95]
	v_mfma_f32_16x16x32_bf16 v[88:91], v[220:223], v[178:181], v[88:91]
	v_mfma_f32_16x16x32_bf16 v[84:87], v[212:215], v[196:199], v[84:87]
	v_mfma_f32_16x16x32_bf16 v[80:83], v[220:223], v[196:199], v[80:83]
	v_mfma_f32_16x16x32_bf16 v[76:79], v[212:215], v[204:207], v[76:79]
	v_mfma_f32_16x16x32_bf16 v[72:75], v[220:223], v[204:207], v[72:75]
	v_mfma_f32_16x16x32_bf16 v[100:103], v[216:219], v[162:165], v[100:103]
	v_mfma_f32_16x16x32_bf16 v[96:99], v[224:227], v[162:165], v[96:99]
	v_mfma_f32_16x16x32_bf16 v[92:95], v[216:219], v[182:185], v[92:95]
	v_mfma_f32_16x16x32_bf16 v[88:91], v[224:227], v[182:185], v[88:91]
	v_mfma_f32_16x16x32_bf16 v[84:87], v[216:219], v[200:203], v[84:87]
	v_mfma_f32_16x16x32_bf16 v[80:83], v[224:227], v[200:203], v[80:83]
	v_mfma_f32_16x16x32_bf16 v[76:79], v[216:219], v[208:211], v[76:79]
	v_mfma_f32_16x16x32_bf16 v[72:75], v[224:227], v[208:211], v[72:75]
	s_barrier
	s_mov_b32 m0, s22
	v_lshl_add_u64 v[166:167], s[4:5], 0, v[152:153]
	ds_read_b128 v[158:161], v176 offset:16384
	ds_read_b128 v[162:165], v176 offset:17408
	ds_read_b128 v[178:181], v176 offset:18432
	ds_read_b128 v[182:185], v176 offset:19456
	ds_read_b128 v[196:199], v176 offset:20480
	ds_read_b128 v[200:203], v176 offset:21504
	ds_read_b128 v[204:207], v176 offset:22528
	ds_read_b128 v[208:211], v176 offset:23552
	global_load_lds_dwordx4 v152, s[4:5]
	s_mov_b32 m0, s23
	s_nop 0
	s_add_u32 vcc_lo, s4, s86
	s_addc_u32 vcc_hi, s5, s87
	global_load_lds_dwordx4 v152, vcc
	s_barrier
	s_waitcnt lgkmcnt(0)
	v_mfma_f32_16x16x32_bf16 v[68:71], v[136:139], v[158:161], v[68:71]
	v_mfma_f32_16x16x32_bf16 v[64:67], v[144:147], v[158:161], v[64:67]
	v_mfma_f32_16x16x32_bf16 v[60:63], v[136:139], v[178:181], v[60:63]
	v_mfma_f32_16x16x32_bf16 v[56:59], v[144:147], v[178:181], v[56:59]
	v_mfma_f32_16x16x32_bf16 v[52:55], v[136:139], v[196:199], v[52:55]
	v_mfma_f32_16x16x32_bf16 v[48:51], v[144:147], v[196:199], v[48:51]
	v_mfma_f32_16x16x32_bf16 v[44:47], v[136:139], v[204:207], v[44:47]
	v_mfma_f32_16x16x32_bf16 v[40:43], v[144:147], v[204:207], v[40:43]
	v_mfma_f32_16x16x32_bf16 v[68:71], v[140:143], v[162:165], v[68:71]
	v_mfma_f32_16x16x32_bf16 v[64:67], v[148:151], v[162:165], v[64:67]
	v_mfma_f32_16x16x32_bf16 v[60:63], v[140:143], v[182:185], v[60:63]
	v_mfma_f32_16x16x32_bf16 v[56:59], v[148:151], v[182:185], v[56:59]
	v_mfma_f32_16x16x32_bf16 v[52:55], v[140:143], v[200:203], v[52:55]
	v_mfma_f32_16x16x32_bf16 v[48:51], v[148:151], v[200:203], v[48:51]
	v_mfma_f32_16x16x32_bf16 v[44:47], v[140:143], v[208:211], v[44:47]
	v_mfma_f32_16x16x32_bf16 v[40:43], v[148:151], v[208:211], v[40:43]
	s_barrier
; #define G_STAGE(bufoff, gbase, o0, h64) do { \
;         __builtin_amdgcn_global_load_lds((const unsigned*)((const char*)(gbase) + (o0)), (LAS unsigned*)(lds + (bufoff) + ldsw), 16, 0, 0); \
;         __builtin_amdgcn_global_load_lds((const unsigned*)((const char*)(gbase) + (h64) + (o0)), (LAS unsigned*)(lds + (bufoff) + ldsw + 8192), 16, 0, 0); } while (0)
; #define G_LDA(dst, b, h) do { _Pragma("unroll") for (int m = 0; m < 4; ++m) _Pragma("unroll") for (int k = 0; k < 2; ++k) dst[m][k] = *(const LAS bf16x8*)(lds + G_SA(b, h) + aoff + m * 2048 + k * 1024); } while (0)
; #define G_LDB(dst, b, h) do { _Pragma("unroll") for (int n = 0; n < 2; ++n) _Pragma("unroll") for (int k = 0; k < 2; ++k) dst[n][k] = *(const LAS bf16x8*)(lds + G_SB(b, h) + boff + n * 2048 + k * 1024); } while (0)
; #define G_WAIT_V(n) asm volatile("s_waitcnt vmcnt(" #n ")" ::: "memory")
; #define G_BAR __builtin_amdgcn_s_barrier()
;     ...
;         for (int t = 0; t < nt; t += 2) {
;             const bool last = (t == nt - 2);
;             const char* a1 = cA + (size_t)(t + 1) * ckA;
;             const char* a2 = last ? nA : cA + (size_t)(t + 2) * ckA; const char* b2 = last ? nB : cB + (size_t)(t + 2) * kB;
;             const char* a3 = a2 + ckA; const char* b3 = b2 + kB;
;             G_LDB(B0, 0, 0); G_SCHED; G_LDA(At, 0, 0); G_STAGE(G_SA(1, 1), a1 + chA, cA0, qA);
;             G_WAIT_L(8); G_BAR; G_WAIT_L(0); G_MMA(0, 0, At, B0); G_BAR; G_SCHED;
;             G_LDB(B1, 0, 1); G_STAGE(G_SB(0, 0), b2, cB0, qB);
;             G_BAR; G_WAIT_L(0); G_MMA(0, 1, At, B1); G_BAR;
;             G_LDA(At, 0, 1); G_STAGE(G_SA(0, 0), a2, cA0, qA);
;             G_BAR; G_WAIT_L(0); G_MMA(1, 0, At, B0); G_BAR; G_SCHED;
;             G_STAGE(G_SB(0, 1), b2 + chB, cB0, qB);
;             G_WAIT_V(6); G_BAR; G_MMA(1, 1, At, B1); G_BAR;
;             G_LDB(B0, 1, 0); G_SCHED; G_LDA(At, 1, 0); G_STAGE(G_SA(0, 1), a2 + chA, cA0, qA);
;             G_WAIT_L(8); G_BAR; G_WAIT_L(0); G_MMA(0, 0, At, B0); G_BAR; G_SCHED;
;             G_LDB(B1, 1, 1); G_STAGE(G_SB(1, 0), b3, cB0, qB);
;             G_BAR; G_WAIT_L(0); G_MMA(0, 1, At, B1); G_BAR;
;             G_LDA(At, 1, 1); G_STAGE(G_SA(1, 0), a3, cA0, qA);
;             G_BAR; G_WAIT_L(0); G_MMA(1, 0, At, B0); G_BAR; G_SCHED;
;             G_STAGE(G_SB(1, 1), b3 + chB, cB0, qB);
;             G_WAIT_V(6); G_BAR; G_MMA(1, 1, At, B1); G_BAR;
	s_add_i32 s4, s43, s21
	v_lshl_add_u64 v[136:137], v[2:3], 0, s[0:1]
	s_mov_b32 m0, s4
	s_nop 0
	global_load_lds_dwordx4 v[136:137], off
	v_lshl_add_u64 v[136:137], v[2:3], 0, s[52:53]
	s_add_i32 m0, s4, 0x2000
	s_nop 0
	global_load_lds_dwordx4 v[136:137], off
	s_waitcnt vmcnt(6)
	s_barrier
	v_mfma_f32_16x16x32_bf16 v[36:39], v[212:215], v[158:161], v[36:39]
	v_mfma_f32_16x16x32_bf16 v[32:35], v[220:223], v[158:161], v[32:35]
	v_mfma_f32_16x16x32_bf16 v[28:31], v[212:215], v[178:181], v[28:31]
	v_mfma_f32_16x16x32_bf16 v[24:27], v[220:223], v[178:181], v[24:27]
	v_mfma_f32_16x16x32_bf16 v[20:23], v[212:215], v[196:199], v[20:23]
	v_mfma_f32_16x16x32_bf16 v[16:19], v[220:223], v[196:199], v[16:19]
	v_mfma_f32_16x16x32_bf16 v[12:15], v[212:215], v[204:207], v[12:15]
	v_mfma_f32_16x16x32_bf16 v[8:11], v[220:223], v[204:207], v[8:11]
	v_mfma_f32_16x16x32_bf16 v[36:39], v[216:219], v[162:165], v[36:39]
	v_mfma_f32_16x16x32_bf16 v[32:35], v[224:227], v[162:165], v[32:35]
	v_mfma_f32_16x16x32_bf16 v[28:31], v[216:219], v[182:185], v[28:31]
	v_mfma_f32_16x16x32_bf16 v[24:27], v[224:227], v[182:185], v[24:27]
	v_mfma_f32_16x16x32_bf16 v[20:23], v[216:219], v[200:203], v[20:23]
	v_mfma_f32_16x16x32_bf16 v[16:19], v[224:227], v[200:203], v[16:19]
	v_mfma_f32_16x16x32_bf16 v[12:15], v[216:219], v[208:211], v[12:15]
	v_mfma_f32_16x16x32_bf16 v[8:11], v[224:227], v[208:211], v[8:11]
	s_barrier
	s_add_i32 s4, 0, 0x18000
	v_add_u32_e32 v0, s4, v175
	ds_read_b128 v[136:139], v0
	ds_read_b128 v[140:143], v0 offset:1024
	ds_read_b128 v[144:147], v0 offset:2048
	ds_read_b128 v[148:151], v0 offset:3072
	s_mov_b32 m0, s24
	v_lshl_add_u64 v[172:173], v[166:167], 0, s[88:89]
	ds_read_b128 v[158:161], v176 offset:32768
	ds_read_b128 v[162:165], v176 offset:33792
	ds_read_b128 v[178:181], v176 offset:34816
	ds_read_b128 v[182:185], v176 offset:35840
	ds_read_b128 v[196:199], v176 offset:36864
	ds_read_b128 v[200:203], v176 offset:37888
	ds_read_b128 v[204:207], v176 offset:38912
	ds_read_b128 v[208:211], v176 offset:39936
	global_load_lds_dwordx4 v[172:173], off
	v_lshl_add_u64 v[172:173], v[166:167], 0, s[64:65]
	s_mov_b32 m0, s25
	s_nop 0
	global_load_lds_dwordx4 v[172:173], off
	s_waitcnt lgkmcnt(8)
	s_barrier
	s_waitcnt lgkmcnt(0)
	v_mfma_f32_16x16x32_bf16 v[104:107], v[136:139], v[158:161], v[104:107]
	v_mfma_f32_16x16x32_bf16 v[108:111], v[144:147], v[158:161], v[108:111]
	v_mfma_f32_16x16x32_bf16 v[132:135], v[136:139], v[178:181], v[132:135]
	v_mfma_f32_16x16x32_bf16 v[128:131], v[144:147], v[178:181], v[128:131]
	v_mfma_f32_16x16x32_bf16 v[124:127], v[136:139], v[196:199], v[124:127]
	v_mfma_f32_16x16x32_bf16 v[120:123], v[144:147], v[196:199], v[120:123]
	v_mfma_f32_16x16x32_bf16 v[116:119], v[136:139], v[204:207], v[116:119]
	v_mfma_f32_16x16x32_bf16 v[112:115], v[144:147], v[204:207], v[112:115]
	v_mfma_f32_16x16x32_bf16 v[104:107], v[140:143], v[162:165], v[104:107]
	v_mfma_f32_16x16x32_bf16 v[108:111], v[148:151], v[162:165], v[108:111]
	v_mfma_f32_16x16x32_bf16 v[132:135], v[140:143], v[182:185], v[132:135]
	v_mfma_f32_16x16x32_bf16 v[128:131], v[148:151], v[182:185], v[128:131]
	v_mfma_f32_16x16x32_bf16 v[124:127], v[140:143], v[200:203], v[124:127]
	v_mfma_f32_16x16x32_bf16 v[120:123], v[148:151], v[200:203], v[120:123]
	v_mfma_f32_16x16x32_bf16 v[116:119], v[140:143], v[208:211], v[116:119]
	v_mfma_f32_16x16x32_bf16 v[112:115], v[148:151], v[208:211], v[112:115]
	s_barrier
	s_add_i32 s5, 0, 0x1c000
	s_add_i32 s4, s4, s21
	v_add_u32_e32 v0, s5, v175
	v_lshl_add_u64 v[172:173], v[2:3], 0, s[46:47]
	s_mov_b32 m0, s4
	ds_read_b128 v[212:215], v0
	ds_read_b128 v[216:219], v0 offset:1024
	ds_read_b128 v[220:223], v0 offset:2048
	ds_read_b128 v[224:227], v0 offset:3072
	global_load_lds_dwordx4 v[172:173], off
	v_lshl_add_u64 v[172:173], v[2:3], 0, s[54:55]
	s_add_i32 m0, s4, 0x2000
	s_nop 0
	global_load_lds_dwordx4 v[172:173], off
	s_barrier
; #define G_STAGE(bufoff, gbase, o0, h64) do { \
;         __builtin_amdgcn_global_load_lds((const unsigned*)((const char*)(gbase) + (o0)), (LAS unsigned*)(lds + (bufoff) + ldsw), 16, 0, 0); \
;         __builtin_amdgcn_global_load_lds((const unsigned*)((const char*)(gbase) + (h64) + (o0)), (LAS unsigned*)(lds + (bufoff) + ldsw + 8192), 16, 0, 0); } while (0)
; #define G_LDA(dst, b, h) do { _Pragma("unroll") for (int m = 0; m < 4; ++m) _Pragma("unroll") for (int k = 0; k < 2; ++k) dst[m][k] = *(const LAS bf16x8*)(lds + G_SA(b, h) + aoff + m * 2048 + k * 1024); } while (0)
; #define G_LDB(dst, b, h) do { _Pragma("unroll") for (int n = 0; n < 2; ++n) _Pragma("unroll") for (int k = 0; k < 2; ++k) dst[n][k] = *(const LAS bf16x8*)(lds + G_SB(b, h) + boff + n * 2048 + k * 1024); } while (0)
; #define G_WAIT_V(n) asm volatile("s_waitcnt vmcnt(" #n ")" ::: "memory")
; #define G_BAR __builtin_amdgcn_s_barrier()
;     ...
;         for (int t = 0; t < nt; t += 2) {
;             const bool last = (t == nt - 2);
;             const char* a1 = cA + (size_t)(t + 1) * ckA;
;             const char* a2 = last ? nA : cA + (size_t)(t + 2) * ckA; const char* b2 = last ? nB : cB + (size_t)(t + 2) * kB;
;             const char* a3 = a2 + ckA; const char* b3 = b2 + kB;
;             G_LDB(B0, 0, 0); G_SCHED; G_LDA(At, 0, 0); G_STAGE(G_SA(1, 1), a1 + chA, cA0, qA);
;             G_WAIT_L(8); G_BAR; G_WAIT_L(0); G_MMA(0, 0, At, B0); G_BAR; G_SCHED;
;             G_LDB(B1, 0, 1); G_STAGE(G_SB(0, 0), b2, cB0, qB);
;             G_BAR; G_WAIT_L(0); G_MMA(0, 1, At, B1); G_BAR;
;             G_LDA(At, 0, 1); G_STAGE(G_SA(0, 0), a2, cA0, qA);
;             G_BAR; G_WAIT_L(0); G_MMA(1, 0, At, B0); G_BAR; G_SCHED;
;             G_STAGE(G_SB(0, 1), b2 + chB, cB0, qB);
;             G_WAIT_V(6); G_BAR; G_MMA(1, 1, At, B1); G_BAR;
;             G_LDB(B0, 1, 0); G_SCHED; G_LDA(At, 1, 0); G_STAGE(G_SA(0, 1), a2 + chA, cA0, qA);
;             G_WAIT_L(8); G_BAR; G_WAIT_L(0); G_MMA(0, 0, At, B0); G_BAR; G_SCHED;
;             G_LDB(B1, 1, 1); G_STAGE(G_SB(1, 0), b3, cB0, qB);
;             G_BAR; G_WAIT_L(0); G_MMA(0, 1, At, B1); G_BAR;
;             G_LDA(At, 1, 1); G_STAGE(G_SA(1, 0), a3, cA0, qA);
;             G_BAR; G_WAIT_L(0); G_MMA(1, 0, At, B0); G_BAR; G_SCHED;
;             G_STAGE(G_SB(1, 1), b3 + chB, cB0, qB);
;             G_WAIT_V(6); G_BAR; G_MMA(1, 1, At, B1); G_BAR;
	s_waitcnt lgkmcnt(0)
	v_mfma_f32_16x16x32_bf16 v[100:103], v[212:215], v[158:161], v[100:103]
	v_mfma_f32_16x16x32_bf16 v[96:99], v[220:223], v[158:161], v[96:99]
	v_mfma_f32_16x16x32_bf16 v[92:95], v[212:215], v[178:181], v[92:95]
	v_mfma_f32_16x16x32_bf16 v[88:91], v[220:223], v[178:181], v[88:91]
	v_mfma_f32_16x16x32_bf16 v[84:87], v[212:215], v[196:199], v[84:87]
	v_mfma_f32_16x16x32_bf16 v[80:83], v[220:223], v[196:199], v[80:83]
	v_mfma_f32_16x16x32_bf16 v[76:79], v[212:215], v[204:207], v[76:79]
	v_mfma_f32_16x16x32_bf16 v[72:75], v[220:223], v[204:207], v[72:75]
	v_mfma_f32_16x16x32_bf16 v[100:103], v[216:219], v[162:165], v[100:103]
	v_mfma_f32_16x16x32_bf16 v[96:99], v[224:227], v[162:165], v[96:99]
	v_mfma_f32_16x16x32_bf16 v[92:95], v[216:219], v[182:185], v[92:95]
	v_mfma_f32_16x16x32_bf16 v[88:91], v[224:227], v[182:185], v[88:91]
	v_mfma_f32_16x16x32_bf16 v[84:87], v[216:219], v[200:203], v[84:87]
	v_mfma_f32_16x16x32_bf16 v[80:83], v[224:227], v[200:203], v[80:83]
	v_mfma_f32_16x16x32_bf16 v[76:79], v[216:219], v[208:211], v[76:79]
	v_mfma_f32_16x16x32_bf16 v[72:75], v[224:227], v[208:211], v[72:75]
	s_barrier
	s_mov_b32 m0, s26
	v_lshl_add_u64 v[172:173], v[166:167], 0, s[46:47]
	ds_read_b128 v[158:161], v176 offset:49152
	ds_read_b128 v[162:165], v176 offset:50176
	ds_read_b128 v[178:181], v176 offset:51200
	ds_read_b128 v[182:185], v176 offset:52224
	ds_read_b128 v[196:199], v176 offset:53248
	ds_read_b128 v[200:203], v176 offset:54272
	ds_read_b128 v[204:207], v176 offset:55296
	ds_read_b128 v[208:211], v176 offset:56320
	global_load_lds_dwordx4 v[172:173], off
	v_lshl_add_u64 v[166:167], v[166:167], 0, s[66:67]
	s_mov_b32 m0, s27
	s_nop 0
	global_load_lds_dwordx4 v[166:167], off
	s_barrier
	s_waitcnt lgkmcnt(0)
	v_mfma_f32_16x16x32_bf16 v[68:71], v[136:139], v[158:161], v[68:71]
	v_mfma_f32_16x16x32_bf16 v[64:67], v[144:147], v[158:161], v[64:67]
	v_mfma_f32_16x16x32_bf16 v[60:63], v[136:139], v[178:181], v[60:63]
	v_mfma_f32_16x16x32_bf16 v[56:59], v[144:147], v[178:181], v[56:59]
	v_mfma_f32_16x16x32_bf16 v[52:55], v[136:139], v[196:199], v[52:55]
	v_mfma_f32_16x16x32_bf16 v[48:51], v[144:147], v[196:199], v[48:51]
	v_mfma_f32_16x16x32_bf16 v[44:47], v[136:139], v[204:207], v[44:47]
	v_mfma_f32_16x16x32_bf16 v[40:43], v[144:147], v[204:207], v[40:43]
	v_mfma_f32_16x16x32_bf16 v[68:71], v[140:143], v[162:165], v[68:71]
	v_mfma_f32_16x16x32_bf16 v[64:67], v[148:151], v[162:165], v[64:67]
	v_mfma_f32_16x16x32_bf16 v[60:63], v[140:143], v[182:185], v[60:63]
	v_mfma_f32_16x16x32_bf16 v[56:59], v[148:151], v[182:185], v[56:59]
	v_mfma_f32_16x16x32_bf16 v[52:55], v[140:143], v[200:203], v[52:55]
	v_mfma_f32_16x16x32_bf16 v[48:51], v[148:151], v[200:203], v[48:51]
	v_mfma_f32_16x16x32_bf16 v[44:47], v[140:143], v[208:211], v[44:47]
	v_mfma_f32_16x16x32_bf16 v[40:43], v[148:151], v[208:211], v[40:43]
	s_barrier
	s_add_i32 s4, s5, s21
	v_lshl_add_u64 v[136:137], v[2:3], 0, s[50:51]
	s_mov_b32 m0, s4
	v_lshl_add_u64 v[2:3], v[2:3], 0, s[58:59]
	global_load_lds_dwordx4 v[136:137], off
	s_add_i32 m0, s4, 0x2000
	s_nop 0
	global_load_lds_dwordx4 v[2:3], off
	s_add_i32 s18, s18, 2
	s_add_u32 s6, s6, 0x100
	s_addc_u32 s7, s7, 0
	s_add_u32 s8, s8, 0x100
	s_addc_u32 s9, s9, 0
	s_cmp_gt_u32 s18, 5
	s_waitcnt vmcnt(6)
	s_barrier
	v_mfma_f32_16x16x32_bf16 v[36:39], v[212:215], v[158:161], v[36:39]
	v_mfma_f32_16x16x32_bf16 v[32:35], v[220:223], v[158:161], v[32:35]
	v_mfma_f32_16x16x32_bf16 v[28:31], v[212:215], v[178:181], v[28:31]
	v_mfma_f32_16x16x32_bf16 v[24:27], v[220:223], v[178:181], v[24:27]
	v_mfma_f32_16x16x32_bf16 v[20:23], v[212:215], v[196:199], v[20:23]
	v_mfma_f32_16x16x32_bf16 v[16:19], v[220:223], v[196:199], v[16:19]
	v_mfma_f32_16x16x32_bf16 v[12:15], v[212:215], v[204:207], v[12:15]
	v_mfma_f32_16x16x32_bf16 v[8:11], v[220:223], v[204:207], v[8:11]
	v_mfma_f32_16x16x32_bf16 v[36:39], v[216:219], v[162:165], v[36:39]
	v_mfma_f32_16x16x32_bf16 v[32:35], v[224:227], v[162:165], v[32:35]
	v_mfma_f32_16x16x32_bf16 v[28:31], v[216:219], v[182:185], v[28:31]
	v_mfma_f32_16x16x32_bf16 v[24:27], v[224:227], v[182:185], v[24:27]
	v_mfma_f32_16x16x32_bf16 v[20:23], v[216:219], v[200:203], v[20:23]
	v_mfma_f32_16x16x32_bf16 v[16:19], v[224:227], v[200:203], v[16:19]
	v_mfma_f32_16x16x32_bf16 v[12:15], v[216:219], v[208:211], v[12:15]
	v_mfma_f32_16x16x32_bf16 v[8:11], v[224:227], v[208:211], v[8:11]
	s_cbranch_scc0 .Ldb_MG1_cont
	v_readfirstlane_b32 s101, v186
	s_cmpk_gt_u32 s101, 0xff
	s_cbranch_scc1 .Ldb_MG1_young
	s_barrier
	s_mov_b32 s101, 1
	s_branch .Ldb_MG1_exit

; #define G_STAGE(bufoff, gbase, o0, h64) do { \
;         __builtin_amdgcn_global_load_lds((const unsigned*)((const char*)(gbase) + (o0)), (LAS unsigned*)(lds + (bufoff) + ldsw), 16, 0, 0); \
;         __builtin_amdgcn_global_load_lds((const unsigned*)((const char*)(gbase) + (h64) + (o0)), (LAS unsigned*)(lds + (bufoff) + ldsw + 8192), 16, 0, 0); } while (0)
; #define G_LDA(dst, b, h) do { _Pragma("unroll") for (int m = 0; m < 4; ++m) _Pragma("unroll") for (int k = 0; k < 2; ++k) dst[m][k] = *(const LAS bf16x8*)(lds + G_SA(b, h) + aoff + m * 2048 + k * 1024); } while (0)
; #define G_LDB(dst, b, h) do { _Pragma("unroll") for (int n = 0; n < 2; ++n) _Pragma("unroll") for (int k = 0; k < 2; ++k) dst[n][k] = *(const LAS bf16x8*)(lds + G_SB(b, h) + boff + n * 2048 + k * 1024); } while (0)
; #define G_WAIT_V(n) asm volatile("s_waitcnt vmcnt(" #n ")" ::: "memory")
; #define G_BAR __builtin_amdgcn_s_barrier()
;     ...
;         for (int t = 0; t < nt; t += 2) {
;             const bool last = (t == nt - 2);
;             const char* a1 = cA + (size_t)(t + 1) * ckA;
;             const char* a2 = last ? nA : cA + (size_t)(t + 2) * ckA; const char* b2 = last ? nB : cB + (size_t)(t + 2) * kB;
;             const char* a3 = a2 + ckA; const char* b3 = b2 + kB;
;             G_LDB(B0, 0, 0); G_SCHED; G_LDA(At, 0, 0); G_STAGE(G_SA(1, 1), a1 + chA, cA0, qA);
;             G_WAIT_L(8); G_BAR; G_WAIT_L(0); G_MMA(0, 0, At, B0); G_BAR; G_SCHED;
;             G_LDB(B1, 0, 1); G_STAGE(G_SB(0, 0), b2, cB0, qB);
;             G_BAR; G_WAIT_L(0); G_MMA(0, 1, At, B1); G_BAR;
;             G_LDA(At, 0, 1); G_STAGE(G_SA(0, 0), a2, cA0, qA);
;             G_BAR; G_WAIT_L(0); G_MMA(1, 0, At, B0); G_BAR; G_SCHED;
;             G_STAGE(G_SB(0, 1), b2 + chB, cB0, qB);
;             G_WAIT_V(6); G_BAR; G_MMA(1, 1, At, B1); G_BAR;
;             G_LDB(B0, 1, 0); G_SCHED; G_LDA(At, 1, 0); G_STAGE(G_SA(0, 1), a2 + chA, cA0, qA);
;             G_WAIT_L(8); G_BAR; G_WAIT_L(0); G_MMA(0, 0, At, B0); G_BAR; G_SCHED;
;             G_LDB(B1, 1, 1); G_STAGE(G_SB(1, 0), b3, cB0, qB);
;             G_BAR; G_WAIT_L(0); G_MMA(0, 1, At, B1); G_BAR;
;             G_LDA(At, 1, 1); G_STAGE(G_SA(1, 0), a3, cA0, qA);
;             G_BAR; G_WAIT_L(0); G_MMA(1, 0, At, B0); G_BAR; G_SCHED;
;             G_STAGE(G_SB(1, 1), b3 + chB, cB0, qB);
;             G_WAIT_V(6); G_BAR; G_MMA(1, 1, At, B1); G_BAR;
.LBB0_1037:
	s_add_u32 s4, s2, 0xfffc0080
	s_addc_u32 s5, s3, -1
	s_add_i32 s33, 0, 0x10000
	v_add_u32_e32 v0, s33, v181
	ds_read_b128 v[136:139], v0
	ds_read_b128 v[140:143], v0 offset:1024
	ds_read_b128 v[144:147], v0 offset:2048
	ds_read_b128 v[148:151], v0 offset:3072
	s_cmp_eq_u32 s15, 12
	s_cselect_b32 s5, s17, s5
	s_cselect_b32 s4, s16, s4
	s_cselect_b32 s21, s19, s7
	s_cselect_b32 s20, s18, s6
	s_add_i32 m0, s24, 0xc000
	ds_read_b128 v[152:155], v182
	ds_read_b128 v[156:159], v182 offset:1024
	ds_read_b128 v[160:163], v182 offset:2048
	ds_read_b128 v[172:175], v182 offset:3072
	ds_read_b128 v[176:179], v182 offset:4096
	ds_read_b128 v[196:199], v182 offset:5120
	ds_read_b128 v[200:203], v182 offset:6144
	ds_read_b128 v[204:207], v182 offset:7168
	global_load_lds_dwordx4 v166, s[2:3]
	s_add_i32 m0, s24, 0xe000
	s_nop 0
	s_add_u32 vcc_lo, s2, s0
	s_addc_u32 vcc_hi, s3, s1
	global_load_lds_dwordx4 v166, vcc
	s_waitcnt lgkmcnt(8)
	s_cmp_eq_u32 s101, 1
	s_cbranch_scc1 .Ldb_WOUT_sk
	s_barrier
.Ldb_WOUT_sk:
	s_mov_b32 s101, 0
	s_waitcnt lgkmcnt(0)
	v_mfma_f32_16x16x32_bf16 v[132:135], v[136:139], v[152:155], v[132:135]
	v_mfma_f32_16x16x32_bf16 v[128:131], v[144:147], v[152:155], v[128:131]
	v_mfma_f32_16x16x32_bf16 v[116:119], v[136:139], v[160:163], v[116:119]
	v_mfma_f32_16x16x32_bf16 v[112:115], v[144:147], v[160:163], v[112:115]
	v_mfma_f32_16x16x32_bf16 v[100:103], v[136:139], v[176:179], v[100:103]
	v_mfma_f32_16x16x32_bf16 v[96:99], v[144:147], v[176:179], v[96:99]
	v_mfma_f32_16x16x32_bf16 v[84:87], v[136:139], v[200:203], v[84:87]
	v_mfma_f32_16x16x32_bf16 v[80:83], v[144:147], v[200:203], v[80:83]
	v_mfma_f32_16x16x32_bf16 v[132:135], v[140:143], v[156:159], v[132:135]
	v_mfma_f32_16x16x32_bf16 v[128:131], v[148:151], v[156:159], v[128:131]
	v_mfma_f32_16x16x32_bf16 v[116:119], v[140:143], v[172:175], v[116:119]
	v_mfma_f32_16x16x32_bf16 v[112:115], v[148:151], v[172:175], v[112:115]
	v_mfma_f32_16x16x32_bf16 v[100:103], v[140:143], v[196:199], v[100:103]
	v_mfma_f32_16x16x32_bf16 v[96:99], v[148:151], v[196:199], v[96:99]
	v_mfma_f32_16x16x32_bf16 v[84:87], v[140:143], v[204:207], v[84:87]
	v_mfma_f32_16x16x32_bf16 v[80:83], v[148:151], v[204:207], v[80:83]
	s_barrier
	s_add_i32 s41, 0, 0x14000
	s_add_i32 s100, s33, s23
	v_add_u32_e32 v0, s41, v181
	s_mov_b32 m0, s100
	ds_read_b128 v[208:211], v0
	ds_read_b128 v[212:215], v0 offset:1024
	ds_read_b128 v[216:219], v0 offset:2048
	ds_read_b128 v[220:223], v0 offset:3072
	global_load_lds_dwordx4 v164, s[20:21]
	s_add_i32 m0, s100, 0x2000
	s_nop 0
	s_add_u32 vcc_lo, s20, s0
	s_addc_u32 vcc_hi, s21, s1
	global_load_lds_dwordx4 v164, vcc
	s_barrier
	s_waitcnt lgkmcnt(0)
	v_mfma_f32_16x16x32_bf16 v[124:127], v[208:211], v[152:155], v[124:127]
	v_mfma_f32_16x16x32_bf16 v[120:123], v[216:219], v[152:155], v[120:123]
	v_mfma_f32_16x16x32_bf16 v[108:111], v[208:211], v[160:163], v[108:111]
	v_mfma_f32_16x16x32_bf16 v[104:107], v[216:219], v[160:163], v[104:107]
	v_mfma_f32_16x16x32_bf16 v[92:95], v[208:211], v[176:179], v[92:95]
	v_mfma_f32_16x16x32_bf16 v[88:91], v[216:219], v[176:179], v[88:91]
	v_mfma_f32_16x16x32_bf16 v[76:79], v[208:211], v[200:203], v[76:79]
	v_mfma_f32_16x16x32_bf16 v[72:75], v[216:219], v[200:203], v[72:75]
	v_mfma_f32_16x16x32_bf16 v[124:127], v[212:215], v[156:159], v[124:127]
	v_mfma_f32_16x16x32_bf16 v[120:123], v[220:223], v[156:159], v[120:123]
	v_mfma_f32_16x16x32_bf16 v[108:111], v[212:215], v[172:175], v[108:111]
	v_mfma_f32_16x16x32_bf16 v[104:107], v[220:223], v[172:175], v[104:107]
	v_mfma_f32_16x16x32_bf16 v[92:95], v[212:215], v[196:199], v[92:95]
	v_mfma_f32_16x16x32_bf16 v[88:91], v[220:223], v[196:199], v[88:91]
	v_mfma_f32_16x16x32_bf16 v[76:79], v[212:215], v[204:207], v[76:79]
	v_mfma_f32_16x16x32_bf16 v[72:75], v[220:223], v[204:207], v[72:75]
	s_barrier
	s_mov_b32 m0, s24
	v_lshl_add_u64 v[224:225], s[4:5], 0, v[2:3]
	ds_read_b128 v[152:155], v182 offset:16384
	ds_read_b128 v[156:159], v182 offset:17408
	ds_read_b128 v[160:163], v182 offset:18432
	ds_read_b128 v[172:175], v182 offset:19456
	ds_read_b128 v[176:179], v182 offset:20480
	ds_read_b128 v[196:199], v182 offset:21504
	ds_read_b128 v[200:203], v182 offset:22528
	ds_read_b128 v[204:207], v182 offset:23552
	global_load_lds_dwordx4 v2, s[4:5]
	s_mov_b32 m0, s25
	s_nop 0
	s_add_u32 vcc_lo, s4, s0
	s_addc_u32 vcc_hi, s5, s1
	global_load_lds_dwordx4 v2, vcc
	s_barrier
	s_waitcnt lgkmcnt(0)
	v_mfma_f32_16x16x32_bf16 v[68:71], v[136:139], v[152:155], v[68:71]
	v_mfma_f32_16x16x32_bf16 v[64:67], v[144:147], v[152:155], v[64:67]
	v_mfma_f32_16x16x32_bf16 v[52:55], v[136:139], v[160:163], v[52:55]
	v_mfma_f32_16x16x32_bf16 v[48:51], v[144:147], v[160:163], v[48:51]
	v_mfma_f32_16x16x32_bf16 v[36:39], v[136:139], v[176:179], v[36:39]
	v_mfma_f32_16x16x32_bf16 v[32:35], v[144:147], v[176:179], v[32:35]
	v_mfma_f32_16x16x32_bf16 v[20:23], v[136:139], v[200:203], v[20:23]
	v_mfma_f32_16x16x32_bf16 v[16:19], v[144:147], v[200:203], v[16:19]
	v_mfma_f32_16x16x32_bf16 v[68:71], v[140:143], v[156:159], v[68:71]
	v_mfma_f32_16x16x32_bf16 v[64:67], v[148:151], v[156:159], v[64:67]
	v_mfma_f32_16x16x32_bf16 v[52:55], v[140:143], v[172:175], v[52:55]
	v_mfma_f32_16x16x32_bf16 v[48:51], v[148:151], v[172:175], v[48:51]
	v_mfma_f32_16x16x32_bf16 v[36:39], v[140:143], v[196:199], v[36:39]
	v_mfma_f32_16x16x32_bf16 v[32:35], v[148:151], v[196:199], v[32:35]
	v_mfma_f32_16x16x32_bf16 v[20:23], v[140:143], v[204:207], v[20:23]
	v_mfma_f32_16x16x32_bf16 v[16:19], v[148:151], v[204:207], v[16:19]
	s_barrier
; #define G_STAGE(bufoff, gbase, o0, h64) do { \
;         __builtin_amdgcn_global_load_lds((const unsigned*)((const char*)(gbase) + (o0)), (LAS unsigned*)(lds + (bufoff) + ldsw), 16, 0, 0); \
;         __builtin_amdgcn_global_load_lds((const unsigned*)((const char*)(gbase) + (h64) + (o0)), (LAS unsigned*)(lds + (bufoff) + ldsw + 8192), 16, 0, 0); } while (0)
; #define G_LDA(dst, b, h) do { _Pragma("unroll") for (int m = 0; m < 4; ++m) _Pragma("unroll") for (int k = 0; k < 2; ++k) dst[m][k] = *(const LAS bf16x8*)(lds + G_SA(b, h) + aoff + m * 2048 + k * 1024); } while (0)
; #define G_LDB(dst, b, h) do { _Pragma("unroll") for (int n = 0; n < 2; ++n) _Pragma("unroll") for (int k = 0; k < 2; ++k) dst[n][k] = *(const LAS bf16x8*)(lds + G_SB(b, h) + boff + n * 2048 + k * 1024); } while (0)
; #define G_WAIT_V(n) asm volatile("s_waitcnt vmcnt(" #n ")" ::: "memory")
; #define G_BAR __builtin_amdgcn_s_barrier()
;     ...
;         for (int t = 0; t < nt; t += 2) {
;             const bool last = (t == nt - 2);
;             const char* a1 = cA + (size_t)(t + 1) * ckA;
;             const char* a2 = last ? nA : cA + (size_t)(t + 2) * ckA; const char* b2 = last ? nB : cB + (size_t)(t + 2) * kB;
;             const char* a3 = a2 + ckA; const char* b3 = b2 + kB;
;             G_LDB(B0, 0, 0); G_SCHED; G_LDA(At, 0, 0); G_STAGE(G_SA(1, 1), a1 + chA, cA0, qA);
;             G_WAIT_L(8); G_BAR; G_WAIT_L(0); G_MMA(0, 0, At, B0); G_BAR; G_SCHED;
;             G_LDB(B1, 0, 1); G_STAGE(G_SB(0, 0), b2, cB0, qB);
;             G_BAR; G_WAIT_L(0); G_MMA(0, 1, At, B1); G_BAR;
;             G_LDA(At, 0, 1); G_STAGE(G_SA(0, 0), a2, cA0, qA);
;             G_BAR; G_WAIT_L(0); G_MMA(1, 0, At, B0); G_BAR; G_SCHED;
;             G_STAGE(G_SB(0, 1), b2 + chB, cB0, qB);
;             G_WAIT_V(6); G_BAR; G_MMA(1, 1, At, B1); G_BAR;
;             G_LDB(B0, 1, 0); G_SCHED; G_LDA(At, 1, 0); G_STAGE(G_SA(0, 1), a2 + chA, cA0, qA);
;             G_WAIT_L(8); G_BAR; G_WAIT_L(0); G_MMA(0, 0, At, B0); G_BAR; G_SCHED;
;             G_LDB(B1, 1, 1); G_STAGE(G_SB(1, 0), b3, cB0, qB);
;             G_BAR; G_WAIT_L(0); G_MMA(0, 1, At, B1); G_BAR;
;             G_LDA(At, 1, 1); G_STAGE(G_SA(1, 0), a3, cA0, qA);
;             G_BAR; G_WAIT_L(0); G_MMA(1, 0, At, B0); G_BAR; G_SCHED;
;             G_STAGE(G_SB(1, 1), b3 + chB, cB0, qB);
;             G_WAIT_V(6); G_BAR; G_MMA(1, 1, At, B1); G_BAR;
	s_add_i32 s100, s41, s23
	s_mov_b32 m0, s100
	s_nop 0
	s_add_u32 vcc_lo, s20, s42
	s_addc_u32 vcc_hi, s21, s43
	global_load_lds_dwordx4 v164, vcc
	s_add_i32 m0, s100, 0x2000
	s_nop 0
	s_add_u32 vcc_lo, s20, s50
	s_addc_u32 vcc_hi, s21, s51
	global_load_lds_dwordx4 v164, vcc
	s_waitcnt vmcnt(6)
	s_barrier
	v_mfma_f32_16x16x32_bf16 v[60:63], v[208:211], v[152:155], v[60:63]
	v_mfma_f32_16x16x32_bf16 v[56:59], v[216:219], v[152:155], v[56:59]
	v_mfma_f32_16x16x32_bf16 v[44:47], v[208:211], v[160:163], v[44:47]
	v_mfma_f32_16x16x32_bf16 v[40:43], v[216:219], v[160:163], v[40:43]
	v_mfma_f32_16x16x32_bf16 v[28:31], v[208:211], v[176:179], v[28:31]
	v_mfma_f32_16x16x32_bf16 v[24:27], v[216:219], v[176:179], v[24:27]
	v_mfma_f32_16x16x32_bf16 v[12:15], v[208:211], v[200:203], v[12:15]
	v_mfma_f32_16x16x32_bf16 v[8:11], v[216:219], v[200:203], v[8:11]
	v_mfma_f32_16x16x32_bf16 v[60:63], v[212:215], v[156:159], v[60:63]
	v_mfma_f32_16x16x32_bf16 v[56:59], v[220:223], v[156:159], v[56:59]
	v_mfma_f32_16x16x32_bf16 v[44:47], v[212:215], v[172:175], v[44:47]
	v_mfma_f32_16x16x32_bf16 v[40:43], v[220:223], v[172:175], v[40:43]
	v_mfma_f32_16x16x32_bf16 v[28:31], v[212:215], v[196:199], v[28:31]
	v_mfma_f32_16x16x32_bf16 v[24:27], v[220:223], v[196:199], v[24:27]
	v_mfma_f32_16x16x32_bf16 v[12:15], v[212:215], v[204:207], v[12:15]
	v_mfma_f32_16x16x32_bf16 v[8:11], v[220:223], v[204:207], v[8:11]
	s_barrier
	s_add_i32 s100, 0, 0x18000
	v_add_u32_e32 v0, s100, v181
	ds_read_b128 v[136:139], v0
	ds_read_b128 v[140:143], v0 offset:1024
	ds_read_b128 v[144:147], v0 offset:2048
	ds_read_b128 v[148:151], v0 offset:3072
	s_mov_b32 m0, s26
	ds_read_b128 v[152:155], v182 offset:32768
	ds_read_b128 v[156:159], v182 offset:33792
	ds_read_b128 v[160:163], v182 offset:34816
	ds_read_b128 v[172:175], v182 offset:35840
	ds_read_b128 v[176:179], v182 offset:36864
	ds_read_b128 v[196:199], v182 offset:37888
	ds_read_b128 v[200:203], v182 offset:38912
	ds_read_b128 v[204:207], v182 offset:39936
	s_add_u32 vcc_lo, s4, s42
	s_addc_u32 vcc_hi, s5, s43
	global_load_lds_dwordx4 v2, vcc
	s_mov_b32 m0, s27
	s_nop 0
	s_add_u32 vcc_lo, s4, s50
	s_addc_u32 vcc_hi, s5, s51
	global_load_lds_dwordx4 v2, vcc
	s_waitcnt lgkmcnt(8)
	s_barrier
	s_waitcnt lgkmcnt(0)
	v_mfma_f32_16x16x32_bf16 v[132:135], v[136:139], v[152:155], v[132:135]
	v_mfma_f32_16x16x32_bf16 v[128:131], v[144:147], v[152:155], v[128:131]
	v_mfma_f32_16x16x32_bf16 v[116:119], v[136:139], v[160:163], v[116:119]
	v_mfma_f32_16x16x32_bf16 v[112:115], v[144:147], v[160:163], v[112:115]
	v_mfma_f32_16x16x32_bf16 v[100:103], v[136:139], v[176:179], v[100:103]
	v_mfma_f32_16x16x32_bf16 v[96:99], v[144:147], v[176:179], v[96:99]
	v_mfma_f32_16x16x32_bf16 v[84:87], v[136:139], v[200:203], v[84:87]
	v_mfma_f32_16x16x32_bf16 v[80:83], v[144:147], v[200:203], v[80:83]
	v_mfma_f32_16x16x32_bf16 v[132:135], v[140:143], v[156:159], v[132:135]
	v_mfma_f32_16x16x32_bf16 v[128:131], v[148:151], v[156:159], v[128:131]
	v_mfma_f32_16x16x32_bf16 v[116:119], v[140:143], v[172:175], v[116:119]
	v_mfma_f32_16x16x32_bf16 v[112:115], v[148:151], v[172:175], v[112:115]
	v_mfma_f32_16x16x32_bf16 v[100:103], v[140:143], v[196:199], v[100:103]
	v_mfma_f32_16x16x32_bf16 v[96:99], v[148:151], v[196:199], v[96:99]
	v_mfma_f32_16x16x32_bf16 v[84:87], v[140:143], v[204:207], v[84:87]
	v_mfma_f32_16x16x32_bf16 v[80:83], v[148:151], v[204:207], v[80:83]
	s_barrier
	s_add_i32 s5, 0, 0x1c000
	s_add_i32 s4, s100, s23
	v_add_u32_e32 v0, s5, v181
	s_mov_b32 m0, s4
	ds_read_b128 v[208:211], v0
	ds_read_b128 v[212:215], v0 offset:1024
	ds_read_b128 v[216:219], v0 offset:2048
	ds_read_b128 v[220:223], v0 offset:3072
	s_add_u32 vcc_lo, s20, s46
	s_addc_u32 vcc_hi, s21, s47
	global_load_lds_dwordx4 v164, vcc
	s_add_i32 m0, s4, 0x2000
	s_nop 0
	s_add_u32 vcc_lo, s20, s52
	s_addc_u32 vcc_hi, s21, s53
	global_load_lds_dwordx4 v164, vcc
	s_barrier
; #define G_STAGE(bufoff, gbase, o0, h64) do { \
;         __builtin_amdgcn_global_load_lds((const unsigned*)((const char*)(gbase) + (o0)), (LAS unsigned*)(lds + (bufoff) + ldsw), 16, 0, 0); \
;         __builtin_amdgcn_global_load_lds((const unsigned*)((const char*)(gbase) + (h64) + (o0)), (LAS unsigned*)(lds + (bufoff) + ldsw + 8192), 16, 0, 0); } while (0)
; #define G_LDA(dst, b, h) do { _Pragma("unroll") for (int m = 0; m < 4; ++m) _Pragma("unroll") for (int k = 0; k < 2; ++k) dst[m][k] = *(const LAS bf16x8*)(lds + G_SA(b, h) + aoff + m * 2048 + k * 1024); } while (0)
; #define G_LDB(dst, b, h) do { _Pragma("unroll") for (int n = 0; n < 2; ++n) _Pragma("unroll") for (int k = 0; k < 2; ++k) dst[n][k] = *(const LAS bf16x8*)(lds + G_SB(b, h) + boff + n * 2048 + k * 1024); } while (0)
; #define G_WAIT_V(n) asm volatile("s_waitcnt vmcnt(" #n ")" ::: "memory")
; #define G_BAR __builtin_amdgcn_s_barrier()
;     ...
;         for (int t = 0; t < nt; t += 2) {
;             const bool last = (t == nt - 2);
;             const char* a1 = cA + (size_t)(t + 1) * ckA;
;             const char* a2 = last ? nA : cA + (size_t)(t + 2) * ckA; const char* b2 = last ? nB : cB + (size_t)(t + 2) * kB;
;             const char* a3 = a2 + ckA; const char* b3 = b2 + kB;
;             G_LDB(B0, 0, 0); G_SCHED; G_LDA(At, 0, 0); G_STAGE(G_SA(1, 1), a1 + chA, cA0, qA);
;             G_WAIT_L(8); G_BAR; G_WAIT_L(0); G_MMA(0, 0, At, B0); G_BAR; G_SCHED;
;             G_LDB(B1, 0, 1); G_STAGE(G_SB(0, 0), b2, cB0, qB);
;             G_BAR; G_WAIT_L(0); G_MMA(0, 1, At, B1); G_BAR;
;             G_LDA(At, 0, 1); G_STAGE(G_SA(0, 0), a2, cA0, qA);
;             G_BAR; G_WAIT_L(0); G_MMA(1, 0, At, B0); G_BAR; G_SCHED;
;             G_STAGE(G_SB(0, 1), b2 + chB, cB0, qB);
;             G_WAIT_V(6); G_BAR; G_MMA(1, 1, At, B1); G_BAR;
;             G_LDB(B0, 1, 0); G_SCHED; G_LDA(At, 1, 0); G_STAGE(G_SA(0, 1), a2 + chA, cA0, qA);
;             G_WAIT_L(8); G_BAR; G_WAIT_L(0); G_MMA(0, 0, At, B0); G_BAR; G_SCHED;
;             G_LDB(B1, 1, 1); G_STAGE(G_SB(1, 0), b3, cB0, qB);
;             G_BAR; G_WAIT_L(0); G_MMA(0, 1, At, B1); G_BAR;
;             G_LDA(At, 1, 1); G_STAGE(G_SA(1, 0), a3, cA0, qA);
;             G_BAR; G_WAIT_L(0); G_MMA(1, 0, At, B0); G_BAR; G_SCHED;
;             G_STAGE(G_SB(1, 1), b3 + chB, cB0, qB);
;             G_WAIT_V(6); G_BAR; G_MMA(1, 1, At, B1); G_BAR;
	s_waitcnt lgkmcnt(0)
	v_mfma_f32_16x16x32_bf16 v[124:127], v[208:211], v[152:155], v[124:127]
	v_mfma_f32_16x16x32_bf16 v[120:123], v[216:219], v[152:155], v[120:123]
	v_mfma_f32_16x16x32_bf16 v[108:111], v[208:211], v[160:163], v[108:111]
	v_mfma_f32_16x16x32_bf16 v[104:107], v[216:219], v[160:163], v[104:107]
	v_mfma_f32_16x16x32_bf16 v[92:95], v[208:211], v[176:179], v[92:95]
	v_mfma_f32_16x16x32_bf16 v[88:91], v[216:219], v[176:179], v[88:91]
	v_mfma_f32_16x16x32_bf16 v[76:79], v[208:211], v[200:203], v[76:79]
	v_mfma_f32_16x16x32_bf16 v[72:75], v[216:219], v[200:203], v[72:75]
	v_mfma_f32_16x16x32_bf16 v[124:127], v[212:215], v[156:159], v[124:127]
	v_mfma_f32_16x16x32_bf16 v[120:123], v[220:223], v[156:159], v[120:123]
	v_mfma_f32_16x16x32_bf16 v[108:111], v[212:215], v[172:175], v[108:111]
	v_mfma_f32_16x16x32_bf16 v[104:107], v[220:223], v[172:175], v[104:107]
	v_mfma_f32_16x16x32_bf16 v[92:95], v[212:215], v[196:199], v[92:95]
	v_mfma_f32_16x16x32_bf16 v[88:91], v[220:223], v[196:199], v[88:91]
	v_mfma_f32_16x16x32_bf16 v[76:79], v[212:215], v[204:207], v[76:79]
	v_mfma_f32_16x16x32_bf16 v[72:75], v[220:223], v[204:207], v[72:75]
	s_barrier
	s_mov_b32 m0, s29
	v_lshl_add_u64 v[226:227], v[224:225], 0, s[46:47]
	ds_read_b128 v[152:155], v182 offset:49152
	ds_read_b128 v[156:159], v182 offset:50176
	ds_read_b128 v[160:163], v182 offset:51200
	ds_read_b128 v[172:175], v182 offset:52224
	ds_read_b128 v[176:179], v182 offset:53248
	ds_read_b128 v[196:199], v182 offset:54272
	ds_read_b128 v[200:203], v182 offset:55296
	ds_read_b128 v[204:207], v182 offset:56320
	global_load_lds_dwordx4 v[226:227], off
	v_lshl_add_u64 v[224:225], v[224:225], 0, s[52:53]
	s_mov_b32 m0, s30
	s_nop 0
	global_load_lds_dwordx4 v[224:225], off
	s_barrier
	s_waitcnt lgkmcnt(0)
	v_mfma_f32_16x16x32_bf16 v[68:71], v[136:139], v[152:155], v[68:71]
	v_mfma_f32_16x16x32_bf16 v[64:67], v[144:147], v[152:155], v[64:67]
	v_mfma_f32_16x16x32_bf16 v[52:55], v[136:139], v[160:163], v[52:55]
	v_mfma_f32_16x16x32_bf16 v[48:51], v[144:147], v[160:163], v[48:51]
	v_mfma_f32_16x16x32_bf16 v[36:39], v[136:139], v[176:179], v[36:39]
	v_mfma_f32_16x16x32_bf16 v[32:35], v[144:147], v[176:179], v[32:35]
	v_mfma_f32_16x16x32_bf16 v[20:23], v[136:139], v[200:203], v[20:23]
	v_mfma_f32_16x16x32_bf16 v[16:19], v[144:147], v[200:203], v[16:19]
	v_mfma_f32_16x16x32_bf16 v[68:71], v[140:143], v[156:159], v[68:71]
	v_mfma_f32_16x16x32_bf16 v[64:67], v[148:151], v[156:159], v[64:67]
	v_mfma_f32_16x16x32_bf16 v[52:55], v[140:143], v[172:175], v[52:55]
	v_mfma_f32_16x16x32_bf16 v[48:51], v[148:151], v[172:175], v[48:51]
	v_mfma_f32_16x16x32_bf16 v[36:39], v[140:143], v[196:199], v[36:39]
	v_mfma_f32_16x16x32_bf16 v[32:35], v[148:151], v[196:199], v[32:35]
	v_mfma_f32_16x16x32_bf16 v[20:23], v[140:143], v[204:207], v[20:23]
	v_mfma_f32_16x16x32_bf16 v[16:19], v[148:151], v[204:207], v[16:19]
	s_barrier
	s_add_i32 s4, s5, s23
	s_mov_b32 m0, s4
	s_nop 0
	s_add_u32 vcc_lo, s20, s54
	s_addc_u32 vcc_hi, s21, s55
	global_load_lds_dwordx4 v164, vcc
	s_add_i32 m0, s4, 0x2000
	s_nop 0
	s_add_u32 vcc_lo, s20, s58
	s_addc_u32 vcc_hi, s21, s59
	global_load_lds_dwordx4 v164, vcc
	s_add_i32 s15, s15, 2
	s_add_u32 s2, s2, 0x100
	s_addc_u32 s3, s3, 0
	s_add_u32 s6, s6, 0x100
	s_addc_u32 s7, s7, 0
	s_cmp_gt_u32 s15, 13
	s_waitcnt vmcnt(6)
	s_barrier
	v_mfma_f32_16x16x32_bf16 v[60:63], v[208:211], v[152:155], v[60:63]
	v_mfma_f32_16x16x32_bf16 v[56:59], v[216:219], v[152:155], v[56:59]
	v_mfma_f32_16x16x32_bf16 v[44:47], v[208:211], v[160:163], v[44:47]
	v_mfma_f32_16x16x32_bf16 v[40:43], v[216:219], v[160:163], v[40:43]
	v_mfma_f32_16x16x32_bf16 v[28:31], v[208:211], v[176:179], v[28:31]
	v_mfma_f32_16x16x32_bf16 v[24:27], v[216:219], v[176:179], v[24:27]
	v_mfma_f32_16x16x32_bf16 v[12:15], v[208:211], v[200:203], v[12:15]
	v_mfma_f32_16x16x32_bf16 v[8:11], v[216:219], v[200:203], v[8:11]
	v_mfma_f32_16x16x32_bf16 v[60:63], v[212:215], v[156:159], v[60:63]
	v_mfma_f32_16x16x32_bf16 v[56:59], v[220:223], v[156:159], v[56:59]
	v_mfma_f32_16x16x32_bf16 v[44:47], v[212:215], v[172:175], v[44:47]
	v_mfma_f32_16x16x32_bf16 v[40:43], v[220:223], v[172:175], v[40:43]
	v_mfma_f32_16x16x32_bf16 v[28:31], v[212:215], v[196:199], v[28:31]
	v_mfma_f32_16x16x32_bf16 v[24:27], v[220:223], v[196:199], v[24:27]
	v_mfma_f32_16x16x32_bf16 v[12:15], v[212:215], v[204:207], v[12:15]
	v_mfma_f32_16x16x32_bf16 v[8:11], v[220:223], v[204:207], v[8:11]
	s_cbranch_scc0 .Ldb_WOUT_cont
	v_readfirstlane_b32 s101, v186
	s_cmpk_gt_u32 s101, 0xff
	s_cbranch_scc1 .Ldb_WOUT_young
	s_barrier
	s_mov_b32 s101, 1
	s_branch .Ldb_WOUT_exit

; #define G_STAGE(bufoff, gbase, o0, h64) do { \
;         __builtin_amdgcn_global_load_lds((const unsigned*)((const char*)(gbase) + (o0)), (LAS unsigned*)(lds + (bufoff) + ldsw), 16, 0, 0); \
;         __builtin_amdgcn_global_load_lds((const unsigned*)((const char*)(gbase) + (h64) + (o0)), (LAS unsigned*)(lds + (bufoff) + ldsw + 8192), 16, 0, 0); } while (0)
; #define G_LDA(dst, b, h) do { _Pragma("unroll") for (int m = 0; m < 4; ++m) _Pragma("unroll") for (int k = 0; k < 2; ++k) dst[m][k] = *(const LAS bf16x8*)(lds + G_SA(b, h) + aoff + m * 2048 + k * 1024); } while (0)
; #define G_LDB(dst, b, h) do { _Pragma("unroll") for (int n = 0; n < 2; ++n) _Pragma("unroll") for (int k = 0; k < 2; ++k) dst[n][k] = *(const LAS bf16x8*)(lds + G_SB(b, h) + boff + n * 2048 + k * 1024); } while (0)
; #define G_WAIT_V(n) asm volatile("s_waitcnt vmcnt(" #n ")" ::: "memory")
; #define G_BAR __builtin_amdgcn_s_barrier()
;     ...
;         for (int t = 0; t < nt; t += 2) {
;             const bool last = (t == nt - 2);
;             const char* a1 = cA + (size_t)(t + 1) * ckA;
;             const char* a2 = last ? nA : cA + (size_t)(t + 2) * ckA; const char* b2 = last ? nB : cB + (size_t)(t + 2) * kB;
;             const char* a3 = a2 + ckA; const char* b3 = b2 + kB;
;             G_LDB(B0, 0, 0); G_SCHED; G_LDA(At, 0, 0); G_STAGE(G_SA(1, 1), a1 + chA, cA0, qA);
;             G_WAIT_L(8); G_BAR; G_WAIT_L(0); G_MMA(0, 0, At, B0); G_BAR; G_SCHED;
;             G_LDB(B1, 0, 1); G_STAGE(G_SB(0, 0), b2, cB0, qB);
;             G_BAR; G_WAIT_L(0); G_MMA(0, 1, At, B1); G_BAR;
;             G_LDA(At, 0, 1); G_STAGE(G_SA(0, 0), a2, cA0, qA);
;             G_BAR; G_WAIT_L(0); G_MMA(1, 0, At, B0); G_BAR; G_SCHED;
;             G_STAGE(G_SB(0, 1), b2 + chB, cB0, qB);
;             G_WAIT_V(6); G_BAR; G_MMA(1, 1, At, B1); G_BAR;
;             G_LDB(B0, 1, 0); G_SCHED; G_LDA(At, 1, 0); G_STAGE(G_SA(0, 1), a2 + chA, cA0, qA);
;             G_WAIT_L(8); G_BAR; G_WAIT_L(0); G_MMA(0, 0, At, B0); G_BAR; G_SCHED;
;             G_LDB(B1, 1, 1); G_STAGE(G_SB(1, 0), b3, cB0, qB);
;             G_BAR; G_WAIT_L(0); G_MMA(0, 1, At, B1); G_BAR;
;             G_LDA(At, 1, 1); G_STAGE(G_SA(1, 0), a3, cA0, qA);
;             G_BAR; G_WAIT_L(0); G_MMA(1, 0, At, B0); G_BAR; G_SCHED;
;             G_STAGE(G_SB(1, 1), b3 + chB, cB0, qB);
;             G_WAIT_V(6); G_BAR; G_MMA(1, 1, At, B1); G_BAR;
.LBB0_1120:
	s_add_u32 s4, s2, 0xfffc0080
	s_addc_u32 s5, s3, -1
	s_add_i32 s19, 0, 0x10000
	v_add_u32_e32 v0, s19, v149
	ds_read_b128 v[140:143], v0
	ds_read_b128 v[144:147], v0 offset:1024
	ds_read_b128 v[152:155], v0 offset:2048
	ds_read_b128 v[156:159], v0 offset:3072
	s_cmp_eq_u32 s18, 12
	s_cselect_b32 s5, s13, s5
	s_cselect_b32 s4, s12, s4
	s_cselect_b32 s41, s15, s17
	s_cselect_b32 s40, s14, s16
	s_add_i32 m0, s26, 0xc000
	ds_read_b128 v[160:163], v150
	ds_read_b128 v[164:167], v150 offset:1024
	ds_read_b128 v[172:175], v150 offset:2048
	ds_read_b128 v[176:179], v150 offset:3072
	ds_read_b128 v[180:183], v150 offset:4096
	ds_read_b128 v[196:199], v150 offset:5120
	ds_read_b128 v[200:203], v150 offset:6144
	ds_read_b128 v[204:207], v150 offset:7168
	global_load_lds_dwordx4 v138, s[2:3]
	s_add_i32 m0, s26, 0xe000
	s_nop 0
	s_add_u32 vcc_lo, s2, s0
	s_addc_u32 vcc_hi, s3, s1
	global_load_lds_dwordx4 v138, vcc
	s_waitcnt lgkmcnt(8)
	s_cmp_eq_u32 s101, 1
	s_cbranch_scc1 .Ldb_FFI_sk
	s_barrier
.Ldb_FFI_sk:
	s_mov_b32 s101, 0
	s_waitcnt lgkmcnt(0)
	v_mfma_f32_16x16x32_bf16 v[132:135], v[140:143], v[160:163], v[132:135]
	v_mfma_f32_16x16x32_bf16 v[124:127], v[152:155], v[160:163], v[124:127]
	v_mfma_f32_16x16x32_bf16 v[116:119], v[140:143], v[172:175], v[116:119]
	v_mfma_f32_16x16x32_bf16 v[108:111], v[152:155], v[172:175], v[108:111]
	v_mfma_f32_16x16x32_bf16 v[100:103], v[140:143], v[180:183], v[100:103]
	v_mfma_f32_16x16x32_bf16 v[92:95], v[152:155], v[180:183], v[92:95]
	v_mfma_f32_16x16x32_bf16 v[84:87], v[140:143], v[200:203], v[84:87]
	v_mfma_f32_16x16x32_bf16 v[76:79], v[152:155], v[200:203], v[76:79]
	v_mfma_f32_16x16x32_bf16 v[132:135], v[144:147], v[164:167], v[132:135]
	v_mfma_f32_16x16x32_bf16 v[124:127], v[156:159], v[164:167], v[124:127]
	v_mfma_f32_16x16x32_bf16 v[116:119], v[144:147], v[176:179], v[116:119]
	v_mfma_f32_16x16x32_bf16 v[108:111], v[156:159], v[176:179], v[108:111]
	v_mfma_f32_16x16x32_bf16 v[100:103], v[144:147], v[196:199], v[100:103]
	v_mfma_f32_16x16x32_bf16 v[92:95], v[156:159], v[196:199], v[92:95]
	v_mfma_f32_16x16x32_bf16 v[84:87], v[144:147], v[204:207], v[84:87]
	v_mfma_f32_16x16x32_bf16 v[76:79], v[156:159], v[204:207], v[76:79]
	s_barrier
	s_add_i32 s39, 0, 0x14000
	s_add_i32 s19, s19, s21
	v_add_u32_e32 v0, s39, v149
	s_mov_b32 m0, s19
	ds_read_b128 v[208:211], v0
	ds_read_b128 v[212:215], v0 offset:1024
	ds_read_b128 v[216:219], v0 offset:2048
	ds_read_b128 v[220:223], v0 offset:3072
	global_load_lds_dwordx4 v2, s[40:41]
	s_add_i32 m0, s19, 0x2000
	s_nop 0
	s_add_u32 vcc_lo, s40, s0
	s_addc_u32 vcc_hi, s41, s1
	global_load_lds_dwordx4 v2, vcc
	s_barrier
	s_waitcnt lgkmcnt(0)
	v_mfma_f32_16x16x32_bf16 v[128:131], v[208:211], v[160:163], v[128:131]
	v_mfma_f32_16x16x32_bf16 v[120:123], v[216:219], v[160:163], v[120:123]
	v_mfma_f32_16x16x32_bf16 v[112:115], v[208:211], v[172:175], v[112:115]
	v_mfma_f32_16x16x32_bf16 v[104:107], v[216:219], v[172:175], v[104:107]
	v_mfma_f32_16x16x32_bf16 v[96:99], v[208:211], v[180:183], v[96:99]
	v_mfma_f32_16x16x32_bf16 v[88:91], v[216:219], v[180:183], v[88:91]
	v_mfma_f32_16x16x32_bf16 v[80:83], v[208:211], v[200:203], v[80:83]
	v_mfma_f32_16x16x32_bf16 v[72:75], v[216:219], v[200:203], v[72:75]
	v_mfma_f32_16x16x32_bf16 v[128:131], v[212:215], v[164:167], v[128:131]
	v_mfma_f32_16x16x32_bf16 v[120:123], v[220:223], v[164:167], v[120:123]
	v_mfma_f32_16x16x32_bf16 v[112:115], v[212:215], v[176:179], v[112:115]
	v_mfma_f32_16x16x32_bf16 v[104:107], v[220:223], v[176:179], v[104:107]
	v_mfma_f32_16x16x32_bf16 v[96:99], v[212:215], v[196:199], v[96:99]
	v_mfma_f32_16x16x32_bf16 v[88:91], v[220:223], v[196:199], v[88:91]
	v_mfma_f32_16x16x32_bf16 v[80:83], v[212:215], v[204:207], v[80:83]
	v_mfma_f32_16x16x32_bf16 v[72:75], v[220:223], v[204:207], v[72:75]
	s_barrier
	s_mov_b32 m0, s26
	v_lshl_add_u64 v[224:225], s[4:5], 0, v[136:137]
	ds_read_b128 v[160:163], v150 offset:16384
	ds_read_b128 v[164:167], v150 offset:17408
	ds_read_b128 v[172:175], v150 offset:18432
	ds_read_b128 v[176:179], v150 offset:19456
	ds_read_b128 v[180:183], v150 offset:20480
	ds_read_b128 v[196:199], v150 offset:21504
	ds_read_b128 v[200:203], v150 offset:22528
	ds_read_b128 v[204:207], v150 offset:23552
	global_load_lds_dwordx4 v136, s[4:5]
	s_mov_b32 m0, s27
	s_nop 0
	s_add_u32 vcc_lo, s4, s0
	s_addc_u32 vcc_hi, s5, s1
	global_load_lds_dwordx4 v136, vcc
	s_barrier
	s_waitcnt lgkmcnt(0)
	v_mfma_f32_16x16x32_bf16 v[68:71], v[140:143], v[160:163], v[68:71]
	v_mfma_f32_16x16x32_bf16 v[60:63], v[152:155], v[160:163], v[60:63]
	v_mfma_f32_16x16x32_bf16 v[52:55], v[140:143], v[172:175], v[52:55]
	v_mfma_f32_16x16x32_bf16 v[44:47], v[152:155], v[172:175], v[44:47]
	v_mfma_f32_16x16x32_bf16 v[36:39], v[140:143], v[180:183], v[36:39]
	v_mfma_f32_16x16x32_bf16 v[28:31], v[152:155], v[180:183], v[28:31]
	v_mfma_f32_16x16x32_bf16 v[20:23], v[140:143], v[200:203], v[20:23]
	v_mfma_f32_16x16x32_bf16 v[12:15], v[152:155], v[200:203], v[12:15]
	v_mfma_f32_16x16x32_bf16 v[68:71], v[144:147], v[164:167], v[68:71]
	v_mfma_f32_16x16x32_bf16 v[60:63], v[156:159], v[164:167], v[60:63]
	v_mfma_f32_16x16x32_bf16 v[52:55], v[144:147], v[176:179], v[52:55]
	v_mfma_f32_16x16x32_bf16 v[44:47], v[156:159], v[176:179], v[44:47]
	v_mfma_f32_16x16x32_bf16 v[36:39], v[144:147], v[196:199], v[36:39]
	v_mfma_f32_16x16x32_bf16 v[28:31], v[156:159], v[196:199], v[28:31]
	v_mfma_f32_16x16x32_bf16 v[20:23], v[144:147], v[204:207], v[20:23]
	v_mfma_f32_16x16x32_bf16 v[12:15], v[156:159], v[204:207], v[12:15]
	s_barrier
; #define G_STAGE(bufoff, gbase, o0, h64) do { \
;         __builtin_amdgcn_global_load_lds((const unsigned*)((const char*)(gbase) + (o0)), (LAS unsigned*)(lds + (bufoff) + ldsw), 16, 0, 0); \
;         __builtin_amdgcn_global_load_lds((const unsigned*)((const char*)(gbase) + (h64) + (o0)), (LAS unsigned*)(lds + (bufoff) + ldsw + 8192), 16, 0, 0); } while (0)
; #define G_LDA(dst, b, h) do { _Pragma("unroll") for (int m = 0; m < 4; ++m) _Pragma("unroll") for (int k = 0; k < 2; ++k) dst[m][k] = *(const LAS bf16x8*)(lds + G_SA(b, h) + aoff + m * 2048 + k * 1024); } while (0)
; #define G_LDB(dst, b, h) do { _Pragma("unroll") for (int n = 0; n < 2; ++n) _Pragma("unroll") for (int k = 0; k < 2; ++k) dst[n][k] = *(const LAS bf16x8*)(lds + G_SB(b, h) + boff + n * 2048 + k * 1024); } while (0)
; #define G_WAIT_V(n) asm volatile("s_waitcnt vmcnt(" #n ")" ::: "memory")
; #define G_WAIT_L(n) asm volatile("s_waitcnt lgkmcnt(" #n ")" ::: "memory")
; #define G_BAR __builtin_amdgcn_s_barrier()
; #define G_SCHED __builtin_amdgcn_sched_barrier(0)
;     ...
;             G_STAGE(G_SB(0, 1), b2 + chB, cB0, qB);
;             G_WAIT_V(6); G_BAR; G_MMA(1, 1, At, B1); G_BAR;
;             G_LDB(B0, 1, 0); G_SCHED; G_LDA(At, 1, 0); G_STAGE(G_SA(0, 1), a2 + chA, cA0, qA);
;             G_WAIT_L(8); G_BAR; G_WAIT_L(0); G_MMA(0, 0, At, B0); G_BAR; G_SCHED;
;             G_LDB(B1, 1, 1); G_STAGE(G_SB(1, 0), b3, cB0, qB);
	s_add_i32 s100, s39, s21
	s_mov_b32 m0, s100
	s_nop 0
	s_add_u32 vcc_lo, s40, s42
	s_addc_u32 vcc_hi, s41, s43
	global_load_lds_dwordx4 v2, vcc
	s_add_i32 m0, s100, 0x2000
	s_nop 0
	s_add_u32 vcc_lo, s40, s50
	s_addc_u32 vcc_hi, s41, s51
	global_load_lds_dwordx4 v2, vcc
	s_waitcnt vmcnt(6)
	s_barrier
	v_mfma_f32_16x16x32_bf16 v[64:67], v[208:211], v[160:163], v[64:67]
	v_mfma_f32_16x16x32_bf16 v[56:59], v[216:219], v[160:163], v[56:59]
	v_mfma_f32_16x16x32_bf16 v[48:51], v[208:211], v[172:175], v[48:51]
	v_mfma_f32_16x16x32_bf16 v[40:43], v[216:219], v[172:175], v[40:43]
	v_mfma_f32_16x16x32_bf16 v[32:35], v[208:211], v[180:183], v[32:35]
	v_mfma_f32_16x16x32_bf16 v[24:27], v[216:219], v[180:183], v[24:27]
	v_mfma_f32_16x16x32_bf16 v[16:19], v[208:211], v[200:203], v[16:19]
	v_mfma_f32_16x16x32_bf16 v[8:11], v[216:219], v[200:203], v[8:11]
	v_mfma_f32_16x16x32_bf16 v[64:67], v[212:215], v[164:167], v[64:67]
	v_mfma_f32_16x16x32_bf16 v[56:59], v[220:223], v[164:167], v[56:59]
	v_mfma_f32_16x16x32_bf16 v[48:51], v[212:215], v[176:179], v[48:51]
	v_mfma_f32_16x16x32_bf16 v[40:43], v[220:223], v[176:179], v[40:43]
	v_mfma_f32_16x16x32_bf16 v[32:35], v[212:215], v[196:199], v[32:35]
	v_mfma_f32_16x16x32_bf16 v[24:27], v[220:223], v[196:199], v[24:27]
	v_mfma_f32_16x16x32_bf16 v[16:19], v[212:215], v[204:207], v[16:19]
	v_mfma_f32_16x16x32_bf16 v[8:11], v[220:223], v[204:207], v[8:11]
	s_barrier
	s_add_i32 s100, 0, 0x18000
	v_add_u32_e32 v0, s100, v149
	ds_read_b128 v[140:143], v0
	ds_read_b128 v[144:147], v0 offset:1024
	ds_read_b128 v[152:155], v0 offset:2048
	ds_read_b128 v[156:159], v0 offset:3072
	s_mov_b32 m0, s29
	ds_read_b128 v[160:163], v150 offset:32768
	ds_read_b128 v[164:167], v150 offset:33792
	ds_read_b128 v[172:175], v150 offset:34816
	ds_read_b128 v[176:179], v150 offset:35840
	ds_read_b128 v[180:183], v150 offset:36864
	ds_read_b128 v[196:199], v150 offset:37888
	ds_read_b128 v[200:203], v150 offset:38912
	ds_read_b128 v[204:207], v150 offset:39936
	s_add_u32 vcc_lo, s4, s42
	s_addc_u32 vcc_hi, s5, s43
	global_load_lds_dwordx4 v136, vcc
	s_mov_b32 m0, s30
	s_nop 0
	s_add_u32 vcc_lo, s4, s50
	s_addc_u32 vcc_hi, s5, s51
	global_load_lds_dwordx4 v136, vcc
	s_waitcnt lgkmcnt(8)
	s_barrier
	s_waitcnt lgkmcnt(0)
	v_mfma_f32_16x16x32_bf16 v[132:135], v[140:143], v[160:163], v[132:135]
	v_mfma_f32_16x16x32_bf16 v[124:127], v[152:155], v[160:163], v[124:127]
	v_mfma_f32_16x16x32_bf16 v[116:119], v[140:143], v[172:175], v[116:119]
	v_mfma_f32_16x16x32_bf16 v[108:111], v[152:155], v[172:175], v[108:111]
	v_mfma_f32_16x16x32_bf16 v[100:103], v[140:143], v[180:183], v[100:103]
	v_mfma_f32_16x16x32_bf16 v[92:95], v[152:155], v[180:183], v[92:95]
	v_mfma_f32_16x16x32_bf16 v[84:87], v[140:143], v[200:203], v[84:87]
	v_mfma_f32_16x16x32_bf16 v[76:79], v[152:155], v[200:203], v[76:79]
	v_mfma_f32_16x16x32_bf16 v[132:135], v[144:147], v[164:167], v[132:135]
	v_mfma_f32_16x16x32_bf16 v[124:127], v[156:159], v[164:167], v[124:127]
	v_mfma_f32_16x16x32_bf16 v[116:119], v[144:147], v[176:179], v[116:119]
	v_mfma_f32_16x16x32_bf16 v[108:111], v[156:159], v[176:179], v[108:111]
	v_mfma_f32_16x16x32_bf16 v[100:103], v[144:147], v[196:199], v[100:103]
	v_mfma_f32_16x16x32_bf16 v[92:95], v[156:159], v[196:199], v[92:95]
	v_mfma_f32_16x16x32_bf16 v[84:87], v[144:147], v[204:207], v[84:87]
	v_mfma_f32_16x16x32_bf16 v[76:79], v[156:159], v[204:207], v[76:79]
	s_barrier
	s_add_i32 s5, 0, 0x1c000
	s_add_i32 s4, s100, s21
	v_add_u32_e32 v0, s5, v149
	s_mov_b32 m0, s4
	ds_read_b128 v[208:211], v0
	ds_read_b128 v[212:215], v0 offset:1024
	ds_read_b128 v[216:219], v0 offset:2048
	ds_read_b128 v[220:223], v0 offset:3072
	s_add_u32 vcc_lo, s40, s46
	s_addc_u32 vcc_hi, s41, s47
	global_load_lds_dwordx4 v2, vcc
	s_add_i32 m0, s4, 0x2000
	s_nop 0
	s_add_u32 vcc_lo, s40, s52
	s_addc_u32 vcc_hi, s41, s53
	global_load_lds_dwordx4 v2, vcc
	s_barrier
; #define G_STAGE(bufoff, gbase, o0, h64) do { \
;         __builtin_amdgcn_global_load_lds((const unsigned*)((const char*)(gbase) + (o0)), (LAS unsigned*)(lds + (bufoff) + ldsw), 16, 0, 0); \
;         __builtin_amdgcn_global_load_lds((const unsigned*)((const char*)(gbase) + (h64) + (o0)), (LAS unsigned*)(lds + (bufoff) + ldsw + 8192), 16, 0, 0); } while (0)
; #define G_LDA(dst, b, h) do { _Pragma("unroll") for (int m = 0; m < 4; ++m) _Pragma("unroll") for (int k = 0; k < 2; ++k) dst[m][k] = *(const LAS bf16x8*)(lds + G_SA(b, h) + aoff + m * 2048 + k * 1024); } while (0)
; #define G_WAIT_V(n) asm volatile("s_waitcnt vmcnt(" #n ")" ::: "memory")
; #define G_WAIT_L(n) asm volatile("s_waitcnt lgkmcnt(" #n ")" ::: "memory")
; #define G_BAR __builtin_amdgcn_s_barrier()
; #define G_SCHED __builtin_amdgcn_sched_barrier(0)
;     ...
;             G_BAR; G_WAIT_L(0); G_MMA(0, 1, At, B1); G_BAR;
;             G_LDA(At, 1, 1); G_STAGE(G_SA(1, 0), a3, cA0, qA);
;             G_BAR; G_WAIT_L(0); G_MMA(1, 0, At, B0); G_BAR; G_SCHED;
;             G_STAGE(G_SB(1, 1), b3 + chB, cB0, qB);
;             G_WAIT_V(6); G_BAR; G_MMA(1, 1, At, B1); G_BAR;
	s_waitcnt lgkmcnt(0)
	v_mfma_f32_16x16x32_bf16 v[128:131], v[208:211], v[160:163], v[128:131]
	v_mfma_f32_16x16x32_bf16 v[120:123], v[216:219], v[160:163], v[120:123]
	v_mfma_f32_16x16x32_bf16 v[112:115], v[208:211], v[172:175], v[112:115]
	v_mfma_f32_16x16x32_bf16 v[104:107], v[216:219], v[172:175], v[104:107]
	v_mfma_f32_16x16x32_bf16 v[96:99], v[208:211], v[180:183], v[96:99]
	v_mfma_f32_16x16x32_bf16 v[88:91], v[216:219], v[180:183], v[88:91]
	v_mfma_f32_16x16x32_bf16 v[80:83], v[208:211], v[200:203], v[80:83]
	v_mfma_f32_16x16x32_bf16 v[72:75], v[216:219], v[200:203], v[72:75]
	v_mfma_f32_16x16x32_bf16 v[128:131], v[212:215], v[164:167], v[128:131]
	v_mfma_f32_16x16x32_bf16 v[120:123], v[220:223], v[164:167], v[120:123]
	v_mfma_f32_16x16x32_bf16 v[112:115], v[212:215], v[176:179], v[112:115]
	v_mfma_f32_16x16x32_bf16 v[104:107], v[220:223], v[176:179], v[104:107]
	v_mfma_f32_16x16x32_bf16 v[96:99], v[212:215], v[196:199], v[96:99]
	v_mfma_f32_16x16x32_bf16 v[88:91], v[220:223], v[196:199], v[88:91]
	v_mfma_f32_16x16x32_bf16 v[80:83], v[212:215], v[204:207], v[80:83]
	v_mfma_f32_16x16x32_bf16 v[72:75], v[220:223], v[204:207], v[72:75]
	s_barrier
	s_mov_b32 m0, s31
	v_lshl_add_u64 v[226:227], v[224:225], 0, s[46:47]
	ds_read_b128 v[160:163], v150 offset:49152
	ds_read_b128 v[164:167], v150 offset:50176
	ds_read_b128 v[172:175], v150 offset:51200
	ds_read_b128 v[176:179], v150 offset:52224
	ds_read_b128 v[180:183], v150 offset:53248
	ds_read_b128 v[196:199], v150 offset:54272
	ds_read_b128 v[200:203], v150 offset:55296
	ds_read_b128 v[204:207], v150 offset:56320
	global_load_lds_dwordx4 v[226:227], off
	v_lshl_add_u64 v[224:225], v[224:225], 0, s[52:53]
	s_mov_b32 m0, s34
	s_nop 0
	global_load_lds_dwordx4 v[224:225], off
	s_barrier
	s_waitcnt lgkmcnt(0)
	v_mfma_f32_16x16x32_bf16 v[68:71], v[140:143], v[160:163], v[68:71]
	v_mfma_f32_16x16x32_bf16 v[60:63], v[152:155], v[160:163], v[60:63]
	v_mfma_f32_16x16x32_bf16 v[52:55], v[140:143], v[172:175], v[52:55]
	v_mfma_f32_16x16x32_bf16 v[44:47], v[152:155], v[172:175], v[44:47]
	v_mfma_f32_16x16x32_bf16 v[36:39], v[140:143], v[180:183], v[36:39]
	v_mfma_f32_16x16x32_bf16 v[28:31], v[152:155], v[180:183], v[28:31]
	v_mfma_f32_16x16x32_bf16 v[20:23], v[140:143], v[200:203], v[20:23]
	v_mfma_f32_16x16x32_bf16 v[12:15], v[152:155], v[200:203], v[12:15]
	v_mfma_f32_16x16x32_bf16 v[68:71], v[144:147], v[164:167], v[68:71]
	v_mfma_f32_16x16x32_bf16 v[60:63], v[156:159], v[164:167], v[60:63]
	v_mfma_f32_16x16x32_bf16 v[52:55], v[144:147], v[176:179], v[52:55]
	v_mfma_f32_16x16x32_bf16 v[44:47], v[156:159], v[176:179], v[44:47]
	v_mfma_f32_16x16x32_bf16 v[36:39], v[144:147], v[196:199], v[36:39]
	v_mfma_f32_16x16x32_bf16 v[28:31], v[156:159], v[196:199], v[28:31]
	v_mfma_f32_16x16x32_bf16 v[20:23], v[144:147], v[204:207], v[20:23]
	v_mfma_f32_16x16x32_bf16 v[12:15], v[156:159], v[204:207], v[12:15]
	s_barrier
	s_add_i32 s4, s5, s21
	s_mov_b32 m0, s4
	s_nop 0
	s_add_u32 vcc_lo, s40, s54
	s_addc_u32 vcc_hi, s41, s55
	global_load_lds_dwordx4 v2, vcc
	s_add_i32 m0, s4, 0x2000
	s_nop 0
	s_add_u32 vcc_lo, s40, s58
	s_addc_u32 vcc_hi, s41, s59
	global_load_lds_dwordx4 v2, vcc
	s_add_i32 s18, s18, 2
	s_add_u32 s2, s2, 0x100
	s_addc_u32 s3, s3, 0
	s_add_u32 s16, s16, 0x100
	s_addc_u32 s17, s17, 0
	s_cmp_gt_u32 s18, 13
	s_waitcnt vmcnt(6)
	s_barrier
	v_mfma_f32_16x16x32_bf16 v[64:67], v[208:211], v[160:163], v[64:67]
	v_mfma_f32_16x16x32_bf16 v[56:59], v[216:219], v[160:163], v[56:59]
	v_mfma_f32_16x16x32_bf16 v[48:51], v[208:211], v[172:175], v[48:51]
	v_mfma_f32_16x16x32_bf16 v[40:43], v[216:219], v[172:175], v[40:43]
	v_mfma_f32_16x16x32_bf16 v[32:35], v[208:211], v[180:183], v[32:35]
	v_mfma_f32_16x16x32_bf16 v[24:27], v[216:219], v[180:183], v[24:27]
	v_mfma_f32_16x16x32_bf16 v[16:19], v[208:211], v[200:203], v[16:19]
	v_mfma_f32_16x16x32_bf16 v[8:11], v[216:219], v[200:203], v[8:11]
	v_mfma_f32_16x16x32_bf16 v[64:67], v[212:215], v[164:167], v[64:67]
	v_mfma_f32_16x16x32_bf16 v[56:59], v[220:223], v[164:167], v[56:59]
	v_mfma_f32_16x16x32_bf16 v[48:51], v[212:215], v[176:179], v[48:51]
	v_mfma_f32_16x16x32_bf16 v[40:43], v[220:223], v[176:179], v[40:43]
	v_mfma_f32_16x16x32_bf16 v[32:35], v[212:215], v[196:199], v[32:35]
	v_mfma_f32_16x16x32_bf16 v[24:27], v[220:223], v[196:199], v[24:27]
	v_mfma_f32_16x16x32_bf16 v[16:19], v[212:215], v[204:207], v[16:19]
	v_mfma_f32_16x16x32_bf16 v[8:11], v[220:223], v[204:207], v[8:11]
	s_cbranch_scc0 .Ldb_FFI_cont
	v_readfirstlane_b32 s101, v186
	s_cmpk_gt_u32 s101, 0xff
	s_cbranch_scc1 .Ldb_FFI_young
	s_barrier
	s_mov_b32 s101, 1
	s_branch .Ldb_FFI_exit

; #define G_STAGE(bufoff, gbase, o0, h64) do { \
;         __builtin_amdgcn_global_load_lds((const unsigned*)((const char*)(gbase) + (o0)), (LAS unsigned*)(lds + (bufoff) + ldsw), 16, 0, 0); \
;         __builtin_amdgcn_global_load_lds((const unsigned*)((const char*)(gbase) + (h64) + (o0)), (LAS unsigned*)(lds + (bufoff) + ldsw + 8192), 16, 0, 0); } while (0)
; #define G_LDA(dst, b, h) do { _Pragma("unroll") for (int m = 0; m < 4; ++m) _Pragma("unroll") for (int k = 0; k < 2; ++k) dst[m][k] = *(const LAS bf16x8*)(lds + G_SA(b, h) + aoff + m * 2048 + k * 1024); } while (0)
; #define G_LDB(dst, b, h) do { _Pragma("unroll") for (int n = 0; n < 2; ++n) _Pragma("unroll") for (int k = 0; k < 2; ++k) dst[n][k] = *(const LAS bf16x8*)(lds + G_SB(b, h) + boff + n * 2048 + k * 1024); } while (0)
; #define G_WAIT_L(n) asm volatile("s_waitcnt lgkmcnt(" #n ")" ::: "memory")
; #define G_BAR __builtin_amdgcn_s_barrier()
; #define G_SCHED __builtin_amdgcn_sched_barrier(0)
;     ...
;             const bool last = (t == nt - 2);
;             const char* a1 = cA + (size_t)(t + 1) * ckA;
;             const char* a2 = last ? nA : cA + (size_t)(t + 2) * ckA; const char* b2 = last ? nB : cB + (size_t)(t + 2) * kB;
;             const char* a3 = a2 + ckA; const char* b3 = b2 + kB;
;             G_LDB(B0, 0, 0); G_SCHED; G_LDA(At, 0, 0); G_STAGE(G_SA(1, 1), a1 + chA, cA0, qA);
;             G_WAIT_L(8); G_BAR; G_WAIT_L(0); G_MMA(0, 0, At, B0); G_BAR; G_SCHED;
;             G_LDB(B1, 0, 1); G_STAGE(G_SB(0, 0), b2, cB0, qB);
;             G_BAR; G_WAIT_L(0); G_MMA(0, 1, At, B1); G_BAR;
;             G_LDA(At, 0, 1); G_STAGE(G_SA(0, 0), a2, cA0, qA);
;             G_BAR; G_WAIT_L(0); G_MMA(1, 0, At, B0); G_BAR; G_SCHED;
.LBB0_1185:
	s_add_u32 s4, s2, 0xfff50080
	s_addc_u32 s5, s3, -1
	s_add_i32 s33, 0, 0x10000
	v_add_u32_e32 v0, s33, v185
	ds_read_b128 v[136:139], v0
	ds_read_b128 v[140:143], v0 offset:1024
	ds_read_b128 v[144:147], v0 offset:2048
	ds_read_b128 v[148:151], v0 offset:3072
	s_cmp_eq_u32 s21, 40
	s_cselect_b32 s5, s17, s5
	s_cselect_b32 s4, s16, s4
	s_cselect_b32 s23, s19, s7
	s_cselect_b32 s22, s18, s6
	s_add_i32 m0, s26, 0xc000
	ds_read_b128 v[152:155], v195
	ds_read_b128 v[156:159], v195 offset:1024
	ds_read_b128 v[160:163], v195 offset:2048
	ds_read_b128 v[164:167], v195 offset:3072
	ds_read_b128 v[176:179], v195 offset:4096
	ds_read_b128 v[180:183], v195 offset:5120
	ds_read_b128 v[196:199], v195 offset:6144
	ds_read_b128 v[200:203], v195 offset:7168
	global_load_lds_dwordx4 v174, s[2:3]
	s_add_i32 m0, s26, 0xe000
	s_nop 0
	s_add_u32 vcc_lo, s2, s86
	s_addc_u32 vcc_hi, s3, s87
	global_load_lds_dwordx4 v174, vcc
	s_waitcnt lgkmcnt(8)
	s_cmp_eq_u32 s101, 1
	s_cbranch_scc1 .Ldb_FFO_sk
	s_barrier
.Ldb_FFO_sk:
	s_mov_b32 s101, 0
	s_waitcnt lgkmcnt(0)
	v_mfma_f32_16x16x32_bf16 v[132:135], v[136:139], v[152:155], v[132:135]
	v_mfma_f32_16x16x32_bf16 v[128:131], v[144:147], v[152:155], v[128:131]
	v_mfma_f32_16x16x32_bf16 v[116:119], v[136:139], v[160:163], v[116:119]
	v_mfma_f32_16x16x32_bf16 v[112:115], v[144:147], v[160:163], v[112:115]
	v_mfma_f32_16x16x32_bf16 v[100:103], v[136:139], v[176:179], v[100:103]
	v_mfma_f32_16x16x32_bf16 v[96:99], v[144:147], v[176:179], v[96:99]
	v_mfma_f32_16x16x32_bf16 v[84:87], v[136:139], v[196:199], v[84:87]
	v_mfma_f32_16x16x32_bf16 v[80:83], v[144:147], v[196:199], v[80:83]
	v_mfma_f32_16x16x32_bf16 v[132:135], v[140:143], v[156:159], v[132:135]
	v_mfma_f32_16x16x32_bf16 v[128:131], v[148:151], v[156:159], v[128:131]
	v_mfma_f32_16x16x32_bf16 v[116:119], v[140:143], v[164:167], v[116:119]
	v_mfma_f32_16x16x32_bf16 v[112:115], v[148:151], v[164:167], v[112:115]
	v_mfma_f32_16x16x32_bf16 v[100:103], v[140:143], v[180:183], v[100:103]
	v_mfma_f32_16x16x32_bf16 v[96:99], v[148:151], v[180:183], v[96:99]
	v_mfma_f32_16x16x32_bf16 v[84:87], v[140:143], v[200:203], v[84:87]
	v_mfma_f32_16x16x32_bf16 v[80:83], v[148:151], v[200:203], v[80:83]
	s_barrier
	s_add_i32 s44, 0, 0x14000
	s_add_i32 s100, s33, s25
	v_add_u32_e32 v0, s44, v185
	s_mov_b32 m0, s100
	ds_read_b128 v[204:207], v0
	ds_read_b128 v[208:211], v0 offset:1024
	ds_read_b128 v[212:215], v0 offset:2048
	ds_read_b128 v[216:219], v0 offset:3072
	global_load_lds_dwordx4 v172, s[22:23]
	s_add_i32 m0, s100, 0x2000
	s_nop 0
	s_add_u32 vcc_lo, s22, s86
	s_addc_u32 vcc_hi, s23, s87
	global_load_lds_dwordx4 v172, vcc
	s_barrier
	s_waitcnt lgkmcnt(0)
	v_mfma_f32_16x16x32_bf16 v[124:127], v[204:207], v[152:155], v[124:127]
	v_mfma_f32_16x16x32_bf16 v[120:123], v[212:215], v[152:155], v[120:123]
	v_mfma_f32_16x16x32_bf16 v[108:111], v[204:207], v[160:163], v[108:111]
	v_mfma_f32_16x16x32_bf16 v[104:107], v[212:215], v[160:163], v[104:107]
	v_mfma_f32_16x16x32_bf16 v[92:95], v[204:207], v[176:179], v[92:95]
	v_mfma_f32_16x16x32_bf16 v[88:91], v[212:215], v[176:179], v[88:91]
	v_mfma_f32_16x16x32_bf16 v[76:79], v[204:207], v[196:199], v[76:79]
	v_mfma_f32_16x16x32_bf16 v[72:75], v[212:215], v[196:199], v[72:75]
	v_mfma_f32_16x16x32_bf16 v[124:127], v[208:211], v[156:159], v[124:127]
	v_mfma_f32_16x16x32_bf16 v[120:123], v[216:219], v[156:159], v[120:123]
	v_mfma_f32_16x16x32_bf16 v[108:111], v[208:211], v[164:167], v[108:111]
	v_mfma_f32_16x16x32_bf16 v[104:107], v[216:219], v[164:167], v[104:107]
	v_mfma_f32_16x16x32_bf16 v[92:95], v[208:211], v[180:183], v[92:95]
	v_mfma_f32_16x16x32_bf16 v[88:91], v[216:219], v[180:183], v[88:91]
	v_mfma_f32_16x16x32_bf16 v[76:79], v[208:211], v[200:203], v[76:79]
	v_mfma_f32_16x16x32_bf16 v[72:75], v[216:219], v[200:203], v[72:75]
	s_barrier
	s_mov_b32 m0, s26
	v_lshl_add_u64 v[222:223], s[4:5], 0, v[2:3]
	ds_read_b128 v[152:155], v195 offset:16384
	ds_read_b128 v[156:159], v195 offset:17408
	ds_read_b128 v[160:163], v195 offset:18432
	ds_read_b128 v[164:167], v195 offset:19456
	ds_read_b128 v[176:179], v195 offset:20480
	ds_read_b128 v[180:183], v195 offset:21504
	ds_read_b128 v[196:199], v195 offset:22528
	ds_read_b128 v[200:203], v195 offset:23552
	global_load_lds_dwordx4 v2, s[4:5]
	s_mov_b32 m0, s27
	s_nop 0
	s_add_u32 vcc_lo, s4, s86
	s_addc_u32 vcc_hi, s5, s87
	global_load_lds_dwordx4 v2, vcc
	s_barrier
	s_waitcnt lgkmcnt(0)
	v_mfma_f32_16x16x32_bf16 v[68:71], v[136:139], v[152:155], v[68:71]
	v_mfma_f32_16x16x32_bf16 v[64:67], v[144:147], v[152:155], v[64:67]
	v_mfma_f32_16x16x32_bf16 v[52:55], v[136:139], v[160:163], v[52:55]
	v_mfma_f32_16x16x32_bf16 v[48:51], v[144:147], v[160:163], v[48:51]
	v_mfma_f32_16x16x32_bf16 v[36:39], v[136:139], v[176:179], v[36:39]
	v_mfma_f32_16x16x32_bf16 v[32:35], v[144:147], v[176:179], v[32:35]
	v_mfma_f32_16x16x32_bf16 v[20:23], v[136:139], v[196:199], v[20:23]
	v_mfma_f32_16x16x32_bf16 v[16:19], v[144:147], v[196:199], v[16:19]
	v_mfma_f32_16x16x32_bf16 v[68:71], v[140:143], v[156:159], v[68:71]
	v_mfma_f32_16x16x32_bf16 v[64:67], v[148:151], v[156:159], v[64:67]
	v_mfma_f32_16x16x32_bf16 v[52:55], v[140:143], v[164:167], v[52:55]
	v_mfma_f32_16x16x32_bf16 v[48:51], v[148:151], v[164:167], v[48:51]
	v_mfma_f32_16x16x32_bf16 v[36:39], v[140:143], v[180:183], v[36:39]
	v_mfma_f32_16x16x32_bf16 v[32:35], v[148:151], v[180:183], v[32:35]
	v_mfma_f32_16x16x32_bf16 v[20:23], v[140:143], v[200:203], v[20:23]
	v_mfma_f32_16x16x32_bf16 v[16:19], v[148:151], v[200:203], v[16:19]
	s_barrier
; #define G_STAGE(bufoff, gbase, o0, h64) do { \
;         __builtin_amdgcn_global_load_lds((const unsigned*)((const char*)(gbase) + (o0)), (LAS unsigned*)(lds + (bufoff) + ldsw), 16, 0, 0); \
;         __builtin_amdgcn_global_load_lds((const unsigned*)((const char*)(gbase) + (h64) + (o0)), (LAS unsigned*)(lds + (bufoff) + ldsw + 8192), 16, 0, 0); } while (0)
; #define G_LDA(dst, b, h) do { _Pragma("unroll") for (int m = 0; m < 4; ++m) _Pragma("unroll") for (int k = 0; k < 2; ++k) dst[m][k] = *(const LAS bf16x8*)(lds + G_SA(b, h) + aoff + m * 2048 + k * 1024); } while (0)
; #define G_LDB(dst, b, h) do { _Pragma("unroll") for (int n = 0; n < 2; ++n) _Pragma("unroll") for (int k = 0; k < 2; ++k) dst[n][k] = *(const LAS bf16x8*)(lds + G_SB(b, h) + boff + n * 2048 + k * 1024); } while (0)
; #define G_WAIT_V(n) asm volatile("s_waitcnt vmcnt(" #n ")" ::: "memory")
; #define G_WAIT_L(n) asm volatile("s_waitcnt lgkmcnt(" #n ")" ::: "memory")
; #define G_BAR __builtin_amdgcn_s_barrier()
; #define G_SCHED __builtin_amdgcn_sched_barrier(0)
;     ...
;             G_STAGE(G_SB(0, 1), b2 + chB, cB0, qB);
;             G_WAIT_V(6); G_BAR; G_MMA(1, 1, At, B1); G_BAR;
;             G_LDB(B0, 1, 0); G_SCHED; G_LDA(At, 1, 0); G_STAGE(G_SA(0, 1), a2 + chA, cA0, qA);
;             G_WAIT_L(8); G_BAR; G_WAIT_L(0); G_MMA(0, 0, At, B0); G_BAR; G_SCHED;
;             G_LDB(B1, 1, 1); G_STAGE(G_SB(1, 0), b3, cB0, qB);
	s_add_i32 s100, s44, s25
	s_mov_b32 m0, s100
	s_nop 0
	s_add_u32 vcc_lo, s22, s88
	s_addc_u32 vcc_hi, s23, s89
	global_load_lds_dwordx4 v172, vcc
	s_add_i32 m0, s100, 0x2000
	s_nop 0
	s_add_u32 vcc_lo, s22, s64
	s_addc_u32 vcc_hi, s23, s65
	global_load_lds_dwordx4 v172, vcc
	s_waitcnt vmcnt(6)
	s_barrier
	v_mfma_f32_16x16x32_bf16 v[60:63], v[204:207], v[152:155], v[60:63]
	v_mfma_f32_16x16x32_bf16 v[56:59], v[212:215], v[152:155], v[56:59]
	v_mfma_f32_16x16x32_bf16 v[44:47], v[204:207], v[160:163], v[44:47]
	v_mfma_f32_16x16x32_bf16 v[40:43], v[212:215], v[160:163], v[40:43]
	v_mfma_f32_16x16x32_bf16 v[28:31], v[204:207], v[176:179], v[28:31]
	v_mfma_f32_16x16x32_bf16 v[24:27], v[212:215], v[176:179], v[24:27]
	v_mfma_f32_16x16x32_bf16 v[12:15], v[204:207], v[196:199], v[12:15]
	v_mfma_f32_16x16x32_bf16 v[8:11], v[212:215], v[196:199], v[8:11]
	v_mfma_f32_16x16x32_bf16 v[60:63], v[208:211], v[156:159], v[60:63]
	v_mfma_f32_16x16x32_bf16 v[56:59], v[216:219], v[156:159], v[56:59]
	v_mfma_f32_16x16x32_bf16 v[44:47], v[208:211], v[164:167], v[44:47]
	v_mfma_f32_16x16x32_bf16 v[40:43], v[216:219], v[164:167], v[40:43]
	v_mfma_f32_16x16x32_bf16 v[28:31], v[208:211], v[180:183], v[28:31]
	v_mfma_f32_16x16x32_bf16 v[24:27], v[216:219], v[180:183], v[24:27]
	v_mfma_f32_16x16x32_bf16 v[12:15], v[208:211], v[200:203], v[12:15]
	v_mfma_f32_16x16x32_bf16 v[8:11], v[216:219], v[200:203], v[8:11]
	s_barrier
	s_add_i32 s100, 0, 0x18000
	v_add_u32_e32 v0, s100, v185
	ds_read_b128 v[136:139], v0
	ds_read_b128 v[140:143], v0 offset:1024
	ds_read_b128 v[144:147], v0 offset:2048
	ds_read_b128 v[148:151], v0 offset:3072
	s_mov_b32 m0, s29
	ds_read_b128 v[152:155], v195 offset:32768
	ds_read_b128 v[156:159], v195 offset:33792
	ds_read_b128 v[160:163], v195 offset:34816
	ds_read_b128 v[164:167], v195 offset:35840
	ds_read_b128 v[176:179], v195 offset:36864
	ds_read_b128 v[180:183], v195 offset:37888
	ds_read_b128 v[196:199], v195 offset:38912
	ds_read_b128 v[200:203], v195 offset:39936
	s_add_u32 vcc_lo, s4, s88
	s_addc_u32 vcc_hi, s5, s89
	global_load_lds_dwordx4 v2, vcc
	s_mov_b32 m0, s30
	s_nop 0
	s_add_u32 vcc_lo, s4, s64
	s_addc_u32 vcc_hi, s5, s65
	global_load_lds_dwordx4 v2, vcc
	s_waitcnt lgkmcnt(8)
	s_barrier
	s_waitcnt lgkmcnt(0)
	v_mfma_f32_16x16x32_bf16 v[132:135], v[136:139], v[152:155], v[132:135]
	v_mfma_f32_16x16x32_bf16 v[128:131], v[144:147], v[152:155], v[128:131]
	v_mfma_f32_16x16x32_bf16 v[116:119], v[136:139], v[160:163], v[116:119]
	v_mfma_f32_16x16x32_bf16 v[112:115], v[144:147], v[160:163], v[112:115]
	v_mfma_f32_16x16x32_bf16 v[100:103], v[136:139], v[176:179], v[100:103]
	v_mfma_f32_16x16x32_bf16 v[96:99], v[144:147], v[176:179], v[96:99]
	v_mfma_f32_16x16x32_bf16 v[84:87], v[136:139], v[196:199], v[84:87]
	v_mfma_f32_16x16x32_bf16 v[80:83], v[144:147], v[196:199], v[80:83]
	v_mfma_f32_16x16x32_bf16 v[132:135], v[140:143], v[156:159], v[132:135]
	v_mfma_f32_16x16x32_bf16 v[128:131], v[148:151], v[156:159], v[128:131]
	v_mfma_f32_16x16x32_bf16 v[116:119], v[140:143], v[164:167], v[116:119]
	v_mfma_f32_16x16x32_bf16 v[112:115], v[148:151], v[164:167], v[112:115]
	v_mfma_f32_16x16x32_bf16 v[100:103], v[140:143], v[180:183], v[100:103]
	v_mfma_f32_16x16x32_bf16 v[96:99], v[148:151], v[180:183], v[96:99]
	v_mfma_f32_16x16x32_bf16 v[84:87], v[140:143], v[200:203], v[84:87]
	v_mfma_f32_16x16x32_bf16 v[80:83], v[148:151], v[200:203], v[80:83]
	s_barrier
	s_add_i32 s5, 0, 0x1c000
	s_add_i32 s4, s100, s25
	v_add_u32_e32 v0, s5, v185
	s_mov_b32 m0, s4
	ds_read_b128 v[204:207], v0
	ds_read_b128 v[208:211], v0 offset:1024
	ds_read_b128 v[212:215], v0 offset:2048
	ds_read_b128 v[216:219], v0 offset:3072
	s_add_u32 vcc_lo, s22, s46
	s_addc_u32 vcc_hi, s23, s47
	global_load_lds_dwordx4 v172, vcc
	s_add_i32 m0, s4, 0x2000
	s_nop 0
	s_add_u32 vcc_lo, s22, s66
	s_addc_u32 vcc_hi, s23, s67
	global_load_lds_dwordx4 v172, vcc
	s_barrier
; #define G_STAGE(bufoff, gbase, o0, h64) do { \
;         __builtin_amdgcn_global_load_lds((const unsigned*)((const char*)(gbase) + (o0)), (LAS unsigned*)(lds + (bufoff) + ldsw), 16, 0, 0); \
;         __builtin_amdgcn_global_load_lds((const unsigned*)((const char*)(gbase) + (h64) + (o0)), (LAS unsigned*)(lds + (bufoff) + ldsw + 8192), 16, 0, 0); } while (0)
; #define G_LDA(dst, b, h) do { _Pragma("unroll") for (int m = 0; m < 4; ++m) _Pragma("unroll") for (int k = 0; k < 2; ++k) dst[m][k] = *(const LAS bf16x8*)(lds + G_SA(b, h) + aoff + m * 2048 + k * 1024); } while (0)
; #define G_WAIT_V(n) asm volatile("s_waitcnt vmcnt(" #n ")" ::: "memory")
; #define G_WAIT_L(n) asm volatile("s_waitcnt lgkmcnt(" #n ")" ::: "memory")
; #define G_BAR __builtin_amdgcn_s_barrier()
; #define G_SCHED __builtin_amdgcn_sched_barrier(0)
;     ...
;             G_BAR; G_WAIT_L(0); G_MMA(0, 1, At, B1); G_BAR;
;             G_LDA(At, 1, 1); G_STAGE(G_SA(1, 0), a3, cA0, qA);
;             G_BAR; G_WAIT_L(0); G_MMA(1, 0, At, B0); G_BAR; G_SCHED;
;             G_STAGE(G_SB(1, 1), b3 + chB, cB0, qB);
;             G_WAIT_V(6); G_BAR; G_MMA(1, 1, At, B1); G_BAR;
	s_waitcnt lgkmcnt(0)
	v_mfma_f32_16x16x32_bf16 v[124:127], v[204:207], v[152:155], v[124:127]
	v_mfma_f32_16x16x32_bf16 v[120:123], v[212:215], v[152:155], v[120:123]
	v_mfma_f32_16x16x32_bf16 v[108:111], v[204:207], v[160:163], v[108:111]
	v_mfma_f32_16x16x32_bf16 v[104:107], v[212:215], v[160:163], v[104:107]
	v_mfma_f32_16x16x32_bf16 v[92:95], v[204:207], v[176:179], v[92:95]
	v_mfma_f32_16x16x32_bf16 v[88:91], v[212:215], v[176:179], v[88:91]
	v_mfma_f32_16x16x32_bf16 v[76:79], v[204:207], v[196:199], v[76:79]
	v_mfma_f32_16x16x32_bf16 v[72:75], v[212:215], v[196:199], v[72:75]
	v_mfma_f32_16x16x32_bf16 v[124:127], v[208:211], v[156:159], v[124:127]
	v_mfma_f32_16x16x32_bf16 v[120:123], v[216:219], v[156:159], v[120:123]
	v_mfma_f32_16x16x32_bf16 v[108:111], v[208:211], v[164:167], v[108:111]
	v_mfma_f32_16x16x32_bf16 v[104:107], v[216:219], v[164:167], v[104:107]
	v_mfma_f32_16x16x32_bf16 v[92:95], v[208:211], v[180:183], v[92:95]
	v_mfma_f32_16x16x32_bf16 v[88:91], v[216:219], v[180:183], v[88:91]
	v_mfma_f32_16x16x32_bf16 v[76:79], v[208:211], v[200:203], v[76:79]
	v_mfma_f32_16x16x32_bf16 v[72:75], v[216:219], v[200:203], v[72:75]
	s_barrier
	s_mov_b32 m0, s31
	v_lshl_add_u64 v[224:225], v[222:223], 0, s[46:47]
	ds_read_b128 v[152:155], v195 offset:49152
	ds_read_b128 v[156:159], v195 offset:50176
	ds_read_b128 v[160:163], v195 offset:51200
	ds_read_b128 v[164:167], v195 offset:52224
	ds_read_b128 v[176:179], v195 offset:53248
	ds_read_b128 v[180:183], v195 offset:54272
	ds_read_b128 v[196:199], v195 offset:55296
	ds_read_b128 v[200:203], v195 offset:56320
	global_load_lds_dwordx4 v[224:225], off
	v_lshl_add_u64 v[222:223], v[222:223], 0, s[66:67]
	s_mov_b32 m0, s34
	s_nop 0
	global_load_lds_dwordx4 v[222:223], off
	s_barrier
	s_waitcnt lgkmcnt(0)
	v_mfma_f32_16x16x32_bf16 v[68:71], v[136:139], v[152:155], v[68:71]
	v_mfma_f32_16x16x32_bf16 v[64:67], v[144:147], v[152:155], v[64:67]
	v_mfma_f32_16x16x32_bf16 v[52:55], v[136:139], v[160:163], v[52:55]
	v_mfma_f32_16x16x32_bf16 v[48:51], v[144:147], v[160:163], v[48:51]
	v_mfma_f32_16x16x32_bf16 v[36:39], v[136:139], v[176:179], v[36:39]
	v_mfma_f32_16x16x32_bf16 v[32:35], v[144:147], v[176:179], v[32:35]
	v_mfma_f32_16x16x32_bf16 v[20:23], v[136:139], v[196:199], v[20:23]
	v_mfma_f32_16x16x32_bf16 v[16:19], v[144:147], v[196:199], v[16:19]
	v_mfma_f32_16x16x32_bf16 v[68:71], v[140:143], v[156:159], v[68:71]
	v_mfma_f32_16x16x32_bf16 v[64:67], v[148:151], v[156:159], v[64:67]
	v_mfma_f32_16x16x32_bf16 v[52:55], v[140:143], v[164:167], v[52:55]
	v_mfma_f32_16x16x32_bf16 v[48:51], v[148:151], v[164:167], v[48:51]
	v_mfma_f32_16x16x32_bf16 v[36:39], v[140:143], v[180:183], v[36:39]
	v_mfma_f32_16x16x32_bf16 v[32:35], v[148:151], v[180:183], v[32:35]
	v_mfma_f32_16x16x32_bf16 v[20:23], v[140:143], v[200:203], v[20:23]
	v_mfma_f32_16x16x32_bf16 v[16:19], v[148:151], v[200:203], v[16:19]
	s_barrier
	s_add_i32 s4, s5, s25
	s_mov_b32 m0, s4
	s_nop 0
	s_add_u32 vcc_lo, s22, s52
	s_addc_u32 vcc_hi, s23, s53
	global_load_lds_dwordx4 v172, vcc
	s_add_i32 m0, s4, 0x2000
	s_nop 0
	s_add_u32 vcc_lo, s22, s54
	s_addc_u32 vcc_hi, s23, s55
	global_load_lds_dwordx4 v172, vcc
	s_add_i32 s21, s21, 2
	s_add_u32 s2, s2, 0x100
	s_addc_u32 s3, s3, 0
	s_add_u32 s6, s6, 0x100
	s_addc_u32 s7, s7, 0
	s_cmp_gt_u32 s21, 41
	s_waitcnt vmcnt(6)
	s_barrier
	v_mfma_f32_16x16x32_bf16 v[60:63], v[204:207], v[152:155], v[60:63]
	v_mfma_f32_16x16x32_bf16 v[56:59], v[212:215], v[152:155], v[56:59]
	v_mfma_f32_16x16x32_bf16 v[44:47], v[204:207], v[160:163], v[44:47]
	v_mfma_f32_16x16x32_bf16 v[40:43], v[212:215], v[160:163], v[40:43]
	v_mfma_f32_16x16x32_bf16 v[28:31], v[204:207], v[176:179], v[28:31]
	v_mfma_f32_16x16x32_bf16 v[24:27], v[212:215], v[176:179], v[24:27]
	v_mfma_f32_16x16x32_bf16 v[12:15], v[204:207], v[196:199], v[12:15]
	v_mfma_f32_16x16x32_bf16 v[8:11], v[212:215], v[196:199], v[8:11]
	v_mfma_f32_16x16x32_bf16 v[60:63], v[208:211], v[156:159], v[60:63]
	v_mfma_f32_16x16x32_bf16 v[56:59], v[216:219], v[156:159], v[56:59]
	v_mfma_f32_16x16x32_bf16 v[44:47], v[208:211], v[164:167], v[44:47]
	v_mfma_f32_16x16x32_bf16 v[40:43], v[216:219], v[164:167], v[40:43]
	v_mfma_f32_16x16x32_bf16 v[28:31], v[208:211], v[180:183], v[28:31]
	v_mfma_f32_16x16x32_bf16 v[24:27], v[216:219], v[180:183], v[24:27]
	v_mfma_f32_16x16x32_bf16 v[12:15], v[208:211], v[200:203], v[12:15]
	v_mfma_f32_16x16x32_bf16 v[8:11], v[216:219], v[200:203], v[8:11]
	s_cbranch_scc0 .Ldb_FFO_cont
	v_readfirstlane_b32 s101, v186
	s_cmpk_gt_u32 s101, 0xff
	s_cbranch_scc1 .Ldb_FFO_young
	s_barrier
	s_mov_b32 s101, 1
	s_branch .Ldb_FFO_exit

; #define G_STAGE(bufoff, gbase, o0, h64) do { \
;         __builtin_amdgcn_global_load_lds((const unsigned*)((const char*)(gbase) + (o0)), (LAS unsigned*)(lds + (bufoff) + ldsw), 16, 0, 0); \
;         __builtin_amdgcn_global_load_lds((const unsigned*)((const char*)(gbase) + (h64) + (o0)), (LAS unsigned*)(lds + (bufoff) + ldsw + 8192), 16, 0, 0); } while (0)
; #define G_LDA(dst, b, h) do { _Pragma("unroll") for (int m = 0; m < 4; ++m) _Pragma("unroll") for (int k = 0; k < 2; ++k) dst[m][k] = *(const LAS bf16x8*)(lds + G_SA(b, h) + aoff + m * 2048 + k * 1024); } while (0)
; #define G_LDB(dst, b, h) do { _Pragma("unroll") for (int n = 0; n < 2; ++n) _Pragma("unroll") for (int k = 0; k < 2; ++k) dst[n][k] = *(const LAS bf16x8*)(lds + G_SB(b, h) + boff + n * 2048 + k * 1024); } while (0)
; #define G_WAIT_L(n) asm volatile("s_waitcnt lgkmcnt(" #n ")" ::: "memory")
; #define G_BAR __builtin_amdgcn_s_barrier()
; #define G_SCHED __builtin_amdgcn_sched_barrier(0)
;     ...
;             const bool last = (t == nt - 2);
;             const char* a1 = cA + (size_t)(t + 1) * ckA;
;             const char* a2 = last ? nA : cA + (size_t)(t + 2) * ckA; const char* b2 = last ? nB : cB + (size_t)(t + 2) * kB;
;             const char* a3 = a2 + ckA; const char* b3 = b2 + kB;
;             G_LDB(B0, 0, 0); G_SCHED; G_LDA(At, 0, 0); G_STAGE(G_SA(1, 1), a1 + chA, cA0, qA);
;             G_WAIT_L(8); G_BAR; G_WAIT_L(0); G_MMA(0, 0, At, B0); G_BAR; G_SCHED;
;             G_LDB(B1, 0, 1); G_STAGE(G_SB(0, 0), b2, cB0, qB);
;             G_BAR; G_WAIT_L(0); G_MMA(0, 1, At, B1); G_BAR;
;             G_LDA(At, 0, 1); G_STAGE(G_SA(0, 0), a2, cA0, qA);
.LBB0_1260:
	s_add_u32 s22, s10, s18
	s_addc_u32 s23, s11, s19
	s_add_u32 s20, s22, 0x100
	s_addc_u32 s21, s23, 0
	s_and_b64 s[4:5], s[16:17], exec
	s_cselect_b32 s20, s6, s20
	s_cselect_b32 s21, s7, s21
	s_add_u32 s4, s12, s18
	s_addc_u32 s5, s13, s19
	s_add_u32 s18, s4, 0x100
	s_addc_u32 s19, s5, 0
	s_add_i32 s44, 0, 0x10000
	v_add_u32_e32 v139, s44, v137
	ds_read_b128 v[140:143], v139
	ds_read_b128 v[144:147], v139 offset:1024
	ds_read_b128 v[148:151], v139 offset:2048
	ds_read_b128 v[152:155], v139 offset:3072
	s_and_b64 s[4:5], s[16:17], exec
	s_cselect_b32 s16, s8, s18
	s_cselect_b32 s17, s9, s19
	s_add_i32 s5, 0, 0x14000
	s_add_i32 s43, 0, 0x18000
	s_add_i32 s18, 0, 0x1c000
	s_add_i32 s45, s44, s25
	s_add_i32 s51, s5, s25
	s_add_i32 s19, s43, s25
	s_add_i32 s53, s18, s25
	s_mov_b64 s[64:65], 0x8000
	s_mov_b64 s[62:63], 0x10080
	s_add_i32 m0, s31, 0xc000
	s_add_i32 s4, s31, 0xe000
	s_add_i32 s54, s45, 0x2000
	s_add_i32 s50, s51, 0x2000
	s_add_i32 s44, s19, 0x2000
	s_add_i32 s52, s53, 0x2000
	ds_read_b128 v[156:159], v138
	ds_read_b128 v[160:163], v138 offset:1024
	ds_read_b128 v[164:167], v138 offset:2048
	ds_read_b128 v[172:175], v138 offset:3072
	ds_read_b128 v[176:179], v138 offset:4096
	ds_read_b128 v[180:183], v138 offset:5120
	ds_read_b128 v[196:199], v138 offset:6144
	ds_read_b128 v[200:203], v138 offset:7168
	s_add_u32 vcc_lo, s22, s62
	s_addc_u32 vcc_hi, s23, s63
	global_load_lds_dwordx4 v2, vcc
	s_mov_b32 m0, s4
	s_nop 0
	s_add_u32 vcc_lo, s22, s68
	s_addc_u32 vcc_hi, s23, s69
	global_load_lds_dwordx4 v2, vcc
	s_waitcnt lgkmcnt(8)
	s_cmp_eq_u32 s101, 1
	s_cbranch_scc1 .Ldb_PLE0_sk
	s_barrier
.Ldb_PLE0_sk:
	s_mov_b32 s101, 0
	s_waitcnt lgkmcnt(0)
	v_mfma_f32_16x16x32_bf16 v[132:135], v[140:143], v[156:159], v[132:135]
	v_mfma_f32_16x16x32_bf16 v[128:131], v[148:151], v[156:159], v[128:131]
	v_mfma_f32_16x16x32_bf16 v[124:127], v[140:143], v[164:167], v[124:127]
	v_mfma_f32_16x16x32_bf16 v[116:119], v[148:151], v[164:167], v[116:119]
	v_mfma_f32_16x16x32_bf16 v[108:111], v[140:143], v[176:179], v[108:111]
	v_mfma_f32_16x16x32_bf16 v[100:103], v[148:151], v[176:179], v[100:103]
	v_mfma_f32_16x16x32_bf16 v[92:95], v[140:143], v[196:199], v[92:95]
	v_mfma_f32_16x16x32_bf16 v[84:87], v[148:151], v[196:199], v[84:87]
	v_mfma_f32_16x16x32_bf16 v[132:135], v[144:147], v[160:163], v[132:135]
	v_mfma_f32_16x16x32_bf16 v[128:131], v[152:155], v[160:163], v[128:131]
	v_mfma_f32_16x16x32_bf16 v[124:127], v[144:147], v[172:175], v[124:127]
	v_mfma_f32_16x16x32_bf16 v[116:119], v[152:155], v[172:175], v[116:119]
	v_mfma_f32_16x16x32_bf16 v[108:111], v[144:147], v[180:183], v[108:111]
	v_mfma_f32_16x16x32_bf16 v[100:103], v[152:155], v[180:183], v[100:103]
	v_mfma_f32_16x16x32_bf16 v[92:95], v[144:147], v[200:203], v[92:95]
	v_mfma_f32_16x16x32_bf16 v[84:87], v[152:155], v[200:203], v[84:87]
	s_barrier
	s_mov_b32 m0, s45
	v_add_u32_e32 v139, s5, v137
	v_lshl_add_u64 v[184:185], s[16:17], 0, v[0:1]
	ds_read_b128 v[204:207], v139
	ds_read_b128 v[208:211], v139 offset:1024
	ds_read_b128 v[212:215], v139 offset:2048
	ds_read_b128 v[216:219], v139 offset:3072
	global_load_lds_dwordx4 v0, s[16:17]
	s_mov_b32 m0, s54
	s_nop 0
	s_add_u32 vcc_lo, s16, s64
	s_addc_u32 vcc_hi, s17, s65
	global_load_lds_dwordx4 v0, vcc
	s_barrier
	s_waitcnt lgkmcnt(0)
	v_mfma_f32_16x16x32_bf16 v[120:123], v[204:207], v[156:159], v[120:123]
	v_mfma_f32_16x16x32_bf16 v[112:115], v[212:215], v[156:159], v[112:115]
	v_mfma_f32_16x16x32_bf16 v[104:107], v[204:207], v[164:167], v[104:107]
	v_mfma_f32_16x16x32_bf16 v[96:99], v[212:215], v[164:167], v[96:99]
	v_mfma_f32_16x16x32_bf16 v[88:91], v[204:207], v[176:179], v[88:91]
	v_mfma_f32_16x16x32_bf16 v[80:83], v[212:215], v[176:179], v[80:83]
	v_mfma_f32_16x16x32_bf16 v[76:79], v[204:207], v[196:199], v[76:79]
	v_mfma_f32_16x16x32_bf16 v[72:75], v[212:215], v[196:199], v[72:75]
	v_mfma_f32_16x16x32_bf16 v[120:123], v[208:211], v[160:163], v[120:123]
	v_mfma_f32_16x16x32_bf16 v[112:115], v[216:219], v[160:163], v[112:115]
	v_mfma_f32_16x16x32_bf16 v[104:107], v[208:211], v[172:175], v[104:107]
	v_mfma_f32_16x16x32_bf16 v[96:99], v[216:219], v[172:175], v[96:99]
	v_mfma_f32_16x16x32_bf16 v[88:91], v[208:211], v[180:183], v[88:91]
	v_mfma_f32_16x16x32_bf16 v[80:83], v[216:219], v[180:183], v[80:83]
	v_mfma_f32_16x16x32_bf16 v[76:79], v[208:211], v[200:203], v[76:79]
	v_mfma_f32_16x16x32_bf16 v[72:75], v[216:219], v[200:203], v[72:75]
	s_barrier
	s_mov_b32 m0, s31
	v_lshl_add_u64 v[220:221], s[20:21], 0, v[2:3]
	s_mov_b64 s[4:5], 0x8000
	ds_read_b128 v[156:159], v138 offset:16384
	ds_read_b128 v[160:163], v138 offset:17408
	ds_read_b128 v[164:167], v138 offset:18432
	ds_read_b128 v[172:175], v138 offset:19456
	ds_read_b128 v[176:179], v138 offset:20480
	ds_read_b128 v[180:183], v138 offset:21504
	ds_read_b128 v[196:199], v138 offset:22528
	ds_read_b128 v[200:203], v138 offset:23552
	global_load_lds_dwordx4 v2, s[20:21]
	s_mov_b32 m0, s33
	s_mov_b64 s[16:17], 0x18000
	s_add_u32 vcc_lo, s20, s4
	s_addc_u32 vcc_hi, s21, s5
	global_load_lds_dwordx4 v2, vcc
	s_barrier
; #define G_STAGE(bufoff, gbase, o0, h64) do { \
;         __builtin_amdgcn_global_load_lds((const unsigned*)((const char*)(gbase) + (o0)), (LAS unsigned*)(lds + (bufoff) + ldsw), 16, 0, 0); \
;         __builtin_amdgcn_global_load_lds((const unsigned*)((const char*)(gbase) + (h64) + (o0)), (LAS unsigned*)(lds + (bufoff) + ldsw + 8192), 16, 0, 0); } while (0)
; #define G_LDA(dst, b, h) do { _Pragma("unroll") for (int m = 0; m < 4; ++m) _Pragma("unroll") for (int k = 0; k < 2; ++k) dst[m][k] = *(const LAS bf16x8*)(lds + G_SA(b, h) + aoff + m * 2048 + k * 1024); } while (0)
; #define G_LDB(dst, b, h) do { _Pragma("unroll") for (int n = 0; n < 2; ++n) _Pragma("unroll") for (int k = 0; k < 2; ++k) dst[n][k] = *(const LAS bf16x8*)(lds + G_SB(b, h) + boff + n * 2048 + k * 1024); } while (0)
; #define G_WAIT_V(n) asm volatile("s_waitcnt vmcnt(" #n ")" ::: "memory")
; #define G_WAIT_L(n) asm volatile("s_waitcnt lgkmcnt(" #n ")" ::: "memory")
; #define G_BAR __builtin_amdgcn_s_barrier()
; #define G_SCHED __builtin_amdgcn_sched_barrier(0)
;     ...
;             G_BAR; G_WAIT_L(0); G_MMA(1, 0, At, B0); G_BAR; G_SCHED;
;             G_STAGE(G_SB(0, 1), b2 + chB, cB0, qB);
;             G_WAIT_V(6); G_BAR; G_MMA(1, 1, At, B1); G_BAR;
;             G_LDB(B0, 1, 0); G_SCHED; G_LDA(At, 1, 0); G_STAGE(G_SA(0, 1), a2 + chA, cA0, qA);
;             G_WAIT_L(8); G_BAR; G_WAIT_L(0); G_MMA(0, 0, At, B0); G_BAR; G_SCHED;
	s_waitcnt lgkmcnt(0)
	s_mov_b64 s[20:21], 0x8080
	s_waitcnt lgkmcnt(0)
	v_mfma_f32_16x16x32_bf16 v[68:71], v[140:143], v[156:159], v[68:71]
	v_mfma_f32_16x16x32_bf16 v[64:67], v[148:151], v[156:159], v[64:67]
	v_mfma_f32_16x16x32_bf16 v[60:63], v[140:143], v[164:167], v[60:63]
	v_mfma_f32_16x16x32_bf16 v[52:55], v[148:151], v[164:167], v[52:55]
	v_mfma_f32_16x16x32_bf16 v[44:47], v[140:143], v[176:179], v[44:47]
	v_mfma_f32_16x16x32_bf16 v[36:39], v[148:151], v[176:179], v[36:39]
	v_mfma_f32_16x16x32_bf16 v[28:31], v[140:143], v[196:199], v[28:31]
	v_mfma_f32_16x16x32_bf16 v[20:23], v[148:151], v[196:199], v[20:23]
	v_mfma_f32_16x16x32_bf16 v[68:71], v[144:147], v[160:163], v[68:71]
	v_mfma_f32_16x16x32_bf16 v[64:67], v[152:155], v[160:163], v[64:67]
	v_mfma_f32_16x16x32_bf16 v[60:63], v[144:147], v[172:175], v[60:63]
	v_mfma_f32_16x16x32_bf16 v[52:55], v[152:155], v[172:175], v[52:55]
	v_mfma_f32_16x16x32_bf16 v[44:47], v[144:147], v[180:183], v[44:47]
	v_mfma_f32_16x16x32_bf16 v[36:39], v[152:155], v[180:183], v[36:39]
	v_mfma_f32_16x16x32_bf16 v[28:31], v[144:147], v[200:203], v[28:31]
	v_mfma_f32_16x16x32_bf16 v[20:23], v[152:155], v[200:203], v[20:23]
	s_barrier
	s_mov_b32 m0, s51
	v_lshl_add_u64 v[140:141], v[184:185], 0, s[58:59]
	global_load_lds_dwordx4 v[140:141], off
	v_lshl_add_u64 v[140:141], v[184:185], 0, s[16:17]
	s_mov_b32 m0, s50
	s_nop 0
	global_load_lds_dwordx4 v[140:141], off
	s_waitcnt vmcnt(6)
	s_barrier
	v_mfma_f32_16x16x32_bf16 v[56:59], v[204:207], v[156:159], v[56:59]
	v_mfma_f32_16x16x32_bf16 v[48:51], v[212:215], v[156:159], v[48:51]
	v_mfma_f32_16x16x32_bf16 v[40:43], v[204:207], v[164:167], v[40:43]
	v_mfma_f32_16x16x32_bf16 v[32:35], v[212:215], v[164:167], v[32:35]
	v_mfma_f32_16x16x32_bf16 v[24:27], v[204:207], v[176:179], v[24:27]
	v_mfma_f32_16x16x32_bf16 v[16:19], v[212:215], v[176:179], v[16:19]
	v_mfma_f32_16x16x32_bf16 v[12:15], v[204:207], v[196:199], v[12:15]
	v_mfma_f32_16x16x32_bf16 v[8:11], v[212:215], v[196:199], v[8:11]
	v_mfma_f32_16x16x32_bf16 v[56:59], v[208:211], v[160:163], v[56:59]
	v_mfma_f32_16x16x32_bf16 v[48:51], v[216:219], v[160:163], v[48:51]
	v_mfma_f32_16x16x32_bf16 v[40:43], v[208:211], v[172:175], v[40:43]
	v_mfma_f32_16x16x32_bf16 v[32:35], v[216:219], v[172:175], v[32:35]
	v_mfma_f32_16x16x32_bf16 v[24:27], v[208:211], v[180:183], v[24:27]
	v_mfma_f32_16x16x32_bf16 v[16:19], v[216:219], v[180:183], v[16:19]
	v_mfma_f32_16x16x32_bf16 v[12:15], v[208:211], v[200:203], v[12:15]
	v_mfma_f32_16x16x32_bf16 v[8:11], v[216:219], v[200:203], v[8:11]
	s_barrier
	v_add_u32_e32 v139, s43, v137
	ds_read_b128 v[140:143], v139
	ds_read_b128 v[144:147], v139 offset:1024
	ds_read_b128 v[148:151], v139 offset:2048
	ds_read_b128 v[152:155], v139 offset:3072
	s_mov_b32 m0, s34
	v_lshl_add_u64 v[204:205], v[220:221], 0, s[58:59]
	ds_read_b128 v[156:159], v138 offset:32768
	ds_read_b128 v[160:163], v138 offset:33792
	ds_read_b128 v[164:167], v138 offset:34816
	ds_read_b128 v[172:175], v138 offset:35840
	ds_read_b128 v[176:179], v138 offset:36864
	ds_read_b128 v[180:183], v138 offset:37888
	ds_read_b128 v[196:199], v138 offset:38912
	ds_read_b128 v[200:203], v138 offset:39936
	global_load_lds_dwordx4 v[204:205], off
	v_lshl_add_u64 v[204:205], v[220:221], 0, s[16:17]
	s_mov_b32 m0, s35
	s_nop 0
	global_load_lds_dwordx4 v[204:205], off
	s_waitcnt lgkmcnt(8)
	s_barrier
	s_waitcnt lgkmcnt(0)
	v_mfma_f32_16x16x32_bf16 v[132:135], v[140:143], v[156:159], v[132:135]
	v_mfma_f32_16x16x32_bf16 v[128:131], v[148:151], v[156:159], v[128:131]
	v_mfma_f32_16x16x32_bf16 v[124:127], v[140:143], v[164:167], v[124:127]
	v_mfma_f32_16x16x32_bf16 v[116:119], v[148:151], v[164:167], v[116:119]
	v_mfma_f32_16x16x32_bf16 v[108:111], v[140:143], v[176:179], v[108:111]
	v_mfma_f32_16x16x32_bf16 v[100:103], v[148:151], v[176:179], v[100:103]
	v_mfma_f32_16x16x32_bf16 v[92:95], v[140:143], v[196:199], v[92:95]
	v_mfma_f32_16x16x32_bf16 v[84:87], v[148:151], v[196:199], v[84:87]
	v_mfma_f32_16x16x32_bf16 v[132:135], v[144:147], v[160:163], v[132:135]
	v_mfma_f32_16x16x32_bf16 v[128:131], v[152:155], v[160:163], v[128:131]
	v_mfma_f32_16x16x32_bf16 v[124:127], v[144:147], v[172:175], v[124:127]
	v_mfma_f32_16x16x32_bf16 v[116:119], v[152:155], v[172:175], v[116:119]
	v_mfma_f32_16x16x32_bf16 v[108:111], v[144:147], v[180:183], v[108:111]
	v_mfma_f32_16x16x32_bf16 v[100:103], v[152:155], v[180:183], v[100:103]
	v_mfma_f32_16x16x32_bf16 v[92:95], v[144:147], v[200:203], v[92:95]
	v_mfma_f32_16x16x32_bf16 v[84:87], v[152:155], v[200:203], v[84:87]
	s_barrier
; #define G_STAGE(bufoff, gbase, o0, h64) do { \
;         __builtin_amdgcn_global_load_lds((const unsigned*)((const char*)(gbase) + (o0)), (LAS unsigned*)(lds + (bufoff) + ldsw), 16, 0, 0); \
;         __builtin_amdgcn_global_load_lds((const unsigned*)((const char*)(gbase) + (h64) + (o0)), (LAS unsigned*)(lds + (bufoff) + ldsw + 8192), 16, 0, 0); } while (0)
; #define G_LDA(dst, b, h) do { _Pragma("unroll") for (int m = 0; m < 4; ++m) _Pragma("unroll") for (int k = 0; k < 2; ++k) dst[m][k] = *(const LAS bf16x8*)(lds + G_SA(b, h) + aoff + m * 2048 + k * 1024); } while (0)
; #define G_LDB(dst, b, h) do { _Pragma("unroll") for (int n = 0; n < 2; ++n) _Pragma("unroll") for (int k = 0; k < 2; ++k) dst[n][k] = *(const LAS bf16x8*)(lds + G_SB(b, h) + boff + n * 2048 + k * 1024); } while (0)
; #define G_WAIT_V(n) asm volatile("s_waitcnt vmcnt(" #n ")" ::: "memory")
; #define G_WAIT_L(n) asm volatile("s_waitcnt lgkmcnt(" #n ")" ::: "memory")
; #define G_BAR __builtin_amdgcn_s_barrier()
; #define G_SCHED __builtin_amdgcn_sched_barrier(0)
;     ...
;             G_LDB(B1, 1, 1); G_STAGE(G_SB(1, 0), b3, cB0, qB);
;             G_BAR; G_WAIT_L(0); G_MMA(0, 1, At, B1); G_BAR;
;             G_LDA(At, 1, 1); G_STAGE(G_SA(1, 0), a3, cA0, qA);
;             G_BAR; G_WAIT_L(0); G_MMA(1, 0, At, B0); G_BAR; G_SCHED;
;             G_STAGE(G_SB(1, 1), b3 + chB, cB0, qB);
;             G_WAIT_V(6); G_BAR; G_MMA(1, 1, At, B1); G_BAR;
	s_mov_b32 m0, s19
	v_add_u32_e32 v139, s18, v137
	v_lshl_add_u64 v[222:223], v[184:185], 0, s[46:47]
	ds_read_b128 v[204:207], v139
	ds_read_b128 v[208:211], v139 offset:1024
	ds_read_b128 v[212:215], v139 offset:2048
	ds_read_b128 v[216:219], v139 offset:3072
	global_load_lds_dwordx4 v[222:223], off
	v_lshl_add_u64 v[222:223], v[184:185], 0, s[20:21]
	s_mov_b32 m0, s44
	s_mov_b64 s[4:5], 0x10080
	global_load_lds_dwordx4 v[222:223], off
	s_barrier
	s_waitcnt lgkmcnt(0)
	v_mfma_f32_16x16x32_bf16 v[120:123], v[204:207], v[156:159], v[120:123]
	v_mfma_f32_16x16x32_bf16 v[112:115], v[212:215], v[156:159], v[112:115]
	v_mfma_f32_16x16x32_bf16 v[104:107], v[204:207], v[164:167], v[104:107]
	v_mfma_f32_16x16x32_bf16 v[96:99], v[212:215], v[164:167], v[96:99]
	v_mfma_f32_16x16x32_bf16 v[88:91], v[204:207], v[176:179], v[88:91]
	v_mfma_f32_16x16x32_bf16 v[80:83], v[212:215], v[176:179], v[80:83]
	v_mfma_f32_16x16x32_bf16 v[76:79], v[204:207], v[196:199], v[76:79]
	v_mfma_f32_16x16x32_bf16 v[72:75], v[212:215], v[196:199], v[72:75]
	v_mfma_f32_16x16x32_bf16 v[120:123], v[208:211], v[160:163], v[120:123]
	v_mfma_f32_16x16x32_bf16 v[112:115], v[216:219], v[160:163], v[112:115]
	v_mfma_f32_16x16x32_bf16 v[104:107], v[208:211], v[172:175], v[104:107]
	v_mfma_f32_16x16x32_bf16 v[96:99], v[216:219], v[172:175], v[96:99]
	v_mfma_f32_16x16x32_bf16 v[88:91], v[208:211], v[180:183], v[88:91]
	v_mfma_f32_16x16x32_bf16 v[80:83], v[216:219], v[180:183], v[80:83]
	v_mfma_f32_16x16x32_bf16 v[76:79], v[208:211], v[200:203], v[76:79]
	v_mfma_f32_16x16x32_bf16 v[72:75], v[216:219], v[200:203], v[72:75]
	s_barrier
	s_mov_b32 m0, s36
	v_lshl_add_u64 v[222:223], v[220:221], 0, s[46:47]
	ds_read_b128 v[156:159], v138 offset:49152
	ds_read_b128 v[160:163], v138 offset:50176
	ds_read_b128 v[164:167], v138 offset:51200
	ds_read_b128 v[172:175], v138 offset:52224
	ds_read_b128 v[176:179], v138 offset:53248
	ds_read_b128 v[180:183], v138 offset:54272
	ds_read_b128 v[196:199], v138 offset:55296
	ds_read_b128 v[200:203], v138 offset:56320
	global_load_lds_dwordx4 v[222:223], off
	v_lshl_add_u64 v[220:221], v[220:221], 0, s[20:21]
	s_mov_b32 m0, s37
	s_nop 0
	global_load_lds_dwordx4 v[220:221], off
	s_barrier
	s_waitcnt lgkmcnt(0)
	v_mfma_f32_16x16x32_bf16 v[68:71], v[140:143], v[156:159], v[68:71]
	v_mfma_f32_16x16x32_bf16 v[64:67], v[148:151], v[156:159], v[64:67]
	v_mfma_f32_16x16x32_bf16 v[60:63], v[140:143], v[164:167], v[60:63]
	v_mfma_f32_16x16x32_bf16 v[52:55], v[148:151], v[164:167], v[52:55]
	v_mfma_f32_16x16x32_bf16 v[44:47], v[140:143], v[176:179], v[44:47]
	v_mfma_f32_16x16x32_bf16 v[36:39], v[148:151], v[176:179], v[36:39]
	v_mfma_f32_16x16x32_bf16 v[28:31], v[140:143], v[196:199], v[28:31]
	v_mfma_f32_16x16x32_bf16 v[20:23], v[148:151], v[196:199], v[20:23]
	v_mfma_f32_16x16x32_bf16 v[68:71], v[144:147], v[160:163], v[68:71]
	v_mfma_f32_16x16x32_bf16 v[64:67], v[152:155], v[160:163], v[64:67]
	v_mfma_f32_16x16x32_bf16 v[60:63], v[144:147], v[172:175], v[60:63]
	v_mfma_f32_16x16x32_bf16 v[52:55], v[152:155], v[172:175], v[52:55]
	v_mfma_f32_16x16x32_bf16 v[44:47], v[144:147], v[180:183], v[44:47]
	v_mfma_f32_16x16x32_bf16 v[36:39], v[152:155], v[180:183], v[36:39]
	v_mfma_f32_16x16x32_bf16 v[28:31], v[144:147], v[200:203], v[28:31]
	v_mfma_f32_16x16x32_bf16 v[20:23], v[152:155], v[200:203], v[20:23]
	s_barrier
	s_mov_b32 m0, s53
	v_lshl_add_u64 v[140:141], v[184:185], 0, s[4:5]
	global_load_lds_dwordx4 v[140:141], off
	v_lshl_add_u64 v[140:141], v[184:185], 0, s[68:69]
	s_mov_b32 m0, s52
	s_nop 0
	global_load_lds_dwordx4 v[140:141], off
	s_waitcnt vmcnt(6)
	s_barrier
	v_mfma_f32_16x16x32_bf16 v[56:59], v[204:207], v[156:159], v[56:59]
	v_mfma_f32_16x16x32_bf16 v[48:51], v[212:215], v[156:159], v[48:51]
	v_mfma_f32_16x16x32_bf16 v[40:43], v[204:207], v[164:167], v[40:43]
	v_mfma_f32_16x16x32_bf16 v[32:35], v[212:215], v[164:167], v[32:35]
	v_mfma_f32_16x16x32_bf16 v[24:27], v[204:207], v[176:179], v[24:27]
	v_mfma_f32_16x16x32_bf16 v[16:19], v[212:215], v[176:179], v[16:19]
	v_mfma_f32_16x16x32_bf16 v[12:15], v[204:207], v[196:199], v[12:15]
	v_mfma_f32_16x16x32_bf16 v[8:11], v[212:215], v[196:199], v[8:11]
	v_mfma_f32_16x16x32_bf16 v[56:59], v[208:211], v[160:163], v[56:59]
	v_mfma_f32_16x16x32_bf16 v[48:51], v[216:219], v[160:163], v[48:51]
	v_mfma_f32_16x16x32_bf16 v[40:43], v[208:211], v[172:175], v[40:43]
	v_mfma_f32_16x16x32_bf16 v[32:35], v[216:219], v[172:175], v[32:35]
	v_mfma_f32_16x16x32_bf16 v[24:27], v[208:211], v[180:183], v[24:27]
	v_mfma_f32_16x16x32_bf16 v[16:19], v[216:219], v[180:183], v[16:19]
	v_mfma_f32_16x16x32_bf16 v[12:15], v[208:211], v[200:203], v[12:15]
	v_mfma_f32_16x16x32_bf16 v[8:11], v[216:219], v[200:203], v[8:11]
	s_andn2_b64 vcc, exec, s[14:15]
	s_mov_b64 s[16:17], -1
	s_mov_b64 s[14:15], 0
	s_mov_b64 s[18:19], 0x100
	s_cbranch_vccz .Ldb_PLE0_cont
	v_readfirstlane_b32 s101, v186
	s_cmpk_gt_u32 s101, 0xff
	s_cbranch_scc1 .Ldb_PLE0_young
	s_barrier
	s_mov_b32 s101, 1
	s_branch .Ldb_PLE0_exit

; #define G_STAGE(bufoff, gbase, o0, h64) do { \
;         __builtin_amdgcn_global_load_lds((const unsigned*)((const char*)(gbase) + (o0)), (LAS unsigned*)(lds + (bufoff) + ldsw), 16, 0, 0); \
;         __builtin_amdgcn_global_load_lds((const unsigned*)((const char*)(gbase) + (h64) + (o0)), (LAS unsigned*)(lds + (bufoff) + ldsw + 8192), 16, 0, 0); } while (0)
; #define G_LDA(dst, b, h) do { _Pragma("unroll") for (int m = 0; m < 4; ++m) _Pragma("unroll") for (int k = 0; k < 2; ++k) dst[m][k] = *(const LAS bf16x8*)(lds + G_SA(b, h) + aoff + m * 2048 + k * 1024); } while (0)
; #define G_LDB(dst, b, h) do { _Pragma("unroll") for (int n = 0; n < 2; ++n) _Pragma("unroll") for (int k = 0; k < 2; ++k) dst[n][k] = *(const LAS bf16x8*)(lds + G_SB(b, h) + boff + n * 2048 + k * 1024); } while (0)
; #define G_WAIT_L(n) asm volatile("s_waitcnt lgkmcnt(" #n ")" ::: "memory")
; #define G_BAR __builtin_amdgcn_s_barrier()
; #define G_SCHED __builtin_amdgcn_sched_barrier(0)
;     ...
;             const bool last = (t == nt - 2);
;             const char* a1 = cA + (size_t)(t + 1) * ckA;
;             const char* a2 = last ? nA : cA + (size_t)(t + 2) * ckA; const char* b2 = last ? nB : cB + (size_t)(t + 2) * kB;
;             const char* a3 = a2 + ckA; const char* b3 = b2 + kB;
;             G_LDB(B0, 0, 0); G_SCHED; G_LDA(At, 0, 0); G_STAGE(G_SA(1, 1), a1 + chA, cA0, qA);
;             G_WAIT_L(8); G_BAR; G_WAIT_L(0); G_MMA(0, 0, At, B0); G_BAR; G_SCHED;
;             G_LDB(B1, 0, 1); G_STAGE(G_SB(0, 0), b2, cB0, qB);
;             G_BAR; G_WAIT_L(0); G_MMA(0, 1, At, B1); G_BAR;
;             G_LDA(At, 0, 1); G_STAGE(G_SA(0, 0), a2, cA0, qA);
;             G_BAR; G_WAIT_L(0); G_MMA(1, 0, At, B0); G_BAR; G_SCHED;
.LBB0_1283:
	s_add_u32 s4, s2, 0xfffc0080
	s_addc_u32 s5, s3, -1
	s_add_i32 s25, 0, 0x10000
	v_add_u32_e32 v0, s25, v181
	ds_read_b128 v[136:139], v0
	ds_read_b128 v[140:143], v0 offset:1024
	ds_read_b128 v[144:147], v0 offset:2048
	ds_read_b128 v[148:151], v0 offset:3072
	s_cmp_eq_u32 s24, 12
	s_cselect_b32 s5, s19, s5
	s_cselect_b32 s4, s18, s4
	s_cselect_b32 s41, s21, s23
	s_cselect_b32 s40, s20, s22
	s_add_i32 m0, s29, 0xc000
	ds_read_b128 v[152:155], v182
	ds_read_b128 v[160:163], v182 offset:1024
	ds_read_b128 v[164:167], v182 offset:2048
	ds_read_b128 v[172:175], v182 offset:3072
	ds_read_b128 v[176:179], v182 offset:4096
	ds_read_b128 v[196:199], v182 offset:5120
	ds_read_b128 v[200:203], v182 offset:6144
	ds_read_b128 v[204:207], v182 offset:7168
	global_load_lds_dwordx4 v158, s[2:3]
	s_add_i32 m0, s29, 0xe000
	s_nop 0
	s_add_u32 vcc_lo, s2, s0
	s_addc_u32 vcc_hi, s3, s1
	global_load_lds_dwordx4 v158, vcc
	s_waitcnt lgkmcnt(8)
	s_cmp_eq_u32 s101, 1
	s_cbranch_scc1 .Ldb_PLE1_sk
	s_barrier
.Ldb_PLE1_sk:
	s_mov_b32 s101, 0
	s_waitcnt lgkmcnt(0)
	v_mfma_f32_16x16x32_bf16 v[132:135], v[136:139], v[152:155], v[132:135]
	v_mfma_f32_16x16x32_bf16 v[128:131], v[144:147], v[152:155], v[128:131]
	v_mfma_f32_16x16x32_bf16 v[116:119], v[136:139], v[164:167], v[116:119]
	v_mfma_f32_16x16x32_bf16 v[112:115], v[144:147], v[164:167], v[112:115]
	v_mfma_f32_16x16x32_bf16 v[100:103], v[136:139], v[176:179], v[100:103]
	v_mfma_f32_16x16x32_bf16 v[96:99], v[144:147], v[176:179], v[96:99]
	v_mfma_f32_16x16x32_bf16 v[84:87], v[136:139], v[200:203], v[84:87]
	v_mfma_f32_16x16x32_bf16 v[80:83], v[144:147], v[200:203], v[80:83]
	v_mfma_f32_16x16x32_bf16 v[132:135], v[140:143], v[160:163], v[132:135]
	v_mfma_f32_16x16x32_bf16 v[128:131], v[148:151], v[160:163], v[128:131]
	v_mfma_f32_16x16x32_bf16 v[116:119], v[140:143], v[172:175], v[116:119]
	v_mfma_f32_16x16x32_bf16 v[112:115], v[148:151], v[172:175], v[112:115]
	v_mfma_f32_16x16x32_bf16 v[100:103], v[140:143], v[196:199], v[100:103]
	v_mfma_f32_16x16x32_bf16 v[96:99], v[148:151], v[196:199], v[96:99]
	v_mfma_f32_16x16x32_bf16 v[84:87], v[140:143], v[204:207], v[84:87]
	v_mfma_f32_16x16x32_bf16 v[80:83], v[148:151], v[204:207], v[80:83]
	s_barrier
	s_add_i32 s44, 0, 0x14000
	s_add_i32 s25, s25, s27
	v_add_u32_e32 v0, s44, v181
	s_mov_b32 m0, s25
	ds_read_b128 v[208:211], v0
	ds_read_b128 v[212:215], v0 offset:1024
	ds_read_b128 v[216:219], v0 offset:2048
	ds_read_b128 v[220:223], v0 offset:3072
	global_load_lds_dwordx4 v156, s[40:41]
	s_add_i32 m0, s25, 0x2000
	s_nop 0
	s_add_u32 vcc_lo, s40, s0
	s_addc_u32 vcc_hi, s41, s1
	global_load_lds_dwordx4 v156, vcc
	s_barrier
	s_waitcnt lgkmcnt(0)
	v_mfma_f32_16x16x32_bf16 v[124:127], v[208:211], v[152:155], v[124:127]
	v_mfma_f32_16x16x32_bf16 v[120:123], v[216:219], v[152:155], v[120:123]
	v_mfma_f32_16x16x32_bf16 v[108:111], v[208:211], v[164:167], v[108:111]
	v_mfma_f32_16x16x32_bf16 v[104:107], v[216:219], v[164:167], v[104:107]
	v_mfma_f32_16x16x32_bf16 v[92:95], v[208:211], v[176:179], v[92:95]
	v_mfma_f32_16x16x32_bf16 v[88:91], v[216:219], v[176:179], v[88:91]
	v_mfma_f32_16x16x32_bf16 v[76:79], v[208:211], v[200:203], v[76:79]
	v_mfma_f32_16x16x32_bf16 v[72:75], v[216:219], v[200:203], v[72:75]
	v_mfma_f32_16x16x32_bf16 v[124:127], v[212:215], v[160:163], v[124:127]
	v_mfma_f32_16x16x32_bf16 v[120:123], v[220:223], v[160:163], v[120:123]
	v_mfma_f32_16x16x32_bf16 v[108:111], v[212:215], v[172:175], v[108:111]
	v_mfma_f32_16x16x32_bf16 v[104:107], v[220:223], v[172:175], v[104:107]
	v_mfma_f32_16x16x32_bf16 v[92:95], v[212:215], v[196:199], v[92:95]
	v_mfma_f32_16x16x32_bf16 v[88:91], v[220:223], v[196:199], v[88:91]
	v_mfma_f32_16x16x32_bf16 v[76:79], v[212:215], v[204:207], v[76:79]
	v_mfma_f32_16x16x32_bf16 v[72:75], v[220:223], v[204:207], v[72:75]
	s_barrier
	s_mov_b32 m0, s29
	v_lshl_add_u64 v[224:225], s[4:5], 0, v[2:3]
	ds_read_b128 v[152:155], v182 offset:16384
	ds_read_b128 v[160:163], v182 offset:17408
	ds_read_b128 v[164:167], v182 offset:18432
	ds_read_b128 v[172:175], v182 offset:19456
	ds_read_b128 v[176:179], v182 offset:20480
	ds_read_b128 v[196:199], v182 offset:21504
	ds_read_b128 v[200:203], v182 offset:22528
	ds_read_b128 v[204:207], v182 offset:23552
	global_load_lds_dwordx4 v2, s[4:5]
	s_mov_b32 m0, s30
	s_nop 0
	s_add_u32 vcc_lo, s4, s0
	s_addc_u32 vcc_hi, s5, s1
	global_load_lds_dwordx4 v2, vcc
	s_barrier
	s_waitcnt lgkmcnt(0)
	v_mfma_f32_16x16x32_bf16 v[68:71], v[136:139], v[152:155], v[68:71]
	v_mfma_f32_16x16x32_bf16 v[64:67], v[144:147], v[152:155], v[64:67]
	v_mfma_f32_16x16x32_bf16 v[52:55], v[136:139], v[164:167], v[52:55]
	v_mfma_f32_16x16x32_bf16 v[48:51], v[144:147], v[164:167], v[48:51]
	v_mfma_f32_16x16x32_bf16 v[36:39], v[136:139], v[176:179], v[36:39]
	v_mfma_f32_16x16x32_bf16 v[32:35], v[144:147], v[176:179], v[32:35]
	v_mfma_f32_16x16x32_bf16 v[20:23], v[136:139], v[200:203], v[20:23]
	v_mfma_f32_16x16x32_bf16 v[16:19], v[144:147], v[200:203], v[16:19]
	v_mfma_f32_16x16x32_bf16 v[68:71], v[140:143], v[160:163], v[68:71]
	v_mfma_f32_16x16x32_bf16 v[64:67], v[148:151], v[160:163], v[64:67]
	v_mfma_f32_16x16x32_bf16 v[52:55], v[140:143], v[172:175], v[52:55]
	v_mfma_f32_16x16x32_bf16 v[48:51], v[148:151], v[172:175], v[48:51]
	v_mfma_f32_16x16x32_bf16 v[36:39], v[140:143], v[196:199], v[36:39]
	v_mfma_f32_16x16x32_bf16 v[32:35], v[148:151], v[196:199], v[32:35]
	v_mfma_f32_16x16x32_bf16 v[20:23], v[140:143], v[204:207], v[20:23]
	v_mfma_f32_16x16x32_bf16 v[16:19], v[148:151], v[204:207], v[16:19]
	s_barrier
; #define G_STAGE(bufoff, gbase, o0, h64) do { \
;         __builtin_amdgcn_global_load_lds((const unsigned*)((const char*)(gbase) + (o0)), (LAS unsigned*)(lds + (bufoff) + ldsw), 16, 0, 0); \
;         __builtin_amdgcn_global_load_lds((const unsigned*)((const char*)(gbase) + (h64) + (o0)), (LAS unsigned*)(lds + (bufoff) + ldsw + 8192), 16, 0, 0); } while (0)
; #define G_LDA(dst, b, h) do { _Pragma("unroll") for (int m = 0; m < 4; ++m) _Pragma("unroll") for (int k = 0; k < 2; ++k) dst[m][k] = *(const LAS bf16x8*)(lds + G_SA(b, h) + aoff + m * 2048 + k * 1024); } while (0)
; #define G_LDB(dst, b, h) do { _Pragma("unroll") for (int n = 0; n < 2; ++n) _Pragma("unroll") for (int k = 0; k < 2; ++k) dst[n][k] = *(const LAS bf16x8*)(lds + G_SB(b, h) + boff + n * 2048 + k * 1024); } while (0)
; #define G_WAIT_V(n) asm volatile("s_waitcnt vmcnt(" #n ")" ::: "memory")
; #define G_WAIT_L(n) asm volatile("s_waitcnt lgkmcnt(" #n ")" ::: "memory")
; #define G_BAR __builtin_amdgcn_s_barrier()
; #define G_SCHED __builtin_amdgcn_sched_barrier(0)
;     ...
;             G_STAGE(G_SB(0, 1), b2 + chB, cB0, qB);
;             G_WAIT_V(6); G_BAR; G_MMA(1, 1, At, B1); G_BAR;
;             G_LDB(B0, 1, 0); G_SCHED; G_LDA(At, 1, 0); G_STAGE(G_SA(0, 1), a2 + chA, cA0, qA);
;             G_WAIT_L(8); G_BAR; G_WAIT_L(0); G_MMA(0, 0, At, B0); G_BAR; G_SCHED;
;             G_LDB(B1, 1, 1); G_STAGE(G_SB(1, 0), b3, cB0, qB);
	s_add_i32 s100, s44, s27
	s_mov_b32 m0, s100
	s_nop 0
	s_add_u32 vcc_lo, s40, s54
	s_addc_u32 vcc_hi, s41, s55
	global_load_lds_dwordx4 v156, vcc
	s_add_i32 m0, s100, 0x2000
	s_nop 0
	s_add_u32 vcc_lo, s40, s58
	s_addc_u32 vcc_hi, s41, s59
	global_load_lds_dwordx4 v156, vcc
	s_waitcnt vmcnt(6)
	s_barrier
	v_mfma_f32_16x16x32_bf16 v[60:63], v[208:211], v[152:155], v[60:63]
	v_mfma_f32_16x16x32_bf16 v[56:59], v[216:219], v[152:155], v[56:59]
	v_mfma_f32_16x16x32_bf16 v[44:47], v[208:211], v[164:167], v[44:47]
	v_mfma_f32_16x16x32_bf16 v[40:43], v[216:219], v[164:167], v[40:43]
	v_mfma_f32_16x16x32_bf16 v[28:31], v[208:211], v[176:179], v[28:31]
	v_mfma_f32_16x16x32_bf16 v[24:27], v[216:219], v[176:179], v[24:27]
	v_mfma_f32_16x16x32_bf16 v[12:15], v[208:211], v[200:203], v[12:15]
	v_mfma_f32_16x16x32_bf16 v[8:11], v[216:219], v[200:203], v[8:11]
	v_mfma_f32_16x16x32_bf16 v[60:63], v[212:215], v[160:163], v[60:63]
	v_mfma_f32_16x16x32_bf16 v[56:59], v[220:223], v[160:163], v[56:59]
	v_mfma_f32_16x16x32_bf16 v[44:47], v[212:215], v[172:175], v[44:47]
	v_mfma_f32_16x16x32_bf16 v[40:43], v[220:223], v[172:175], v[40:43]
	v_mfma_f32_16x16x32_bf16 v[28:31], v[212:215], v[196:199], v[28:31]
	v_mfma_f32_16x16x32_bf16 v[24:27], v[220:223], v[196:199], v[24:27]
	v_mfma_f32_16x16x32_bf16 v[12:15], v[212:215], v[204:207], v[12:15]
	v_mfma_f32_16x16x32_bf16 v[8:11], v[220:223], v[204:207], v[8:11]
	s_barrier
	s_add_i32 s100, 0, 0x18000
	v_add_u32_e32 v0, s100, v181
	ds_read_b128 v[136:139], v0
	ds_read_b128 v[140:143], v0 offset:1024
	ds_read_b128 v[144:147], v0 offset:2048
	ds_read_b128 v[148:151], v0 offset:3072
	s_mov_b32 m0, s31
	ds_read_b128 v[152:155], v182 offset:32768
	ds_read_b128 v[160:163], v182 offset:33792
	ds_read_b128 v[164:167], v182 offset:34816
	ds_read_b128 v[172:175], v182 offset:35840
	ds_read_b128 v[176:179], v182 offset:36864
	ds_read_b128 v[196:199], v182 offset:37888
	ds_read_b128 v[200:203], v182 offset:38912
	ds_read_b128 v[204:207], v182 offset:39936
	s_add_u32 vcc_lo, s4, s54
	s_addc_u32 vcc_hi, s5, s55
	global_load_lds_dwordx4 v2, vcc
	s_mov_b32 m0, s34
	s_nop 0
	s_add_u32 vcc_lo, s4, s58
	s_addc_u32 vcc_hi, s5, s59
	global_load_lds_dwordx4 v2, vcc
	s_waitcnt lgkmcnt(8)
	s_barrier
	s_waitcnt lgkmcnt(0)
	v_mfma_f32_16x16x32_bf16 v[132:135], v[136:139], v[152:155], v[132:135]
	v_mfma_f32_16x16x32_bf16 v[128:131], v[144:147], v[152:155], v[128:131]
	v_mfma_f32_16x16x32_bf16 v[116:119], v[136:139], v[164:167], v[116:119]
	v_mfma_f32_16x16x32_bf16 v[112:115], v[144:147], v[164:167], v[112:115]
	v_mfma_f32_16x16x32_bf16 v[100:103], v[136:139], v[176:179], v[100:103]
	v_mfma_f32_16x16x32_bf16 v[96:99], v[144:147], v[176:179], v[96:99]
	v_mfma_f32_16x16x32_bf16 v[84:87], v[136:139], v[200:203], v[84:87]
	v_mfma_f32_16x16x32_bf16 v[80:83], v[144:147], v[200:203], v[80:83]
	v_mfma_f32_16x16x32_bf16 v[132:135], v[140:143], v[160:163], v[132:135]
	v_mfma_f32_16x16x32_bf16 v[128:131], v[148:151], v[160:163], v[128:131]
	v_mfma_f32_16x16x32_bf16 v[116:119], v[140:143], v[172:175], v[116:119]
	v_mfma_f32_16x16x32_bf16 v[112:115], v[148:151], v[172:175], v[112:115]
	v_mfma_f32_16x16x32_bf16 v[100:103], v[140:143], v[196:199], v[100:103]
	v_mfma_f32_16x16x32_bf16 v[96:99], v[148:151], v[196:199], v[96:99]
	v_mfma_f32_16x16x32_bf16 v[84:87], v[140:143], v[204:207], v[84:87]
	v_mfma_f32_16x16x32_bf16 v[80:83], v[148:151], v[204:207], v[80:83]
	s_barrier
	s_add_i32 s5, 0, 0x1c000
	s_add_i32 s4, s100, s27
	v_add_u32_e32 v0, s5, v181
	s_mov_b32 m0, s4
	ds_read_b128 v[208:211], v0
	ds_read_b128 v[212:215], v0 offset:1024
	ds_read_b128 v[216:219], v0 offset:2048
	ds_read_b128 v[220:223], v0 offset:3072
	s_add_u32 vcc_lo, s40, s46
	s_addc_u32 vcc_hi, s41, s47
	global_load_lds_dwordx4 v156, vcc
	s_add_i32 m0, s4, 0x2000
	s_nop 0
	s_add_u32 vcc_lo, s40, s62
	s_addc_u32 vcc_hi, s41, s63
	global_load_lds_dwordx4 v156, vcc
	s_barrier
; #define G_STAGE(bufoff, gbase, o0, h64) do { \
;         __builtin_amdgcn_global_load_lds((const unsigned*)((const char*)(gbase) + (o0)), (LAS unsigned*)(lds + (bufoff) + ldsw), 16, 0, 0); \
;         __builtin_amdgcn_global_load_lds((const unsigned*)((const char*)(gbase) + (h64) + (o0)), (LAS unsigned*)(lds + (bufoff) + ldsw + 8192), 16, 0, 0); } while (0)
; #define G_LDA(dst, b, h) do { _Pragma("unroll") for (int m = 0; m < 4; ++m) _Pragma("unroll") for (int k = 0; k < 2; ++k) dst[m][k] = *(const LAS bf16x8*)(lds + G_SA(b, h) + aoff + m * 2048 + k * 1024); } while (0)
; #define G_WAIT_V(n) asm volatile("s_waitcnt vmcnt(" #n ")" ::: "memory")
; #define G_WAIT_L(n) asm volatile("s_waitcnt lgkmcnt(" #n ")" ::: "memory")
; #define G_BAR __builtin_amdgcn_s_barrier()
; #define G_SCHED __builtin_amdgcn_sched_barrier(0)
;     ...
;             G_BAR; G_WAIT_L(0); G_MMA(0, 1, At, B1); G_BAR;
;             G_LDA(At, 1, 1); G_STAGE(G_SA(1, 0), a3, cA0, qA);
;             G_BAR; G_WAIT_L(0); G_MMA(1, 0, At, B0); G_BAR; G_SCHED;
;             G_STAGE(G_SB(1, 1), b3 + chB, cB0, qB);
;             G_WAIT_V(6); G_BAR; G_MMA(1, 1, At, B1); G_BAR;
	s_waitcnt lgkmcnt(0)
	v_mfma_f32_16x16x32_bf16 v[124:127], v[208:211], v[152:155], v[124:127]
	v_mfma_f32_16x16x32_bf16 v[120:123], v[216:219], v[152:155], v[120:123]
	v_mfma_f32_16x16x32_bf16 v[108:111], v[208:211], v[164:167], v[108:111]
	v_mfma_f32_16x16x32_bf16 v[104:107], v[216:219], v[164:167], v[104:107]
	v_mfma_f32_16x16x32_bf16 v[92:95], v[208:211], v[176:179], v[92:95]
	v_mfma_f32_16x16x32_bf16 v[88:91], v[216:219], v[176:179], v[88:91]
	v_mfma_f32_16x16x32_bf16 v[76:79], v[208:211], v[200:203], v[76:79]
	v_mfma_f32_16x16x32_bf16 v[72:75], v[216:219], v[200:203], v[72:75]
	v_mfma_f32_16x16x32_bf16 v[124:127], v[212:215], v[160:163], v[124:127]
	v_mfma_f32_16x16x32_bf16 v[120:123], v[220:223], v[160:163], v[120:123]
	v_mfma_f32_16x16x32_bf16 v[108:111], v[212:215], v[172:175], v[108:111]
	v_mfma_f32_16x16x32_bf16 v[104:107], v[220:223], v[172:175], v[104:107]
	v_mfma_f32_16x16x32_bf16 v[92:95], v[212:215], v[196:199], v[92:95]
	v_mfma_f32_16x16x32_bf16 v[88:91], v[220:223], v[196:199], v[88:91]
	v_mfma_f32_16x16x32_bf16 v[76:79], v[212:215], v[204:207], v[76:79]
	v_mfma_f32_16x16x32_bf16 v[72:75], v[220:223], v[204:207], v[72:75]
	s_barrier
	s_mov_b32 m0, s35
	v_lshl_add_u64 v[226:227], v[224:225], 0, s[46:47]
	ds_read_b128 v[152:155], v182 offset:49152
	ds_read_b128 v[160:163], v182 offset:50176
	ds_read_b128 v[164:167], v182 offset:51200
	ds_read_b128 v[172:175], v182 offset:52224
	ds_read_b128 v[176:179], v182 offset:53248
	ds_read_b128 v[196:199], v182 offset:54272
	ds_read_b128 v[200:203], v182 offset:55296
	ds_read_b128 v[204:207], v182 offset:56320
	global_load_lds_dwordx4 v[226:227], off
	v_lshl_add_u64 v[224:225], v[224:225], 0, s[62:63]
	s_mov_b32 m0, s36
	s_nop 0
	global_load_lds_dwordx4 v[224:225], off
	s_barrier
	s_waitcnt lgkmcnt(0)
	v_mfma_f32_16x16x32_bf16 v[68:71], v[136:139], v[152:155], v[68:71]
	v_mfma_f32_16x16x32_bf16 v[64:67], v[144:147], v[152:155], v[64:67]
	v_mfma_f32_16x16x32_bf16 v[52:55], v[136:139], v[164:167], v[52:55]
	v_mfma_f32_16x16x32_bf16 v[48:51], v[144:147], v[164:167], v[48:51]
	v_mfma_f32_16x16x32_bf16 v[36:39], v[136:139], v[176:179], v[36:39]
	v_mfma_f32_16x16x32_bf16 v[32:35], v[144:147], v[176:179], v[32:35]
	v_mfma_f32_16x16x32_bf16 v[20:23], v[136:139], v[200:203], v[20:23]
	v_mfma_f32_16x16x32_bf16 v[16:19], v[144:147], v[200:203], v[16:19]
	v_mfma_f32_16x16x32_bf16 v[68:71], v[140:143], v[160:163], v[68:71]
	v_mfma_f32_16x16x32_bf16 v[64:67], v[148:151], v[160:163], v[64:67]
	v_mfma_f32_16x16x32_bf16 v[52:55], v[140:143], v[172:175], v[52:55]
	v_mfma_f32_16x16x32_bf16 v[48:51], v[148:151], v[172:175], v[48:51]
	v_mfma_f32_16x16x32_bf16 v[36:39], v[140:143], v[196:199], v[36:39]
	v_mfma_f32_16x16x32_bf16 v[32:35], v[148:151], v[196:199], v[32:35]
	v_mfma_f32_16x16x32_bf16 v[20:23], v[140:143], v[204:207], v[20:23]
	v_mfma_f32_16x16x32_bf16 v[16:19], v[148:151], v[204:207], v[16:19]
	s_barrier
	s_add_i32 s4, s5, s27
	s_mov_b32 m0, s4
	s_nop 0
	s_add_u32 vcc_lo, s40, s64
	s_addc_u32 vcc_hi, s41, s65
	global_load_lds_dwordx4 v156, vcc
	s_add_i32 m0, s4, 0x2000
	s_nop 0
	s_add_u32 vcc_lo, s40, s66
	s_addc_u32 vcc_hi, s41, s67
	global_load_lds_dwordx4 v156, vcc
	s_add_i32 s24, s24, 2
	s_add_u32 s2, s2, 0x100
	s_addc_u32 s3, s3, 0
	s_add_u32 s22, s22, 0x100
	s_addc_u32 s23, s23, 0
	s_cmp_gt_u32 s24, 13
	s_waitcnt vmcnt(6)
	s_barrier
	v_mfma_f32_16x16x32_bf16 v[60:63], v[208:211], v[152:155], v[60:63]
	v_mfma_f32_16x16x32_bf16 v[56:59], v[216:219], v[152:155], v[56:59]
	v_mfma_f32_16x16x32_bf16 v[44:47], v[208:211], v[164:167], v[44:47]
	v_mfma_f32_16x16x32_bf16 v[40:43], v[216:219], v[164:167], v[40:43]
	v_mfma_f32_16x16x32_bf16 v[28:31], v[208:211], v[176:179], v[28:31]
	v_mfma_f32_16x16x32_bf16 v[24:27], v[216:219], v[176:179], v[24:27]
	v_mfma_f32_16x16x32_bf16 v[12:15], v[208:211], v[200:203], v[12:15]
	v_mfma_f32_16x16x32_bf16 v[8:11], v[216:219], v[200:203], v[8:11]
	v_mfma_f32_16x16x32_bf16 v[60:63], v[212:215], v[160:163], v[60:63]
	v_mfma_f32_16x16x32_bf16 v[56:59], v[220:223], v[160:163], v[56:59]
	v_mfma_f32_16x16x32_bf16 v[44:47], v[212:215], v[172:175], v[44:47]
	v_mfma_f32_16x16x32_bf16 v[40:43], v[220:223], v[172:175], v[40:43]
	v_mfma_f32_16x16x32_bf16 v[28:31], v[212:215], v[196:199], v[28:31]
	v_mfma_f32_16x16x32_bf16 v[24:27], v[220:223], v[196:199], v[24:27]
	v_mfma_f32_16x16x32_bf16 v[12:15], v[212:215], v[204:207], v[12:15]
	v_mfma_f32_16x16x32_bf16 v[8:11], v[220:223], v[204:207], v[8:11]
	s_cbranch_scc0 .Ldb_PLE1_cont
	v_readfirstlane_b32 s101, v186
	s_cmpk_gt_u32 s101, 0xff
	s_cbranch_scc1 .Ldb_PLE1_young
	s_barrier
	s_mov_b32 s101, 1
	s_branch .Ldb_PLE1_exit
